# scan v3: w and kT stored fragment-linear by prep (1 KiB contiguous fragment loads), q/qk staged through swizzled LDS by a loader wave, parity-specialised bodies
# speedup vs baseline: 1.1340x; 1.0738x over previous
; DEVI bf16_t f2bf(float a) { return (bf16_t)(pack2(a, 0.f) & 0xffff); }
; #define MFMA16(a, b, c) __builtin_amdgcn_mfma_f32_16x16x32_bf16((a), (b), (c), 0, 0, 0)
; DEVI void scan_item(const Params& p, int h, int sl, char* smem) {
;     ...
;       f32x4 acco[2][NW];
; #pragma unroll
;       for (int ct = 0; ct < NW; ++ct) {
;         bf16x8 sb[4];
; #pragma unroll
;         for (int s = 0; s < 4; ++s) sb[s] = *(const bf16x8*)(sbx + ((ct * 4 + s) * 64 + lane) * 16);
; #pragma unroll
;         for (int m = 0; m < 2; ++m) acco[m][ct] = f32x4{0.f, 0.f, 0.f, 0.f};
; #pragma unroll
;         for (int s = 0; s < 4; ++s)
; #pragma unroll
;           for (int m = 0; m < 2; ++m) acco[m][ct] = MFMA16(qfr[m][s], sb[s], acco[m][ct]);
;       }
;       if (n + 1 < NCH) qload(n + 1);
;       __syncthreads();
;       const int t0 = n * 64 - 48;
; #pragma unroll
;       for (int m = 0; m < 2; ++m) {
;         const int mt = cw * 2 + m;
;         bf16x8 qkf[2];
; #pragma unroll
;         for (int s2 = 0; s2 < 2; ++s2) {
;           const char* a = qksm + (mt * 16 + l15) * 144 + s2 * 64 + quad * 8;
;           qkf[s2] = mk8(*(const u32x2*)a, *(const u32x2*)(a + 32));
;         }
;         const f32x4 ge4 = *(const f32x4*)(gsm + mt * 16 + quad * 4);
; #pragma unroll
;         for (int ct = 0; ct < NW; ++ct) {
;           f32x4 a2 = f32x4{0.f, 0.f, 0.f, 0.f};
; #pragma unroll
;           for (int s2 = 0; s2 < 2; ++s2) {
;             const bf16x8 vb = *(const bf16x8*)(vbx + ((ct * 2 + s2) * 64 + lane) * 16);
;             a2 = MFMA16(qkf[s2], vb, a2);
;           }
; #pragma unroll
;           for (int jj = 0; jj < 4; ++jj) {
;             const int t = t0 + mt * 16 + quad * 4 + jj;
;             const float o = ge4[jj] * acco[m][ct][jj] + a2[jj];
;             if (t >= 0) r1[(size_t)t * 3072 + 2048 + h * 128 + vb0 + ct * 16 + l15] = f2bf(o);
;           }
;         }
;       }
.LBB0_1158:
	s_and_b64 vcc, exec, s[0:1]
	s_cbranch_vccz .LBB0_1238
	v_lshrrev_b32_e32 v2, 6, v206
	v_and_b32_e32 v0, 63, v206
	v_readfirstlane_b32 s5, v2
	s_and_b32 s9, s88, 7
	s_lshr_b32 s13, s88, 3
	v_and_b32_e32 v3, 15, v0
	v_lshrrev_b32_e32 v4, 4, v0
	s_lshl_b32 s18, s9, 8
	s_add_u32 s0, s14, 0x9bab000
	s_addc_u32 s1, s15, 0
	s_add_u32 s0, s0, s18
	s_addc_u32 s1, s1, 0
	s_cmp_eq_u32 s5, 0
	s_cbranch_scc1 .Lsc_state
	s_cmp_eq_u32 s5, 3
	s_cbranch_scc1 .Lsc_loader
	s_sub_u32 s24, s5, 1
	s_lshl_b32 s24, s24, 1
	s_lshl_b32 s25, s24, 4
	v_add_u32_e32 v5, s25, v3
	v_mul_u32_u24_e32 v6, 0x1800, v5
	v_lshlrev_b32_e32 v104, 2, v5
	v_add_u32_e32 v104, 0x1800, v104
	s_lshl_b32 s36, s13, 5
	v_lshl_add_u32 v7, v4, 3, s36
	v_add_u32_e32 v7, 0x1000, v7
	v_add_u32_e32 v106, v6, v7
	v_lshlrev_b32_e32 v6, 8, v5
	v_or_b32_e32 v7, 0, v4
	v_xor_b32_e32 v7, v7, v3
	v_lshl_add_u32 v116, v7, 4, v6
	v_add_u32_e32 v116, 12320, v116
	v_or_b32_e32 v7, 4, v4
	v_xor_b32_e32 v7, v7, v3
	v_lshl_add_u32 v117, v7, 4, v6
	v_add_u32_e32 v117, 12320, v117
	v_or_b32_e32 v7, 8, v4
	v_xor_b32_e32 v7, v7, v3
	v_lshl_add_u32 v118, v7, 4, v6
	v_add_u32_e32 v118, 12320, v118
	v_or_b32_e32 v7, 12, v4
	v_xor_b32_e32 v7, v7, v3
	v_lshl_add_u32 v119, v7, 4, v6
	v_add_u32_e32 v119, 12320, v119
	v_lshlrev_b32_e32 v6, 7, v5
	v_and_b32_e32 v2, 7, v3
	v_or_b32_e32 v7, 0, v4
	v_xor_b32_e32 v7, v7, v2
	v_lshl_add_u32 v124, v7, 4, v6
	v_add_u32_e32 v124, 45088, v124
	v_or_b32_e32 v7, 4, v4
	v_xor_b32_e32 v7, v7, v2
	v_lshl_add_u32 v125, v7, 4, v6
	v_add_u32_e32 v125, 45088, v125
	v_add_u32_e32 v5, s25, v3
	v_add_u32_e32 v5, 16, v5
	v_mul_u32_u24_e32 v6, 0x1800, v5
	v_lshlrev_b32_e32 v105, 2, v5
	v_add_u32_e32 v105, 0x1800, v105
	s_lshl_b32 s36, s13, 5
	v_lshl_add_u32 v7, v4, 3, s36
	v_add_u32_e32 v7, 0x1000, v7
	v_add_u32_e32 v107, v6, v7
	v_lshlrev_b32_e32 v6, 8, v5
	v_or_b32_e32 v7, 0, v4
	v_xor_b32_e32 v7, v7, v3
	v_lshl_add_u32 v120, v7, 4, v6
	v_add_u32_e32 v120, 12320, v120
	v_or_b32_e32 v7, 4, v4
	v_xor_b32_e32 v7, v7, v3
	v_lshl_add_u32 v121, v7, 4, v6
	v_add_u32_e32 v121, 12320, v121
	v_or_b32_e32 v7, 8, v4
	v_xor_b32_e32 v7, v7, v3
	v_lshl_add_u32 v122, v7, 4, v6
	v_add_u32_e32 v122, 12320, v122
	v_or_b32_e32 v7, 12, v4
	v_xor_b32_e32 v7, v7, v3
	v_lshl_add_u32 v123, v7, 4, v6
	v_add_u32_e32 v123, 12320, v123
	v_lshlrev_b32_e32 v6, 7, v5
	v_and_b32_e32 v2, 7, v3
	v_or_b32_e32 v7, 0, v4
	v_xor_b32_e32 v7, v7, v2
	v_lshl_add_u32 v126, v7, 4, v6
	v_add_u32_e32 v126, 45088, v126
	v_or_b32_e32 v7, 4, v4
	v_xor_b32_e32 v7, v7, v2
	v_lshl_add_u32 v127, v7, 4, v6
	v_add_u32_e32 v127, 45088, v127
	v_lshlrev_b32_e32 v108, 4, v0
	v_add_u32_e32 v108, 32, v108
	s_mul_i32 s18, s9, 0x300
	s_add_u32 s10, s14, 0x6bc1800
	s_addc_u32 s11, s15, 0
	s_add_u32 s10, s10, s18
	s_addc_u32 s11, s11, 0
	global_load_dword v56, v104, s[10:11]
	global_load_dword v57, v105, s[10:11]
	s_mov_b32 s18, 0
	s_waitcnt vmcnt(0)
	s_barrier
.Lsc_out_loop:
	s_bitcmp1_b32 s18, 0
	s_cbranch_scc1 .Lsc_out_odd
	s_add_u32 s0, s0, 0x60000
	s_addc_u32 s1, s1, 0
	s_add_u32 s10, s10, 0x1800
	s_addc_u32 s11, s11, 0
	s_barrier
	ds_read_b128 v[60:63], v108 offset:0
	ds_read_b128 v[64:67], v108 offset:1024
	ds_read_b128 v[68:71], v108 offset:2048
	ds_read_b128 v[72:75], v108 offset:3072
	ds_read_b128 v[8:11], v116 offset:0
	ds_read_b128 v[12:15], v117 offset:0
	ds_read_b128 v[16:19], v118 offset:0
	ds_read_b128 v[20:23], v119 offset:0
	ds_read_b128 v[24:27], v120 offset:0
	ds_read_b128 v[28:31], v121 offset:0
	ds_read_b128 v[32:35], v122 offset:0
	ds_read_b128 v[36:39], v123 offset:0
	ds_read_b128 v[76:79], v108 offset:4096
	ds_read_b128 v[80:83], v108 offset:5120
	s_waitcnt lgkmcnt(9)
	v_mfma_f32_16x16x32_bf16 v[84:87], v[60:63], v[8:11], 0
	s_waitcnt lgkmcnt(8)
	v_mfma_f32_16x16x32_bf16 v[84:87], v[64:67], v[12:15], v[84:87]
	s_waitcnt lgkmcnt(7)
	v_mfma_f32_16x16x32_bf16 v[84:87], v[68:71], v[16:19], v[84:87]
	s_waitcnt lgkmcnt(6)
	v_mfma_f32_16x16x32_bf16 v[84:87], v[72:75], v[20:23], v[84:87]
	s_waitcnt lgkmcnt(5)
	v_mfma_f32_16x16x32_bf16 v[88:91], v[60:63], v[24:27], 0
	s_waitcnt lgkmcnt(4)
	v_mfma_f32_16x16x32_bf16 v[88:91], v[64:67], v[28:31], v[88:91]
	s_waitcnt lgkmcnt(3)
	v_mfma_f32_16x16x32_bf16 v[88:91], v[68:71], v[32:35], v[88:91]
	s_waitcnt lgkmcnt(2)
	v_mfma_f32_16x16x32_bf16 v[88:91], v[72:75], v[36:39], v[88:91]
	ds_read_b128 v[40:43], v124 offset:0
	ds_read_b128 v[44:47], v125 offset:0
	ds_read_b128 v[48:51], v126 offset:0
	ds_read_b128 v[52:55], v127 offset:0
	s_waitcnt lgkmcnt(3)
	v_mfma_f32_16x16x32_bf16 v[92:95], v[76:79], v[40:43], 0
	s_waitcnt lgkmcnt(2)
	v_mfma_f32_16x16x32_bf16 v[92:95], v[80:83], v[44:47], v[92:95]
	s_waitcnt lgkmcnt(1)
	v_mfma_f32_16x16x32_bf16 v[96:99], v[76:79], v[48:51], 0
	s_waitcnt lgkmcnt(0)
	v_mfma_f32_16x16x32_bf16 v[96:99], v[80:83], v[52:55], v[96:99]
	s_lshl_b32 s36, s18, 2
	s_add_u32 s36, s36, s24
	s_waitcnt vmcnt(3)
	s_nop 4
	v_fma_f32 v110, -v56, v84, v92
	v_fma_f32 v111, -v56, v85, v93
	v_fma_f32 v112, -v56, v86, v94
	v_fma_f32 v113, -v56, v87, v95
	global_load_dword v56, v104, s[10:11]
	v_cvt_pk_bf16_f32 v114, v110, v111
	v_cvt_pk_bf16_f32 v115, v112, v113
	s_cmp_lt_u32 s36, 3
	s_cbranch_scc1 .Lsc_out_skip0_0
	global_store_dwordx2 v106, v[114:115], s[0:1]
.Lsc_out_skip0_0:
	s_waitcnt vmcnt(3)
	v_fma_f32 v110, -v57, v88, v96
	v_fma_f32 v111, -v57, v89, v97
	v_fma_f32 v112, -v57, v90, v98
	v_fma_f32 v113, -v57, v91, v99
	global_load_dword v57, v105, s[10:11]
	v_cvt_pk_bf16_f32 v114, v110, v111
	v_cvt_pk_bf16_f32 v115, v112, v113
	s_cmp_lt_u32 s36, 2
	s_cbranch_scc1 .Lsc_out_skip1_0
	global_store_dwordx2 v107, v[114:115], s[0:1]

; DEVI bf16_t f2bf(float a) { return (bf16_t)(pack2(a, 0.f) & 0xffff); }
; #define MFMA16(a, b, c) __builtin_amdgcn_mfma_f32_16x16x32_bf16((a), (b), (c), 0, 0, 0)
; DEVI void scan_item(const Params& p, int h, int sl, char* smem) {
;     ...
;       f32x4 acco[2][NW];
; #pragma unroll
;       for (int ct = 0; ct < NW; ++ct) {
;         bf16x8 sb[4];
; #pragma unroll
;         for (int s = 0; s < 4; ++s) sb[s] = *(const bf16x8*)(sbx + ((ct * 4 + s) * 64 + lane) * 16);
; #pragma unroll
;         for (int m = 0; m < 2; ++m) acco[m][ct] = f32x4{0.f, 0.f, 0.f, 0.f};
; #pragma unroll
;         for (int s = 0; s < 4; ++s)
; #pragma unroll
;           for (int m = 0; m < 2; ++m) acco[m][ct] = MFMA16(qfr[m][s], sb[s], acco[m][ct]);
;       }
;       if (n + 1 < NCH) qload(n + 1);
;       __syncthreads();
;       const int t0 = n * 64 - 48;
; #pragma unroll
;       for (int m = 0; m < 2; ++m) {
;         const int mt = cw * 2 + m;
;         bf16x8 qkf[2];
; #pragma unroll
;         for (int s2 = 0; s2 < 2; ++s2) {
;           const char* a = qksm + (mt * 16 + l15) * 144 + s2 * 64 + quad * 8;
;           qkf[s2] = mk8(*(const u32x2*)a, *(const u32x2*)(a + 32));
;         }
;         const f32x4 ge4 = *(const f32x4*)(gsm + mt * 16 + quad * 4);
; #pragma unroll
;         for (int ct = 0; ct < NW; ++ct) {
;           f32x4 a2 = f32x4{0.f, 0.f, 0.f, 0.f};
; #pragma unroll
;           for (int s2 = 0; s2 < 2; ++s2) {
;             const bf16x8 vb = *(const bf16x8*)(vbx + ((ct * 2 + s2) * 64 + lane) * 16);
;             a2 = MFMA16(qkf[s2], vb, a2);
;           }
; #pragma unroll
;           for (int jj = 0; jj < 4; ++jj) {
;             const int t = t0 + mt * 16 + quad * 4 + jj;
;             const float o = ge4[jj] * acco[m][ct][jj] + a2[jj];
;             if (t >= 0) r1[(size_t)t * 3072 + 2048 + h * 128 + vb0 + ct * 16 + l15] = f2bf(o);
;           }
;         }
;       }
.Lsc_out_odd:
	s_add_u32 s0, s0, 0x60000
	s_addc_u32 s1, s1, 0
	s_add_u32 s10, s10, 0x1800
	s_addc_u32 s11, s11, 0
	s_barrier
	ds_read_b128 v[60:63], v108 offset:6144
	ds_read_b128 v[64:67], v108 offset:7168
	ds_read_b128 v[68:71], v108 offset:8192
	ds_read_b128 v[72:75], v108 offset:9216
	ds_read_b128 v[8:11], v116 offset:16384
	ds_read_b128 v[12:15], v117 offset:16384
	ds_read_b128 v[16:19], v118 offset:16384
	ds_read_b128 v[20:23], v119 offset:16384
	ds_read_b128 v[24:27], v120 offset:16384
	ds_read_b128 v[28:31], v121 offset:16384
	ds_read_b128 v[32:35], v122 offset:16384
	ds_read_b128 v[36:39], v123 offset:16384
	ds_read_b128 v[76:79], v108 offset:10240
	ds_read_b128 v[80:83], v108 offset:11264
	s_waitcnt lgkmcnt(9)
	v_mfma_f32_16x16x32_bf16 v[84:87], v[60:63], v[8:11], 0
	s_waitcnt lgkmcnt(8)
	v_mfma_f32_16x16x32_bf16 v[84:87], v[64:67], v[12:15], v[84:87]
	s_waitcnt lgkmcnt(7)
	v_mfma_f32_16x16x32_bf16 v[84:87], v[68:71], v[16:19], v[84:87]
	s_waitcnt lgkmcnt(6)
	v_mfma_f32_16x16x32_bf16 v[84:87], v[72:75], v[20:23], v[84:87]
	s_waitcnt lgkmcnt(5)
	v_mfma_f32_16x16x32_bf16 v[88:91], v[60:63], v[24:27], 0
	s_waitcnt lgkmcnt(4)
	v_mfma_f32_16x16x32_bf16 v[88:91], v[64:67], v[28:31], v[88:91]
	s_waitcnt lgkmcnt(3)
	v_mfma_f32_16x16x32_bf16 v[88:91], v[68:71], v[32:35], v[88:91]
	s_waitcnt lgkmcnt(2)
	v_mfma_f32_16x16x32_bf16 v[88:91], v[72:75], v[36:39], v[88:91]
	ds_read_b128 v[40:43], v124 offset:8192
	ds_read_b128 v[44:47], v125 offset:8192
	ds_read_b128 v[48:51], v126 offset:8192
	ds_read_b128 v[52:55], v127 offset:8192
	s_waitcnt lgkmcnt(3)
	v_mfma_f32_16x16x32_bf16 v[92:95], v[76:79], v[40:43], 0
	s_waitcnt lgkmcnt(2)
	v_mfma_f32_16x16x32_bf16 v[92:95], v[80:83], v[44:47], v[92:95]
	s_waitcnt lgkmcnt(1)
	v_mfma_f32_16x16x32_bf16 v[96:99], v[76:79], v[48:51], 0
	s_waitcnt lgkmcnt(0)
	v_mfma_f32_16x16x32_bf16 v[96:99], v[80:83], v[52:55], v[96:99]
	s_lshl_b32 s36, s18, 2
	s_add_u32 s36, s36, s24
	s_waitcnt vmcnt(3)
	s_nop 4
	v_fma_f32 v110, -v56, v84, v92
	v_fma_f32 v111, -v56, v85, v93
	v_fma_f32 v112, -v56, v86, v94
	v_fma_f32 v113, -v56, v87, v95
	global_load_dword v56, v104, s[10:11]
	v_cvt_pk_bf16_f32 v114, v110, v111
	v_cvt_pk_bf16_f32 v115, v112, v113
	s_cmp_lt_u32 s36, 3
	s_cbranch_scc1 .Lsc_out_skip0_1
	global_store_dwordx2 v106, v[114:115], s[0:1]

; DEVI void scan_item(const Params& p, int h, int sl, char* smem) {
;     ...
;       }
;     }
;     __syncthreads();
;   }
.Lsc_out_skip1_1:
.Lsc_out_join:
	s_cmp_lg_u32 s18, 0
	s_cbranch_scc1 .Lsc_out_nodrain
	s_waitcnt vmcnt(0)

; DEVI void scan_item(const Params& p, int h, int sl, char* smem) {
;     ...
;   auto gload = [&](int n) {
;     const int t0 = n * 64 - 48;
; #pragma unroll
;     for (int i = 0; i < 4; ++i) {
;       const int ch = tid + i * 256, row = ch >> 4, kc = ch & 15;
;       const int t = t0 + row;
;       pw[i] = u32x4{0, 0, 0, 0};
;       if (t >= 0) pw[i] = *(const u32x4*)(r1 + (size_t)t * 3072 + 1024 + h * 128 + kc * 8);
;     }
;     const bf16_t* qk = r0 + R0_QK + (size_t)(n * 8 + h) * 4096;
; #pragma unroll
;     for (int i = 0; i < 2; ++i) pqk[i] = *(const u32x4*)(qk + (size_t)(tid + i * 256) * 8);
;     const bf16_t* kt = r0 + R0_KT + (size_t)(n * 8 + h) * 8192;
; #pragma unroll
;     for (int i = 0; i < 4; ++i) pkt[i] = *(const u32x4*)(kt + (size_t)(tid + i * 256) * 8);
;     if (tid < 48) pg = *(const u32x4*)((const float*)(r0 + R0_G) + (size_t)(n * 8 + h) * 192 + tid * 4);
;     if (tid < 64 * NW * 2) {
;       const int row = tid / (NW * 2), kc = tid % (NW * 2);
;       const int t = t0 + row;
;       pu = u32x4{0, 0, 0, 0};
;       if (t >= 0) pu = *(const u32x4*)(r1 + (size_t)t * 3072 + 2048 + h * 128 + vb0 + kc * 8);
;     }
;   };
;   auto lstore = [&]() {
; #pragma unroll
;     for (int i = 0; i < 4; ++i) {
;       const int ch = tid + i * 256, row = ch >> 4, kc = ch & 15;
;       *(u32x4*)(wsm + row * 272 + kc * 16) = pw[i];
;     }
;     if (tid < 48) *(u32x4*)(gsm + tid * 4) = pg;
;     if (tid < 64 * NW * 2) {
;       const int row = tid / (NW * 2), kc = tid % (NW * 2);
;       *(u32x4*)(usm + row * USTR + kc * 16) = pu;
;     }
;   };
;   auto lstore2 = [&]() {
; #pragma unroll
;     for (int i = 0; i < 2; ++i) {
;       const int ch = tid + i * 256, row = ch >> 3, kc = ch & 7;
;       *(u32x4*)(qksm + row * 144 + kc * 16) = pqk[i];
;     }
; #pragma unroll
;     for (int i = 0; i < 4; ++i) {
;       const int ch = tid + i * 256, row = ch >> 3, kc = ch & 7;
;       *(u32x4*)(ktsm + row * 144 + kc * 16) = pkt[i];
;     }
;   };
.Lsc_loader:
	s_lshl_b32 s40, s13, 5
	v_lshl_add_u32 v5, v3, 1, s40
	v_mul_u32_u24_e32 v6, 0x6000, v4
	v_add_u32_e32 v5, v5, v6
	v_add_u32_e32 v5, 0xc1000, v5
	v_mov_b32_e32 v120, v5
	v_add_u32_e32 v121, 0x1800, v5
	v_add_u32_e32 v122, 0x3000, v5
	v_add_u32_e32 v123, 0x4800, v5
	v_mul_u32_u24_e32 v6, 0x1800, v4
	v_lshl_add_u32 v5, v3, 4, v6
	v_add_u32_e32 v5, 0x60000, v5
	v_mov_b32_e32 v124, v5
	v_add_u32_e32 v6, 0, v4
	v_xor_b32_e32 v7, v6, v3
	v_lshlrev_b32_e32 v6, 8, v6
	v_lshl_add_u32 v130, v7, 4, v6
	v_add_u32_e32 v130, 12320, v130
	v_add_u32_e32 v125, 0x6000, v5
	v_add_u32_e32 v6, 4, v4
	v_xor_b32_e32 v7, v6, v3
	v_lshlrev_b32_e32 v6, 8, v6
	v_lshl_add_u32 v131, v7, 4, v6
	v_add_u32_e32 v131, 12320, v131
	v_add_u32_e32 v126, 0xc000, v5
	v_add_u32_e32 v6, 8, v4
	v_xor_b32_e32 v7, v6, v3
	v_lshlrev_b32_e32 v6, 8, v6
	v_lshl_add_u32 v132, v7, 4, v6
	v_add_u32_e32 v132, 12320, v132
	v_add_u32_e32 v127, 0x12000, v5
	v_add_u32_e32 v6, 12, v4
	v_xor_b32_e32 v7, v6, v3
	v_lshlrev_b32_e32 v6, 8, v6
	v_lshl_add_u32 v133, v7, 4, v6
	v_add_u32_e32 v133, 12320, v133
	v_lshlrev_b32_e32 v128, 4, v0
	v_add_u32_e32 v128, 0x10000, v128
	v_lshrrev_b32_e32 v5, 3, v0
	v_and_b32_e32 v6, 7, v0
	v_xor_b32_e32 v6, v6, v5
	v_lshlrev_b32_e32 v5, 7, v5
	v_lshl_add_u32 v134, v6, 4, v5
	v_add_u32_e32 v134, 45088, v134
	v_lshlrev_b32_e32 v129, 4, v0
	v_add_u32_e32 v129, 61472, v129
	s_add_u32 s6, s0, 0x18000
	s_addc_u32 s7, s1, 0
	s_add_u32 s10, s0, 0x30000
	s_addc_u32 s11, s1, 0
	s_add_u32 s16, s0, 0x48000
	s_addc_u32 s17, s1, 0
	s_lshl_b32 s40, s9, 13
	s_add_u32 s24, s14, 0x5ba4000
	s_addc_u32 s25, s15, 0
	s_add_u32 s24, s24, s40
	s_addc_u32 s25, s25, 0
	s_sub_u32 s36, s0, 0x60000
	s_subb_u32 s37, s1, 0
	s_sub_u32 s38, s6, 0x60000
	s_subb_u32 s39, s7, 0
	s_sub_u32 s40, s10, 0x60000
	s_subb_u32 s41, s11, 0
	s_sub_u32 s42, s16, 0x60000
	s_subb_u32 s43, s17, 0
	global_load_ushort v8, v120, s[36:37]
	global_load_ushort v9, v121, s[36:37]
	global_load_ushort v10, v122, s[36:37]
	global_load_ushort v11, v123, s[36:37]
	global_load_ushort v12, v120, s[38:39]
	global_load_ushort v13, v121, s[38:39]
	global_load_ushort v14, v122, s[38:39]
	global_load_ushort v15, v123, s[38:39]
	global_load_ushort v16, v120, s[40:41]
	global_load_ushort v17, v121, s[40:41]
	global_load_ushort v18, v122, s[40:41]
	global_load_ushort v19, v123, s[40:41]
	global_load_ushort v20, v120, s[42:43]
	global_load_ushort v21, v121, s[42:43]
	global_load_ushort v22, v122, s[42:43]
	global_load_ushort v23, v123, s[42:43]
	s_waitcnt vmcnt(0)
	v_mov_b32_e32 v8, 0
	v_mov_b32_e32 v9, 0
	v_mov_b32_e32 v10, 0
	v_mov_b32_e32 v11, 0
	v_mov_b32_e32 v12, 0
	v_mov_b32_e32 v13, 0
	v_mov_b32_e32 v14, 0
	v_mov_b32_e32 v15, 0
	v_mov_b32_e32 v16, 0
	v_mov_b32_e32 v17, 0
	v_mov_b32_e32 v18, 0
	v_mov_b32_e32 v19, 0
	v_lshlrev_b32_e32 v8, 16, v8
	v_lshlrev_b32_e32 v9, 16, v9
	v_lshlrev_b32_e32 v10, 16, v10
	v_lshlrev_b32_e32 v11, 16, v11
	v_lshlrev_b32_e32 v12, 16, v12
	v_lshlrev_b32_e32 v13, 16, v13
	v_lshlrev_b32_e32 v14, 16, v14
	v_lshlrev_b32_e32 v15, 16, v15
	v_lshlrev_b32_e32 v16, 16, v16
	v_lshlrev_b32_e32 v17, 16, v17
	v_lshlrev_b32_e32 v18, 16, v18
	v_lshlrev_b32_e32 v19, 16, v19
	v_lshlrev_b32_e32 v20, 16, v20
	v_lshlrev_b32_e32 v21, 16, v21
	v_lshlrev_b32_e32 v22, 16, v22
	v_lshlrev_b32_e32 v23, 16, v23
	ds_write_b128 v129, v[8:11] offset:0
	ds_write_b128 v129, v[12:15] offset:1024
	ds_write_b128 v129, v[16:19] offset:2048
	ds_write_b128 v129, v[20:23] offset:3072
	global_load_dwordx4 v[24:27], v124, s[0:1]
	global_load_dwordx4 v[28:31], v125, s[0:1]
	global_load_dwordx4 v[32:35], v126, s[0:1]
	global_load_dwordx4 v[36:39], v127, s[0:1]
	global_load_dwordx4 v[40:43], v124, s[6:7]
	global_load_dwordx4 v[44:47], v125, s[6:7]
	global_load_dwordx4 v[48:51], v126, s[6:7]
	global_load_dwordx4 v[52:55], v127, s[6:7]
	global_load_dwordx4 v[56:59], v124, s[10:11]
	global_load_dwordx4 v[60:63], v125, s[10:11]
	global_load_dwordx4 v[64:67], v126, s[10:11]
	global_load_dwordx4 v[68:71], v127, s[10:11]
	global_load_dwordx4 v[72:75], v124, s[16:17]
	global_load_dwordx4 v[76:79], v125, s[16:17]
	global_load_dwordx4 v[80:83], v126, s[16:17]
	global_load_dwordx4 v[84:87], v127, s[16:17]
	global_load_dwordx4 v[88:91], v128, s[24:25] offset:-4096
	global_load_dwordx4 v[92:95], v128, s[24:25] offset:-3072
	global_load_dwordx4 v[96:99], v128, s[24:25] offset:-2048
	global_load_dwordx4 v[100:103], v128, s[24:25] offset:-1024
	global_load_dwordx4 v[104:107], v128, s[24:25] offset:0
	global_load_dwordx4 v[108:111], v128, s[24:25] offset:1024
	global_load_dwordx4 v[112:115], v128, s[24:25] offset:2048
	global_load_dwordx4 v[116:119], v128, s[24:25] offset:3072
	global_load_ushort v8, v120, s[0:1]
	global_load_ushort v9, v121, s[0:1]
	global_load_ushort v10, v122, s[0:1]
	global_load_ushort v11, v123, s[0:1]
	global_load_ushort v12, v120, s[6:7]
	global_load_ushort v13, v121, s[6:7]
	global_load_ushort v14, v122, s[6:7]
	global_load_ushort v15, v123, s[6:7]
	global_load_ushort v16, v120, s[10:11]
	global_load_ushort v17, v121, s[10:11]
	global_load_ushort v18, v122, s[10:11]
	global_load_ushort v19, v123, s[10:11]
	global_load_ushort v20, v120, s[16:17]
	global_load_ushort v21, v121, s[16:17]
	global_load_ushort v22, v122, s[16:17]
	global_load_ushort v23, v123, s[16:17]
	s_waitcnt lgkmcnt(0)
	s_barrier
	s_mov_b32 s18, 0
; DEVI void scan_item(const Params& p, int h, int sl, char* smem) {
;     ...
;   auto lstore = [&]() {
; #pragma unroll
;     for (int i = 0; i < 4; ++i) {
;       const int ch = tid + i * 256, row = ch >> 4, kc = ch & 15;
;       *(u32x4*)(wsm + row * 272 + kc * 16) = pw[i];
;     }
;     if (tid < 48) *(u32x4*)(gsm + tid * 4) = pg;
;     if (tid < 64 * NW * 2) {
;       const int row = tid / (NW * 2), kc = tid % (NW * 2);
;       *(u32x4*)(usm + row * USTR + kc * 16) = pu;
;     }
;   };
;   auto lstore2 = [&]() {
; #pragma unroll
;     for (int i = 0; i < 2; ++i) {
;       const int ch = tid + i * 256, row = ch >> 3, kc = ch & 7;
;       *(u32x4*)(qksm + row * 144 + kc * 16) = pqk[i];
;     }
; #pragma unroll
;     for (int i = 0; i < 4; ++i) {
;       const int ch = tid + i * 256, row = ch >> 3, kc = ch & 7;
;       *(u32x4*)(ktsm + row * 144 + kc * 16) = pkt[i];
;     }
;   };
.Lsc_ld_loop:
	s_bitcmp1_b32 s18, 0
	s_cbranch_scc1 .Lsc_ld_odd
	s_waitcnt vmcnt(0)
	ds_write_b128 v130, v[24:27] offset:0
	ds_write_b128 v131, v[28:31] offset:0
	ds_write_b128 v132, v[32:35] offset:0
	ds_write_b128 v133, v[36:39] offset:0
	ds_write_b128 v130, v[40:43] offset:4096
	ds_write_b128 v131, v[44:47] offset:4096
	ds_write_b128 v132, v[48:51] offset:4096
	ds_write_b128 v133, v[52:55] offset:4096
	ds_write_b128 v130, v[56:59] offset:8192
	ds_write_b128 v131, v[60:63] offset:8192
	ds_write_b128 v132, v[64:67] offset:8192
	ds_write_b128 v133, v[68:71] offset:8192
	ds_write_b128 v130, v[72:75] offset:12288
	ds_write_b128 v131, v[76:79] offset:12288
	ds_write_b128 v132, v[80:83] offset:12288
	ds_write_b128 v133, v[84:87] offset:12288
	ds_write_b128 v134, v[88:91] offset:0
	ds_write_b128 v134, v[92:95] offset:1024
	ds_write_b128 v134, v[96:99] offset:2048
	ds_write_b128 v134, v[100:103] offset:3072
	ds_write_b128 v134, v[104:107] offset:4096
	ds_write_b128 v134, v[108:111] offset:5120
	ds_write_b128 v134, v[112:115] offset:6144
	ds_write_b128 v134, v[116:119] offset:7168
	v_lshlrev_b32_e32 v8, 16, v8
	v_lshlrev_b32_e32 v9, 16, v9
	v_lshlrev_b32_e32 v10, 16, v10
	v_lshlrev_b32_e32 v11, 16, v11
	v_lshlrev_b32_e32 v12, 16, v12
	v_lshlrev_b32_e32 v13, 16, v13
	v_lshlrev_b32_e32 v14, 16, v14
	v_lshlrev_b32_e32 v15, 16, v15
	v_lshlrev_b32_e32 v16, 16, v16
	v_lshlrev_b32_e32 v17, 16, v17
	v_lshlrev_b32_e32 v18, 16, v18
	v_lshlrev_b32_e32 v19, 16, v19
	v_lshlrev_b32_e32 v20, 16, v20
	v_lshlrev_b32_e32 v21, 16, v21
	v_lshlrev_b32_e32 v22, 16, v22
	v_lshlrev_b32_e32 v23, 16, v23
	ds_write_b128 v129, v[8:11] offset:4096
	ds_write_b128 v129, v[12:15] offset:5120
	ds_write_b128 v129, v[16:19] offset:6144
	ds_write_b128 v129, v[20:23] offset:7168
	s_add_u32 s0, s0, 0x60000
	s_addc_u32 s1, s1, 0
	s_add_u32 s6, s6, 0x60000
	s_addc_u32 s7, s7, 0
	s_add_u32 s10, s10, 0x60000
	s_addc_u32 s11, s11, 0
	s_add_u32 s16, s16, 0x60000
	s_addc_u32 s17, s17, 0
	s_add_u32 s24, s24, 0x10000
	s_addc_u32 s25, s25, 0
	s_cmp_ge_u32 s18, 256
	s_cbranch_scc1 .Lsc_ld_noload0
	global_load_dwordx4 v[24:27], v124, s[0:1]
	global_load_dwordx4 v[28:31], v125, s[0:1]
	global_load_dwordx4 v[32:35], v126, s[0:1]
	global_load_dwordx4 v[36:39], v127, s[0:1]
	global_load_dwordx4 v[40:43], v124, s[6:7]
	global_load_dwordx4 v[44:47], v125, s[6:7]
	global_load_dwordx4 v[48:51], v126, s[6:7]
	global_load_dwordx4 v[52:55], v127, s[6:7]
	global_load_dwordx4 v[56:59], v124, s[10:11]
	global_load_dwordx4 v[60:63], v125, s[10:11]
	global_load_dwordx4 v[64:67], v126, s[10:11]
	global_load_dwordx4 v[68:71], v127, s[10:11]
	global_load_dwordx4 v[72:75], v124, s[16:17]
	global_load_dwordx4 v[76:79], v125, s[16:17]
	global_load_dwordx4 v[80:83], v126, s[16:17]
	global_load_dwordx4 v[84:87], v127, s[16:17]
	global_load_dwordx4 v[88:91], v128, s[24:25] offset:-4096
	global_load_dwordx4 v[92:95], v128, s[24:25] offset:-3072
	global_load_dwordx4 v[96:99], v128, s[24:25] offset:-2048
	global_load_dwordx4 v[100:103], v128, s[24:25] offset:-1024
	global_load_dwordx4 v[104:107], v128, s[24:25] offset:0
	global_load_dwordx4 v[108:111], v128, s[24:25] offset:1024
	global_load_dwordx4 v[112:115], v128, s[24:25] offset:2048
	global_load_dwordx4 v[116:119], v128, s[24:25] offset:3072
	global_load_ushort v8, v120, s[0:1]
	global_load_ushort v9, v121, s[0:1]
	global_load_ushort v10, v122, s[0:1]
	global_load_ushort v11, v123, s[0:1]
	global_load_ushort v12, v120, s[6:7]
	global_load_ushort v13, v121, s[6:7]
	global_load_ushort v14, v122, s[6:7]
	global_load_ushort v15, v123, s[6:7]
	global_load_ushort v16, v120, s[10:11]
	global_load_ushort v17, v121, s[10:11]
	global_load_ushort v18, v122, s[10:11]
	global_load_ushort v19, v123, s[10:11]
	global_load_ushort v20, v120, s[16:17]
	global_load_ushort v21, v121, s[16:17]
	global_load_ushort v22, v122, s[16:17]
	global_load_ushort v23, v123, s[16:17]
.Lsc_ld_noload0:
	s_waitcnt lgkmcnt(0)
	s_barrier
	s_branch .Lsc_ld_join
.Lsc_ld_odd:
	s_waitcnt vmcnt(0)
	ds_write_b128 v130, v[24:27] offset:16384
	ds_write_b128 v131, v[28:31] offset:16384
	ds_write_b128 v132, v[32:35] offset:16384
	ds_write_b128 v133, v[36:39] offset:16384
	ds_write_b128 v130, v[40:43] offset:20480
	ds_write_b128 v131, v[44:47] offset:20480
	ds_write_b128 v132, v[48:51] offset:20480
	ds_write_b128 v133, v[52:55] offset:20480
	ds_write_b128 v130, v[56:59] offset:24576
	ds_write_b128 v131, v[60:63] offset:24576
	ds_write_b128 v132, v[64:67] offset:24576
	ds_write_b128 v133, v[68:71] offset:24576
	ds_write_b128 v130, v[72:75] offset:28672
	ds_write_b128 v131, v[76:79] offset:28672
	ds_write_b128 v132, v[80:83] offset:28672
	ds_write_b128 v133, v[84:87] offset:28672
	ds_write_b128 v134, v[88:91] offset:8192
	ds_write_b128 v134, v[92:95] offset:9216
	ds_write_b128 v134, v[96:99] offset:10240
	ds_write_b128 v134, v[100:103] offset:11264
	ds_write_b128 v134, v[104:107] offset:12288
	ds_write_b128 v134, v[108:111] offset:13312
	ds_write_b128 v134, v[112:115] offset:14336
	ds_write_b128 v134, v[116:119] offset:15360
	v_lshlrev_b32_e32 v8, 16, v8
	v_lshlrev_b32_e32 v9, 16, v9
	v_lshlrev_b32_e32 v10, 16, v10
	v_lshlrev_b32_e32 v11, 16, v11
	v_lshlrev_b32_e32 v12, 16, v12
	v_lshlrev_b32_e32 v13, 16, v13
	v_lshlrev_b32_e32 v14, 16, v14
	v_lshlrev_b32_e32 v15, 16, v15
	v_lshlrev_b32_e32 v16, 16, v16
	v_lshlrev_b32_e32 v17, 16, v17
	v_lshlrev_b32_e32 v18, 16, v18
	v_lshlrev_b32_e32 v19, 16, v19
	v_lshlrev_b32_e32 v20, 16, v20
	v_lshlrev_b32_e32 v21, 16, v21
	v_lshlrev_b32_e32 v22, 16, v22
	v_lshlrev_b32_e32 v23, 16, v23
	ds_write_b128 v129, v[8:11] offset:0
	ds_write_b128 v129, v[12:15] offset:1024
	ds_write_b128 v129, v[16:19] offset:2048
	ds_write_b128 v129, v[20:23] offset:3072
	s_add_u32 s0, s0, 0x60000
	s_addc_u32 s1, s1, 0
	s_add_u32 s6, s6, 0x60000
	s_addc_u32 s7, s7, 0
	s_add_u32 s10, s10, 0x60000
	s_addc_u32 s11, s11, 0
	s_add_u32 s16, s16, 0x60000
	s_addc_u32 s17, s17, 0
	s_add_u32 s24, s24, 0x10000
	s_addc_u32 s25, s25, 0
	s_cmp_ge_u32 s18, 256
	s_cbranch_scc1 .Lsc_ld_noload1
; DEVI void scan_item(const Params& p, int h, int sl, char* smem) {
;     ...
;   auto gload = [&](int n) {
;     const int t0 = n * 64 - 48;
; #pragma unroll
;     for (int i = 0; i < 4; ++i) {
;       const int ch = tid + i * 256, row = ch >> 4, kc = ch & 15;
;       const int t = t0 + row;
;       pw[i] = u32x4{0, 0, 0, 0};
;       if (t >= 0) pw[i] = *(const u32x4*)(r1 + (size_t)t * 3072 + 1024 + h * 128 + kc * 8);
;     }
;     const bf16_t* qk = r0 + R0_QK + (size_t)(n * 8 + h) * 4096;
; #pragma unroll
;     for (int i = 0; i < 2; ++i) pqk[i] = *(const u32x4*)(qk + (size_t)(tid + i * 256) * 8);
;     const bf16_t* kt = r0 + R0_KT + (size_t)(n * 8 + h) * 8192;
; #pragma unroll
;     for (int i = 0; i < 4; ++i) pkt[i] = *(const u32x4*)(kt + (size_t)(tid + i * 256) * 8);
;     if (tid < 48) pg = *(const u32x4*)((const float*)(r0 + R0_G) + (size_t)(n * 8 + h) * 192 + tid * 4);
;     if (tid < 64 * NW * 2) {
;       const int row = tid / (NW * 2), kc = tid % (NW * 2);
;       const int t = t0 + row;
;       pu = u32x4{0, 0, 0, 0};
;       if (t >= 0) pu = *(const u32x4*)(r1 + (size_t)t * 3072 + 2048 + h * 128 + vb0 + kc * 8);
;     }
;   };
;     ...
;   f32x4 S[8];
; #pragma unroll
;   for (int r = 0; r < 8; ++r) S[r] = f32x4{0.f, 0.f, 0.f, 0.f};
;   gload(0);
;   if (!is_state) qload(0);
	global_load_dwordx4 v[24:27], v124, s[0:1]
	global_load_dwordx4 v[28:31], v125, s[0:1]
	global_load_dwordx4 v[32:35], v126, s[0:1]
	global_load_dwordx4 v[36:39], v127, s[0:1]
	global_load_dwordx4 v[40:43], v124, s[6:7]
	global_load_dwordx4 v[44:47], v125, s[6:7]
	global_load_dwordx4 v[48:51], v126, s[6:7]
	global_load_dwordx4 v[52:55], v127, s[6:7]
	global_load_dwordx4 v[56:59], v124, s[10:11]
	global_load_dwordx4 v[60:63], v125, s[10:11]
	global_load_dwordx4 v[64:67], v126, s[10:11]
	global_load_dwordx4 v[68:71], v127, s[10:11]
	global_load_dwordx4 v[72:75], v124, s[16:17]
	global_load_dwordx4 v[76:79], v125, s[16:17]
	global_load_dwordx4 v[80:83], v126, s[16:17]
	global_load_dwordx4 v[84:87], v127, s[16:17]
	global_load_dwordx4 v[88:91], v128, s[24:25] offset:-4096
	global_load_dwordx4 v[92:95], v128, s[24:25] offset:-3072
	global_load_dwordx4 v[96:99], v128, s[24:25] offset:-2048
	global_load_dwordx4 v[100:103], v128, s[24:25] offset:-1024
	global_load_dwordx4 v[104:107], v128, s[24:25] offset:0
	global_load_dwordx4 v[108:111], v128, s[24:25] offset:1024
	global_load_dwordx4 v[112:115], v128, s[24:25] offset:2048
	global_load_dwordx4 v[116:119], v128, s[24:25] offset:3072
	global_load_ushort v8, v120, s[0:1]
	global_load_ushort v9, v121, s[0:1]
	global_load_ushort v10, v122, s[0:1]
	global_load_ushort v11, v123, s[0:1]
	global_load_ushort v12, v120, s[6:7]
	global_load_ushort v13, v121, s[6:7]
	global_load_ushort v14, v122, s[6:7]
	global_load_ushort v15, v123, s[6:7]
	global_load_ushort v16, v120, s[10:11]
	global_load_ushort v17, v121, s[10:11]
	global_load_ushort v18, v122, s[10:11]
	global_load_ushort v19, v123, s[10:11]
	global_load_ushort v20, v120, s[16:17]
	global_load_ushort v21, v121, s[16:17]
	global_load_ushort v22, v122, s[16:17]
	global_load_ushort v23, v123, s[16:17]
.Lsc_ld_noload1:
	s_waitcnt lgkmcnt(0)
	s_barrier
.Lsc_ld_join:
	s_add_u32 s18, s18, 1
	s_cmp_lt_u32 s18, 257
	s_cbranch_scc1 .Lsc_ld_loop
	s_branch .Lsc_done
.Lsc_state:
	s_setprio 3
	v_mul_u32_u24_e32 v5, 0x1800, v4
	v_lshl_add_u32 v5, v3, 4, v5
	v_add_u32_e32 v5, 0x60800, v5
	v_mov_b32_e32 v178, v5
	v_add_u32_e32 v179, 0x6000, v5
	v_add_u32_e32 v180, 0xc000, v5
	v_add_u32_e32 v181, 0x12000, v5
	v_lshlrev_b32_e32 v182, 4, v0
	v_add_u32_e32 v182, 0x20000, v182
	v_lshlrev_b32_e32 v183, 4, v4
	v_add_u32_e32 v183, 0x1900, v183
	v_lshlrev_b32_e32 v184, 4, v0
	v_add_u32_e32 v185, 61472, v184
	v_add_u32_e32 v184, 32, v184
	s_add_u32 s6, s0, 0x18000
	s_addc_u32 s7, s1, 0
	s_add_u32 s10, s0, 0x30000
	s_addc_u32 s11, s1, 0
	s_add_u32 s16, s0, 0x48000
	s_addc_u32 s17, s1, 0
	s_lshl_b32 s18, s9, 14
	s_add_u32 s24, s14, 0x3b74000
	s_addc_u32 s25, s15, 0
	s_add_u32 s24, s24, s18
	s_addc_u32 s25, s25, 0
	s_add_u32 s36, s24, 0x2000
	s_addc_u32 s37, s25, 0
	s_mul_i32 s18, s9, 0x300
	s_add_u32 s38, s14, 0x6bc1800
	s_addc_u32 s39, s15, 0
	s_add_u32 s38, s38, s18
	s_addc_u32 s39, s39, 0
	v_mov_b32_e32 v2, 0
	v_mov_b32_e32 v3, 0
	v_mov_b32_e32 v4, 0
	v_mov_b32_e32 v5, 0
	v_mov_b32_e32 v6, 0
	v_mov_b32_e32 v7, 0
	v_mov_b32_e32 v8, 0
	v_mov_b32_e32 v9, 0
	v_mov_b32_e32 v10, 0
	v_mov_b32_e32 v11, 0
	v_mov_b32_e32 v12, 0
	v_mov_b32_e32 v13, 0
	v_mov_b32_e32 v14, 0
	v_mov_b32_e32 v15, 0
	v_mov_b32_e32 v16, 0
	v_mov_b32_e32 v17, 0
	v_mov_b32_e32 v18, 0
	v_mov_b32_e32 v19, 0
	v_mov_b32_e32 v20, 0
	v_mov_b32_e32 v21, 0
	v_mov_b32_e32 v22, 0
	v_mov_b32_e32 v23, 0
	v_mov_b32_e32 v24, 0
	v_mov_b32_e32 v25, 0
	v_mov_b32_e32 v26, 0
	v_mov_b32_e32 v27, 0
	v_mov_b32_e32 v28, 0
	v_mov_b32_e32 v29, 0
	v_mov_b32_e32 v30, 0
	v_mov_b32_e32 v31, 0
	v_mov_b32_e32 v32, 0
	v_mov_b32_e32 v33, 0
	global_load_dwordx4 v[98:101], v182, s[24:25] offset:-4096
	global_load_dwordx4 v[102:105], v182, s[24:25] offset:-3072
	global_load_dwordx4 v[106:109], v182, s[24:25] offset:-2048
	global_load_dwordx4 v[110:113], v182, s[24:25] offset:-1024
	global_load_dwordx4 v[114:117], v182, s[24:25] offset:0
	global_load_dwordx4 v[118:121], v182, s[24:25] offset:1024
	global_load_dwordx4 v[122:125], v182, s[24:25] offset:2048
	global_load_dwordx4 v[126:129], v182, s[24:25] offset:3072
	global_load_dwordx4 v[130:133], v182, s[36:37] offset:-4096
	global_load_dwordx4 v[134:137], v182, s[36:37] offset:-3072
	global_load_dwordx4 v[138:141], v182, s[36:37] offset:-2048
	global_load_dwordx4 v[142:145], v182, s[36:37] offset:-1024
	global_load_dwordx4 v[146:149], v182, s[36:37] offset:0
	global_load_dwordx4 v[150:153], v182, s[36:37] offset:1024
	global_load_dwordx4 v[154:157], v182, s[36:37] offset:2048
	global_load_dwordx4 v[158:161], v182, s[36:37] offset:3072
	global_load_dwordx4 v[226:229], v183, s[38:39] offset:0
	global_load_dwordx4 v[230:233], v183, s[38:39] offset:64
	global_load_dwordx4 v[234:237], v183, s[38:39] offset:128
	global_load_dwordx4 v[238:241], v183, s[38:39] offset:192
	s_load_dword s62, s[38:39], 0x1a00
	v_mov_b32_e32 v34, 0
	v_mov_b32_e32 v35, 0
	v_mov_b32_e32 v36, 0
	v_mov_b32_e32 v37, 0
	v_mov_b32_e32 v38, 0
	v_mov_b32_e32 v39, 0
	v_mov_b32_e32 v40, 0
	v_mov_b32_e32 v41, 0
	v_mov_b32_e32 v42, 0
	v_mov_b32_e32 v43, 0
	v_mov_b32_e32 v44, 0
	v_mov_b32_e32 v45, 0
	v_mov_b32_e32 v46, 0
	v_mov_b32_e32 v47, 0
	v_mov_b32_e32 v48, 0
	v_mov_b32_e32 v49, 0
	v_mov_b32_e32 v50, 0
	v_mov_b32_e32 v51, 0
	v_mov_b32_e32 v52, 0
	v_mov_b32_e32 v53, 0
	v_mov_b32_e32 v54, 0
	v_mov_b32_e32 v55, 0
	v_mov_b32_e32 v56, 0
	v_mov_b32_e32 v57, 0
	v_mov_b32_e32 v58, 0
	v_mov_b32_e32 v59, 0
	v_mov_b32_e32 v60, 0
	v_mov_b32_e32 v61, 0
	v_mov_b32_e32 v62, 0
	v_mov_b32_e32 v63, 0
	v_mov_b32_e32 v64, 0
	v_mov_b32_e32 v65, 0
	v_mov_b32_e32 v66, 0
	v_mov_b32_e32 v67, 0
	v_mov_b32_e32 v68, 0
	v_mov_b32_e32 v69, 0
	v_mov_b32_e32 v70, 0
	v_mov_b32_e32 v71, 0
	v_mov_b32_e32 v72, 0
	v_mov_b32_e32 v73, 0
	v_mov_b32_e32 v74, 0
	v_mov_b32_e32 v75, 0
	v_mov_b32_e32 v76, 0
	v_mov_b32_e32 v77, 0
	v_mov_b32_e32 v78, 0
	v_mov_b32_e32 v79, 0
	v_mov_b32_e32 v80, 0
	v_mov_b32_e32 v81, 0
	v_mov_b32_e32 v82, 0
	v_mov_b32_e32 v83, 0
	v_mov_b32_e32 v84, 0
	v_mov_b32_e32 v85, 0
	v_mov_b32_e32 v86, 0
	v_mov_b32_e32 v87, 0
	v_mov_b32_e32 v88, 0
	v_mov_b32_e32 v89, 0
	v_mov_b32_e32 v90, 0
	v_mov_b32_e32 v91, 0
	v_mov_b32_e32 v92, 0
	v_mov_b32_e32 v93, 0
	v_mov_b32_e32 v94, 0
	v_mov_b32_e32 v95, 0
	v_mov_b32_e32 v96, 0
	v_mov_b32_e32 v97, 0
	s_waitcnt vmcnt(0) lgkmcnt(0)
	s_barrier
	ds_read_b128 v[190:193], v185 offset:0
	ds_read_b128 v[194:197], v185 offset:1024
	ds_read_b128 v[198:201], v185 offset:2048
	ds_read_b128 v[202:205], v185 offset:3072
	s_mov_b32 s18, 0
; DEVI float bf2f(bf16_t b) { return __uint_as_float(((unsigned)b) << 16); }
; #define MFMA16(a, b, c) __builtin_amdgcn_mfma_f32_16x16x32_bf16((a), (b), (c), 0, 0, 0)
; DEVI void scan_item(const Params& p, int h, int sl, char* smem) {
;     ...
;     lstore();
;     if (is_state) {
; #pragma unroll
;       for (int s = 0; s < 4; ++s) *(bf16x8*)(sbx + ((cw * 4 + s) * 64 + lane) * 16) = pack8(S[2 * s], S[2 * s + 1]);
;     }
;     __syncthreads();
;     lstore2();
;     if (n + 1 < NCH) gload(n + 1);
;     if (is_state) {
;       bf16x8 sb[4];
; #pragma unroll
;       for (int s = 0; s < 4; ++s) sb[s] = pack8(S[2 * s], S[2 * s + 1]);
;       f32x4 vnew[4];
; #pragma unroll
;       for (int mt = 0; mt < 4; ++mt) vnew[mt] = f32x4{0.f, 0.f, 0.f, 0.f};
; #pragma unroll
;       for (int s = 0; s < 4; ++s) {
; #pragma unroll
;         for (int mt = 0; mt < 4; ++mt) {
;           const char* aw = wsm + (mt * 16 + l15) * 272 + s * 64 + quad * 8;
;           bf16x8 wf = mk8(*(const u32x2*)aw, *(const u32x2*)(aw + 32));
;           vnew[mt] = MFMA16(wf, sb[s], vnew[mt]);
;         }
;       }
; #pragma unroll
;       for (int mt = 0; mt < 4; ++mt) {
; #pragma unroll
;         for (int jj = 0; jj < 4; ++jj) {
;           const int cidx = mt * 16 + quad * 4 + jj;
;           const float u = bf2f(*(const unsigned short*)(usm + cidx * USTR + (cw * 16 + l15) * 2));
;           vnew[mt][jj] = u - vnew[mt][jj];
;         }
;       }
; #pragma unroll
;       for (int s2 = 0; s2 < 2; ++s2)
;         *(bf16x8*)(vbx + ((cw * 2 + s2) * 64 + lane) * 16) = pack8(vnew[2 * s2], vnew[2 * s2 + 1]);
;       __syncthreads();
;       const float eglast = gsm[128];
;       bf16x8 vb[2];
; #pragma unroll
;       for (int mt = 0; mt < 4; ++mt) {
;         const f32x4 gd4 = *(const f32x4*)(gsm + 64 + mt * 16 + quad * 4);
;         vnew[mt] = vnew[mt] * gd4;
;       }
; #pragma unroll
;       for (int s2 = 0; s2 < 2; ++s2) vb[s2] = pack8(vnew[2 * s2], vnew[2 * s2 + 1]);
; #pragma unroll
;       for (int r = 0; r < 8; ++r) S[r] = S[r] * eglast;
; #pragma unroll
;       for (int s2 = 0; s2 < 2; ++s2) {
; #pragma unroll
;         for (int r = 0; r < 8; ++r) {
;           const char* ap = ktsm + (r * 16 + l15) * 144 + s2 * 64 + quad * 8;
;           bf16x8 f = mk8(*(const u32x2*)ap, *(const u32x2*)(ap + 32));
;           S[r] = MFMA16(f, vb[s2], S[r]);
;         }
;       }
.Lsc_st_loop:
	s_bitcmp1_b32 s18, 0
	s_cbranch_scc1 .Lsc_st_odd
	s_add_u32 s0, s0, 0x60000
	s_addc_u32 s1, s1, 0
	s_add_u32 s6, s6, 0x60000
	s_addc_u32 s7, s7, 0
	s_add_u32 s10, s10, 0x60000
	s_addc_u32 s11, s11, 0
	s_add_u32 s16, s16, 0x60000
	s_addc_u32 s17, s17, 0
	s_add_u32 s24, s24, 0x20000
	s_addc_u32 s25, s25, 0
	s_add_u32 s36, s36, 0x20000
	s_addc_u32 s37, s37, 0
	s_add_u32 s38, s38, 0x1800
	s_addc_u32 s39, s39, 0
	v_cvt_pk_bf16_f32 v162, v2, v3
	v_cvt_pk_bf16_f32 v163, v4, v5
	v_cvt_pk_bf16_f32 v164, v6, v7
	v_cvt_pk_bf16_f32 v165, v8, v9
	ds_write_b128 v184, v[162:165] offset:0
	v_cvt_pk_bf16_f32 v166, v10, v11
	v_cvt_pk_bf16_f32 v167, v12, v13
	v_cvt_pk_bf16_f32 v168, v14, v15
	v_cvt_pk_bf16_f32 v169, v16, v17
	ds_write_b128 v184, v[166:169] offset:1024
	v_cvt_pk_bf16_f32 v170, v18, v19
	v_cvt_pk_bf16_f32 v171, v20, v21
	v_cvt_pk_bf16_f32 v172, v22, v23
	v_cvt_pk_bf16_f32 v173, v24, v25
	ds_write_b128 v184, v[170:173] offset:2048
	v_cvt_pk_bf16_f32 v174, v26, v27
	v_cvt_pk_bf16_f32 v175, v28, v29
	v_cvt_pk_bf16_f32 v176, v30, v31
	v_cvt_pk_bf16_f32 v177, v32, v33
	ds_write_b128 v184, v[174:177] offset:3072
	s_waitcnt vmcnt(35) lgkmcnt(4)
	v_mfma_f32_16x16x32_bf16 v[190:193], v[34:37], v[162:165], v[190:193]
	global_load_dwordx4 v[34:37], v178, s[0:1]
	v_mul_f32_e32 v2, s62, v2
	v_mul_f32_e32 v3, s62, v3
	s_waitcnt vmcnt(35)
	v_mfma_f32_16x16x32_bf16 v[194:197], v[50:53], v[162:165], v[194:197]
	global_load_dwordx4 v[50:53], v178, s[6:7]
	v_mul_f32_e32 v4, s62, v4
	v_mul_f32_e32 v5, s62, v5
	s_waitcnt vmcnt(35)
	v_mfma_f32_16x16x32_bf16 v[190:193], v[38:41], v[166:169], v[190:193]
	global_load_dwordx4 v[38:41], v179, s[0:1]
	v_mul_f32_e32 v6, s62, v6
	v_mul_f32_e32 v7, s62, v7
	s_waitcnt vmcnt(35)
	v_mfma_f32_16x16x32_bf16 v[194:197], v[54:57], v[166:169], v[194:197]
	global_load_dwordx4 v[54:57], v179, s[6:7]
	v_mul_f32_e32 v8, s62, v8
	v_mul_f32_e32 v9, s62, v9
	s_waitcnt vmcnt(35)
	v_mfma_f32_16x16x32_bf16 v[190:193], v[42:45], v[170:173], v[190:193]
	global_load_dwordx4 v[42:45], v180, s[0:1]
	v_mul_f32_e32 v10, s62, v10
	v_mul_f32_e32 v11, s62, v11
	s_waitcnt vmcnt(35)
	v_mfma_f32_16x16x32_bf16 v[194:197], v[58:61], v[170:173], v[194:197]
	global_load_dwordx4 v[58:61], v180, s[6:7]
	v_mul_f32_e32 v12, s62, v12
	v_mul_f32_e32 v13, s62, v13
	s_waitcnt vmcnt(35)
	v_mfma_f32_16x16x32_bf16 v[198:201], v[66:69], v[162:165], v[198:201]
	global_load_dwordx4 v[66:69], v178, s[10:11]
	v_mul_f32_e32 v14, s62, v14
	v_mul_f32_e32 v15, s62, v15
	s_waitcnt vmcnt(35)
	v_mfma_f32_16x16x32_bf16 v[202:205], v[82:85], v[162:165], v[202:205]
	global_load_dwordx4 v[82:85], v178, s[16:17]
	v_mul_f32_e32 v16, s62, v16
	v_mul_f32_e32 v17, s62, v17
	s_waitcnt vmcnt(35)
	v_mfma_f32_16x16x32_bf16 v[198:201], v[70:73], v[166:169], v[198:201]
	global_load_dwordx4 v[70:73], v179, s[10:11]
	v_mul_f32_e32 v18, s62, v18
	v_mul_f32_e32 v19, s62, v19
	s_waitcnt vmcnt(35)
	v_mfma_f32_16x16x32_bf16 v[202:205], v[86:89], v[166:169], v[202:205]
	global_load_dwordx4 v[86:89], v179, s[16:17]
	v_mul_f32_e32 v20, s62, v20
	v_mul_f32_e32 v21, s62, v21
	s_waitcnt vmcnt(35)
	v_mfma_f32_16x16x32_bf16 v[198:201], v[74:77], v[170:173], v[198:201]
	global_load_dwordx4 v[74:77], v180, s[10:11]
	v_mul_f32_e32 v22, s62, v22
	v_mul_f32_e32 v23, s62, v23
	s_waitcnt vmcnt(35)
	v_mfma_f32_16x16x32_bf16 v[202:205], v[90:93], v[170:173], v[202:205]
	global_load_dwordx4 v[90:93], v180, s[16:17]
	v_mul_f32_e32 v24, s62, v24
	v_mul_f32_e32 v25, s62, v25
	s_waitcnt vmcnt(35)
	v_mfma_f32_16x16x32_bf16 v[190:193], v[46:49], v[174:177], v[190:193]
	global_load_dwordx4 v[46:49], v181, s[0:1]
	v_mul_f32_e32 v26, s62, v26
	v_mul_f32_e32 v27, s62, v27
	s_waitcnt vmcnt(35)
	v_mfma_f32_16x16x32_bf16 v[194:197], v[62:65], v[174:177], v[194:197]
	global_load_dwordx4 v[62:65], v181, s[6:7]
	v_mul_f32_e32 v28, s62, v28
	v_mul_f32_e32 v29, s62, v29
	s_waitcnt vmcnt(35)
	v_mfma_f32_16x16x32_bf16 v[198:201], v[78:81], v[174:177], v[198:201]
	global_load_dwordx4 v[78:81], v181, s[10:11]
	v_mul_f32_e32 v30, s62, v30
	v_mul_f32_e32 v31, s62, v31
	s_waitcnt vmcnt(35)
	v_mfma_f32_16x16x32_bf16 v[202:205], v[94:97], v[174:177], v[202:205]
	global_load_dwordx4 v[94:97], v181, s[16:17]
	v_mul_f32_e32 v32, s62, v32
	v_mul_f32_e32 v33, s62, v33
	s_load_dword s62, s[38:39], 0x1a00
	s_waitcnt vmcnt(35)
	v_cvt_pk_bf16_f32 v162, v190, v191
	v_cvt_pk_bf16_f32 v163, v192, v193
	v_mul_f32_e64 v190, -v190, v226
	v_mul_f32_e64 v191, -v191, v227
	v_mul_f32_e64 v192, -v192, v228
	v_mul_f32_e64 v193, -v193, v229
	global_load_dwordx4 v[226:229], v183, s[38:39] offset:0
	v_cvt_pk_bf16_f32 v170, v190, v191
	v_cvt_pk_bf16_f32 v171, v192, v193
	s_waitcnt vmcnt(35)
	v_cvt_pk_bf16_f32 v164, v194, v195
	v_cvt_pk_bf16_f32 v165, v196, v197
	v_mul_f32_e64 v194, -v194, v230
	v_mul_f32_e64 v195, -v195, v231
	v_mul_f32_e64 v196, -v196, v232
	v_mul_f32_e64 v197, -v197, v233
	global_load_dwordx4 v[230:233], v183, s[38:39] offset:64
	v_cvt_pk_bf16_f32 v172, v194, v195
	v_cvt_pk_bf16_f32 v173, v196, v197
	ds_write_b128 v184, v[162:165] offset:4096
	s_waitcnt vmcnt(35)
	v_mfma_f32_16x16x32_bf16 v[2:5], v[98:101], v[170:173], v[2:5]
	global_load_dwordx4 v[98:101], v182, s[24:25] offset:-4096
	s_waitcnt vmcnt(35)
	v_mfma_f32_16x16x32_bf16 v[6:9], v[106:109], v[170:173], v[6:9]
	global_load_dwordx4 v[106:109], v182, s[24:25] offset:-2048
	s_waitcnt vmcnt(35)
	v_mfma_f32_16x16x32_bf16 v[10:13], v[114:117], v[170:173], v[10:13]
	global_load_dwordx4 v[114:117], v182, s[24:25] offset:0
	s_waitcnt vmcnt(35)
	v_mfma_f32_16x16x32_bf16 v[14:17], v[122:125], v[170:173], v[14:17]
	global_load_dwordx4 v[122:125], v182, s[24:25] offset:2048
	s_waitcnt vmcnt(35)
	v_cvt_pk_bf16_f32 v166, v198, v199
	v_cvt_pk_bf16_f32 v167, v200, v201
	v_mul_f32_e64 v198, -v198, v234
	v_mul_f32_e64 v199, -v199, v235
	v_mul_f32_e64 v200, -v200, v236
	v_mul_f32_e64 v201, -v201, v237
	global_load_dwordx4 v[234:237], v183, s[38:39] offset:128
	v_cvt_pk_bf16_f32 v174, v198, v199
	v_cvt_pk_bf16_f32 v175, v200, v201
	s_waitcnt vmcnt(35)
	v_cvt_pk_bf16_f32 v168, v202, v203
	v_cvt_pk_bf16_f32 v169, v204, v205
	v_mul_f32_e64 v202, -v202, v238
	v_mul_f32_e64 v203, -v203, v239
	v_mul_f32_e64 v204, -v204, v240
	v_mul_f32_e64 v205, -v205, v241
	global_load_dwordx4 v[238:241], v183, s[38:39] offset:192
	v_cvt_pk_bf16_f32 v176, v202, v203
	v_cvt_pk_bf16_f32 v177, v204, v205
	ds_write_b128 v184, v[166:169] offset:5120
	s_waitcnt vmcnt(35)
	v_mfma_f32_16x16x32_bf16 v[18:21], v[130:133], v[170:173], v[18:21]
	global_load_dwordx4 v[130:133], v182, s[36:37] offset:-4096
	s_waitcnt vmcnt(35)
	v_mfma_f32_16x16x32_bf16 v[22:25], v[138:141], v[170:173], v[22:25]
	global_load_dwordx4 v[138:141], v182, s[36:37] offset:-2048
	s_waitcnt vmcnt(35)
	v_mfma_f32_16x16x32_bf16 v[26:29], v[146:149], v[170:173], v[26:29]
	global_load_dwordx4 v[146:149], v182, s[36:37] offset:0
	s_waitcnt vmcnt(35)
	v_mfma_f32_16x16x32_bf16 v[30:33], v[154:157], v[170:173], v[30:33]
	global_load_dwordx4 v[154:157], v182, s[36:37] offset:2048
	s_waitcnt lgkmcnt(0)
	s_barrier
; #define MFMA16(a, b, c) __builtin_amdgcn_mfma_f32_16x16x32_bf16((a), (b), (c), 0, 0, 0)
; DEVI void scan_item(const Params& p, int h, int sl, char* smem) {
;     ...
;     lstore();
;     if (is_state) {
; #pragma unroll
;       for (int s = 0; s < 4; ++s) *(bf16x8*)(sbx + ((cw * 4 + s) * 64 + lane) * 16) = pack8(S[2 * s], S[2 * s + 1]);
;     }
;     __syncthreads();
;     lstore2();
;     if (n + 1 < NCH) gload(n + 1);
;     if (is_state) {
;       bf16x8 sb[4];
; #pragma unroll
;       for (int s = 0; s < 4; ++s) sb[s] = pack8(S[2 * s], S[2 * s + 1]);
;       f32x4 vnew[4];
; #pragma unroll
;       for (int mt = 0; mt < 4; ++mt) vnew[mt] = f32x4{0.f, 0.f, 0.f, 0.f};
; #pragma unroll
;       for (int s = 0; s < 4; ++s) {
; #pragma unroll
;         for (int mt = 0; mt < 4; ++mt) {
;           const char* aw = wsm + (mt * 16 + l15) * 272 + s * 64 + quad * 8;
;           bf16x8 wf = mk8(*(const u32x2*)aw, *(const u32x2*)(aw + 32));
;           vnew[mt] = MFMA16(wf, sb[s], vnew[mt]);
;     ...
;       for (int s2 = 0; s2 < 2; ++s2) {
; #pragma unroll
;         for (int r = 0; r < 8; ++r) {
;           const char* ap = ktsm + (r * 16 + l15) * 144 + s2 * 64 + quad * 8;
;           bf16x8 f = mk8(*(const u32x2*)ap, *(const u32x2*)(ap + 32));
;           S[r] = MFMA16(f, vb[s2], S[r]);
;         }
;       }
	ds_read_b128 v[190:193], v185 offset:4096
	ds_read_b128 v[194:197], v185 offset:5120
	ds_read_b128 v[198:201], v185 offset:6144
	ds_read_b128 v[202:205], v185 offset:7168
	s_waitcnt vmcnt(35)
	v_mfma_f32_16x16x32_bf16 v[2:5], v[102:105], v[174:177], v[2:5]
	global_load_dwordx4 v[102:105], v182, s[24:25] offset:-3072
	s_waitcnt vmcnt(35)
	v_mfma_f32_16x16x32_bf16 v[6:9], v[110:113], v[174:177], v[6:9]
	global_load_dwordx4 v[110:113], v182, s[24:25] offset:-1024
	s_waitcnt vmcnt(35)
	v_mfma_f32_16x16x32_bf16 v[10:13], v[118:121], v[174:177], v[10:13]
	global_load_dwordx4 v[118:121], v182, s[24:25] offset:1024
	s_waitcnt vmcnt(35)
	v_mfma_f32_16x16x32_bf16 v[14:17], v[126:129], v[174:177], v[14:17]
	global_load_dwordx4 v[126:129], v182, s[24:25] offset:3072
	s_waitcnt vmcnt(35)
	v_mfma_f32_16x16x32_bf16 v[18:21], v[134:137], v[174:177], v[18:21]
	global_load_dwordx4 v[134:137], v182, s[36:37] offset:-3072
	s_waitcnt vmcnt(35)
	v_mfma_f32_16x16x32_bf16 v[22:25], v[142:145], v[174:177], v[22:25]
	global_load_dwordx4 v[142:145], v182, s[36:37] offset:-1024
	s_waitcnt vmcnt(35)
	v_mfma_f32_16x16x32_bf16 v[26:29], v[150:153], v[174:177], v[26:29]
	global_load_dwordx4 v[150:153], v182, s[36:37] offset:1024
	s_waitcnt vmcnt(35)
	v_mfma_f32_16x16x32_bf16 v[30:33], v[158:161], v[174:177], v[30:33]
	global_load_dwordx4 v[158:161], v182, s[36:37] offset:3072
	s_branch .Lsc_st_join
.Lsc_st_odd:
	s_add_u32 s0, s0, 0x60000
	s_addc_u32 s1, s1, 0
	s_add_u32 s6, s6, 0x60000
	s_addc_u32 s7, s7, 0
	s_add_u32 s10, s10, 0x60000
	s_addc_u32 s11, s11, 0
	s_add_u32 s16, s16, 0x60000
	s_addc_u32 s17, s17, 0
	s_add_u32 s24, s24, 0x20000
	s_addc_u32 s25, s25, 0
	s_add_u32 s36, s36, 0x20000
	s_addc_u32 s37, s37, 0
	s_add_u32 s38, s38, 0x1800
	s_addc_u32 s39, s39, 0
	v_cvt_pk_bf16_f32 v162, v2, v3
	v_cvt_pk_bf16_f32 v163, v4, v5
	v_cvt_pk_bf16_f32 v164, v6, v7
	v_cvt_pk_bf16_f32 v165, v8, v9
	ds_write_b128 v184, v[162:165] offset:6144
	v_cvt_pk_bf16_f32 v166, v10, v11
	v_cvt_pk_bf16_f32 v167, v12, v13
	v_cvt_pk_bf16_f32 v168, v14, v15
	v_cvt_pk_bf16_f32 v169, v16, v17
	ds_write_b128 v184, v[166:169] offset:7168
	v_cvt_pk_bf16_f32 v170, v18, v19
	v_cvt_pk_bf16_f32 v171, v20, v21
	v_cvt_pk_bf16_f32 v172, v22, v23
	v_cvt_pk_bf16_f32 v173, v24, v25
	ds_write_b128 v184, v[170:173] offset:8192
	v_cvt_pk_bf16_f32 v174, v26, v27
	v_cvt_pk_bf16_f32 v175, v28, v29
	v_cvt_pk_bf16_f32 v176, v30, v31
	v_cvt_pk_bf16_f32 v177, v32, v33
	ds_write_b128 v184, v[174:177] offset:9216
	s_waitcnt vmcnt(35) lgkmcnt(4)
	v_mfma_f32_16x16x32_bf16 v[190:193], v[34:37], v[162:165], v[190:193]
	global_load_dwordx4 v[34:37], v178, s[0:1]
	v_mul_f32_e32 v2, s62, v2
	v_mul_f32_e32 v3, s62, v3
	s_waitcnt vmcnt(35)
	v_mfma_f32_16x16x32_bf16 v[194:197], v[50:53], v[162:165], v[194:197]
	global_load_dwordx4 v[50:53], v178, s[6:7]
	v_mul_f32_e32 v4, s62, v4
	v_mul_f32_e32 v5, s62, v5
	s_waitcnt vmcnt(35)
	v_mfma_f32_16x16x32_bf16 v[190:193], v[38:41], v[166:169], v[190:193]
	global_load_dwordx4 v[38:41], v179, s[0:1]
	v_mul_f32_e32 v6, s62, v6
	v_mul_f32_e32 v7, s62, v7
	s_waitcnt vmcnt(35)
	v_mfma_f32_16x16x32_bf16 v[194:197], v[54:57], v[166:169], v[194:197]
	global_load_dwordx4 v[54:57], v179, s[6:7]
	v_mul_f32_e32 v8, s62, v8
	v_mul_f32_e32 v9, s62, v9
	s_waitcnt vmcnt(35)
	v_mfma_f32_16x16x32_bf16 v[190:193], v[42:45], v[170:173], v[190:193]
	global_load_dwordx4 v[42:45], v180, s[0:1]
	v_mul_f32_e32 v10, s62, v10
	v_mul_f32_e32 v11, s62, v11
	s_waitcnt vmcnt(35)
	v_mfma_f32_16x16x32_bf16 v[194:197], v[58:61], v[170:173], v[194:197]
	global_load_dwordx4 v[58:61], v180, s[6:7]
	v_mul_f32_e32 v12, s62, v12
	v_mul_f32_e32 v13, s62, v13
	s_waitcnt vmcnt(35)
	v_mfma_f32_16x16x32_bf16 v[198:201], v[66:69], v[162:165], v[198:201]
	global_load_dwordx4 v[66:69], v178, s[10:11]
	v_mul_f32_e32 v14, s62, v14
	v_mul_f32_e32 v15, s62, v15
	s_waitcnt vmcnt(35)
	v_mfma_f32_16x16x32_bf16 v[202:205], v[82:85], v[162:165], v[202:205]
	global_load_dwordx4 v[82:85], v178, s[16:17]
	v_mul_f32_e32 v16, s62, v16
	v_mul_f32_e32 v17, s62, v17
	s_waitcnt vmcnt(35)
	v_mfma_f32_16x16x32_bf16 v[198:201], v[70:73], v[166:169], v[198:201]
	global_load_dwordx4 v[70:73], v179, s[10:11]
	v_mul_f32_e32 v18, s62, v18
	v_mul_f32_e32 v19, s62, v19
	s_waitcnt vmcnt(35)
	v_mfma_f32_16x16x32_bf16 v[202:205], v[86:89], v[166:169], v[202:205]
	global_load_dwordx4 v[86:89], v179, s[16:17]
	v_mul_f32_e32 v20, s62, v20
	v_mul_f32_e32 v21, s62, v21
	s_waitcnt vmcnt(35)
	v_mfma_f32_16x16x32_bf16 v[198:201], v[74:77], v[170:173], v[198:201]
	global_load_dwordx4 v[74:77], v180, s[10:11]
	v_mul_f32_e32 v22, s62, v22
	v_mul_f32_e32 v23, s62, v23
	s_waitcnt vmcnt(35)
	v_mfma_f32_16x16x32_bf16 v[202:205], v[90:93], v[170:173], v[202:205]
	global_load_dwordx4 v[90:93], v180, s[16:17]
	v_mul_f32_e32 v24, s62, v24
	v_mul_f32_e32 v25, s62, v25
	s_waitcnt vmcnt(35)
; DEVI float bf2f(bf16_t b) { return __uint_as_float(((unsigned)b) << 16); }
; #define MFMA16(a, b, c) __builtin_amdgcn_mfma_f32_16x16x32_bf16((a), (b), (c), 0, 0, 0)
; DEVI void scan_item(const Params& p, int h, int sl, char* smem) {
;     ...
;       for (int s = 0; s < 4; ++s) {
; #pragma unroll
;         for (int mt = 0; mt < 4; ++mt) {
;           const char* aw = wsm + (mt * 16 + l15) * 272 + s * 64 + quad * 8;
;           bf16x8 wf = mk8(*(const u32x2*)aw, *(const u32x2*)(aw + 32));
;           vnew[mt] = MFMA16(wf, sb[s], vnew[mt]);
;         }
;       }
; #pragma unroll
;       for (int mt = 0; mt < 4; ++mt) {
; #pragma unroll
;         for (int jj = 0; jj < 4; ++jj) {
;           const int cidx = mt * 16 + quad * 4 + jj;
;           const float u = bf2f(*(const unsigned short*)(usm + cidx * USTR + (cw * 16 + l15) * 2));
;           vnew[mt][jj] = u - vnew[mt][jj];
;         }
;       }
; #pragma unroll
;       for (int s2 = 0; s2 < 2; ++s2)
;         *(bf16x8*)(vbx + ((cw * 2 + s2) * 64 + lane) * 16) = pack8(vnew[2 * s2], vnew[2 * s2 + 1]);
;       __syncthreads();
;       const float eglast = gsm[128];
;       bf16x8 vb[2];
; #pragma unroll
;       for (int mt = 0; mt < 4; ++mt) {
;         const f32x4 gd4 = *(const f32x4*)(gsm + 64 + mt * 16 + quad * 4);
;         vnew[mt] = vnew[mt] * gd4;
;       }
; #pragma unroll
;       for (int s2 = 0; s2 < 2; ++s2) vb[s2] = pack8(vnew[2 * s2], vnew[2 * s2 + 1]);
; #pragma unroll
;       for (int r = 0; r < 8; ++r) S[r] = S[r] * eglast;
; #pragma unroll
;       for (int s2 = 0; s2 < 2; ++s2) {
; #pragma unroll
;         for (int r = 0; r < 8; ++r) {
;           const char* ap = ktsm + (r * 16 + l15) * 144 + s2 * 64 + quad * 8;
;           bf16x8 f = mk8(*(const u32x2*)ap, *(const u32x2*)(ap + 32));
;           S[r] = MFMA16(f, vb[s2], S[r]);
;         }
;       }
	v_mfma_f32_16x16x32_bf16 v[190:193], v[46:49], v[174:177], v[190:193]
	global_load_dwordx4 v[46:49], v181, s[0:1]
	v_mul_f32_e32 v26, s62, v26
	v_mul_f32_e32 v27, s62, v27
	s_waitcnt vmcnt(35)
	v_mfma_f32_16x16x32_bf16 v[194:197], v[62:65], v[174:177], v[194:197]
	global_load_dwordx4 v[62:65], v181, s[6:7]
	v_mul_f32_e32 v28, s62, v28
	v_mul_f32_e32 v29, s62, v29
	s_waitcnt vmcnt(35)
	v_mfma_f32_16x16x32_bf16 v[198:201], v[78:81], v[174:177], v[198:201]
	global_load_dwordx4 v[78:81], v181, s[10:11]
	v_mul_f32_e32 v30, s62, v30
	v_mul_f32_e32 v31, s62, v31
	s_waitcnt vmcnt(35)
	v_mfma_f32_16x16x32_bf16 v[202:205], v[94:97], v[174:177], v[202:205]
	global_load_dwordx4 v[94:97], v181, s[16:17]
	v_mul_f32_e32 v32, s62, v32
	v_mul_f32_e32 v33, s62, v33
	s_load_dword s62, s[38:39], 0x1a00
	s_waitcnt vmcnt(35)
	v_cvt_pk_bf16_f32 v162, v190, v191
	v_cvt_pk_bf16_f32 v163, v192, v193
	v_mul_f32_e64 v190, -v190, v226
	v_mul_f32_e64 v191, -v191, v227
	v_mul_f32_e64 v192, -v192, v228
	v_mul_f32_e64 v193, -v193, v229
	global_load_dwordx4 v[226:229], v183, s[38:39] offset:0
	v_cvt_pk_bf16_f32 v170, v190, v191
	v_cvt_pk_bf16_f32 v171, v192, v193
	s_waitcnt vmcnt(35)
	v_cvt_pk_bf16_f32 v164, v194, v195
	v_cvt_pk_bf16_f32 v165, v196, v197
	v_mul_f32_e64 v194, -v194, v230
	v_mul_f32_e64 v195, -v195, v231
	v_mul_f32_e64 v196, -v196, v232
	v_mul_f32_e64 v197, -v197, v233
	global_load_dwordx4 v[230:233], v183, s[38:39] offset:64
	v_cvt_pk_bf16_f32 v172, v194, v195
	v_cvt_pk_bf16_f32 v173, v196, v197
	ds_write_b128 v184, v[162:165] offset:10240
	s_waitcnt vmcnt(35)
	v_mfma_f32_16x16x32_bf16 v[2:5], v[98:101], v[170:173], v[2:5]
	global_load_dwordx4 v[98:101], v182, s[24:25] offset:-4096
	s_waitcnt vmcnt(35)
	v_mfma_f32_16x16x32_bf16 v[6:9], v[106:109], v[170:173], v[6:9]
	global_load_dwordx4 v[106:109], v182, s[24:25] offset:-2048
	s_waitcnt vmcnt(35)
	v_mfma_f32_16x16x32_bf16 v[10:13], v[114:117], v[170:173], v[10:13]
	global_load_dwordx4 v[114:117], v182, s[24:25] offset:0
	s_waitcnt vmcnt(35)
	v_mfma_f32_16x16x32_bf16 v[14:17], v[122:125], v[170:173], v[14:17]
	global_load_dwordx4 v[122:125], v182, s[24:25] offset:2048
	s_waitcnt vmcnt(35)
	v_cvt_pk_bf16_f32 v166, v198, v199
	v_cvt_pk_bf16_f32 v167, v200, v201
	v_mul_f32_e64 v198, -v198, v234
	v_mul_f32_e64 v199, -v199, v235
	v_mul_f32_e64 v200, -v200, v236
	v_mul_f32_e64 v201, -v201, v237
	global_load_dwordx4 v[234:237], v183, s[38:39] offset:128
	v_cvt_pk_bf16_f32 v174, v198, v199
	v_cvt_pk_bf16_f32 v175, v200, v201
	s_waitcnt vmcnt(35)
	v_cvt_pk_bf16_f32 v168, v202, v203
	v_cvt_pk_bf16_f32 v169, v204, v205
	v_mul_f32_e64 v202, -v202, v238
	v_mul_f32_e64 v203, -v203, v239
	v_mul_f32_e64 v204, -v204, v240
	v_mul_f32_e64 v205, -v205, v241
	global_load_dwordx4 v[238:241], v183, s[38:39] offset:192
	v_cvt_pk_bf16_f32 v176, v202, v203
	v_cvt_pk_bf16_f32 v177, v204, v205
	ds_write_b128 v184, v[166:169] offset:11264
	s_waitcnt vmcnt(35)
	v_mfma_f32_16x16x32_bf16 v[18:21], v[130:133], v[170:173], v[18:21]
	global_load_dwordx4 v[130:133], v182, s[36:37] offset:-4096
	s_waitcnt vmcnt(35)
	v_mfma_f32_16x16x32_bf16 v[22:25], v[138:141], v[170:173], v[22:25]
	global_load_dwordx4 v[138:141], v182, s[36:37] offset:-2048
	s_waitcnt vmcnt(35)
	v_mfma_f32_16x16x32_bf16 v[26:29], v[146:149], v[170:173], v[26:29]
	global_load_dwordx4 v[146:149], v182, s[36:37] offset:0
	s_waitcnt vmcnt(35)
	v_mfma_f32_16x16x32_bf16 v[30:33], v[154:157], v[170:173], v[30:33]
	global_load_dwordx4 v[154:157], v182, s[36:37] offset:2048
	s_waitcnt lgkmcnt(0)
	s_barrier
	ds_read_b128 v[190:193], v185 offset:0
	ds_read_b128 v[194:197], v185 offset:1024
	ds_read_b128 v[198:201], v185 offset:2048
	ds_read_b128 v[202:205], v185 offset:3072
	s_waitcnt vmcnt(35)
	v_mfma_f32_16x16x32_bf16 v[2:5], v[102:105], v[174:177], v[2:5]
	global_load_dwordx4 v[102:105], v182, s[24:25] offset:-3072
	s_waitcnt vmcnt(35)
	v_mfma_f32_16x16x32_bf16 v[6:9], v[110:113], v[174:177], v[6:9]
	global_load_dwordx4 v[110:113], v182, s[24:25] offset:-1024
	s_waitcnt vmcnt(35)
	v_mfma_f32_16x16x32_bf16 v[10:13], v[118:121], v[174:177], v[10:13]
	global_load_dwordx4 v[118:121], v182, s[24:25] offset:1024
	s_waitcnt vmcnt(35)
	v_mfma_f32_16x16x32_bf16 v[14:17], v[126:129], v[174:177], v[14:17]
	global_load_dwordx4 v[126:129], v182, s[24:25] offset:3072
	s_waitcnt vmcnt(35)
	v_mfma_f32_16x16x32_bf16 v[18:21], v[134:137], v[174:177], v[18:21]
	global_load_dwordx4 v[134:137], v182, s[36:37] offset:-3072
	s_waitcnt vmcnt(35)
	v_mfma_f32_16x16x32_bf16 v[22:25], v[142:145], v[174:177], v[22:25]
	global_load_dwordx4 v[142:145], v182, s[36:37] offset:-1024
	s_waitcnt vmcnt(35)
	v_mfma_f32_16x16x32_bf16 v[26:29], v[150:153], v[174:177], v[26:29]
	global_load_dwordx4 v[150:153], v182, s[36:37] offset:1024
	s_waitcnt vmcnt(35)
	v_mfma_f32_16x16x32_bf16 v[30:33], v[158:161], v[174:177], v[30:33]
	global_load_dwordx4 v[158:161], v182, s[36:37] offset:3072
.Lsc_st_join:
	s_add_u32 s18, s18, 1
	s_cmp_lt_u32 s18, 257
	s_cbranch_scc1 .Lsc_st_loop
	s_setprio 0

; DEVI float bf2f(bf16_t b) { return __uint_as_float(((unsigned)b) << 16); }
; DEVI void prep_item(const Params& p, int j, int n, int h, char* smem) {
;     ...
;   {
;     bf16_t* kt = r0 + R0_KT + (size_t)(n * 8 + h) * 8192;
; #pragma unroll
;     for (int i = 0; i < 4; ++i) {
;       const int unit = tid + i * 256, d = unit >> 3, i0 = (unit & 7) * 8;
;       unsigned e[8];
; #pragma unroll
;       for (int q = 0; q < 8; ++q) e[q] = *(const unsigned short*)(ks + (i0 + q) * 272 + d * 2);
;       u32x4 o = {e[0] | (e[1] << 16), e[2] | (e[3] << 16), e[4] | (e[5] << 16), e[6] | (e[7] << 16)};
;       *(u32x4*)(kt + d * 64 + i0) = o;
;     }
;   }
;   {
;     const int c = tid;
;     const bool isu = c < 128;
;     const char* src = isu ? (vs + c * 2) : (ks + (c - 128) * 2);
;     float x[64];
; #pragma unroll
;     for (int i = 0; i < 64; ++i) x[i] = 0.f;
;     int zero;
;     asm volatile("v_mov_b32 %0, 0" : "=v"(zero));
; #pragma unroll
;     for (int i = 0; i < 64; ++i) {
;       const float* amz = am + zero;
;       const float* sbz = sbeta + zero;
;       const float eg = __expf(sbz[64 + i]);
;       float acc = bf2f(*(const unsigned short*)(src + i * 272)) * sbz[i] * (isu ? 1.0f : eg);
; #pragma unroll
;       for (int j4 = 0; j4 < (i + 3) / 4; ++j4) {
;         const f32x4 a = *(const f32x4*)(amz + i * 68 + j4 * 4);
;         acc -= a[0] * x[j4 * 4 + 0];
;         acc -= a[1] * x[j4 * 4 + 1];
;         acc -= a[2] * x[j4 * 4 + 2];
;         acc -= a[3] * x[j4 * 4 + 3];
;       }
;       asm volatile("" : "+v"(zero), "+v"(acc));
;       x[i] = acc;
;     }
.LBB0_1293:
	s_or_b64 exec, exec, s[0:1]
	v_mul_f32_e32 v2, v5, v2
	v_cvt_pk_bf16_f32 v2, v2, s0
	v_cmp_le_i32_e32 vcc, v0, v53
	v_and_b32_e32 v4, 56, v41
	v_ashrrev_i32_e32 v8, 3, v34
	v_cndmask_b32_e32 v0, 0, v2, vcc
	global_store_short v[20:21], v0, off offset:72
	v_lshlrev_b32_e32 v0, 5, v4
	v_and_b32_e32 v85, 24, v4
	v_and_b32_e32 v10, 32, v4
	v_lshrrev_b32_e32 v85, 1, v85
	v_or_b32_e32 v10, v10, v85
	v_mul_u32_u24_e32 v10, 0x110, v10
	v_lshlrev_b32_e32 v4, 1, v8
	v_add3_u32 v4, 32, v4, v10
	ds_write_b32 v45, v3 offset:53232
	s_waitcnt lgkmcnt(0)
	s_barrier
	v_lshlrev_b64 v[2:3], 14, v[36:37]
	ds_read_u16 v5, v4 offset:17408
	ds_read_u16 v9, v4 offset:17680
	ds_read_u16 v11, v4 offset:17952
	ds_read_u16 v12, v4 offset:18224
	ds_read_u16 v13, v4 offset:21760
	ds_read_u16 v14, v4 offset:22032
	ds_read_u16 v15, v4 offset:22304
	ds_read_u16 v16, v4 offset:22576
	v_lshl_add_u64 v[2:3], s[30:31], 0, v[2:3]
	v_lshl_add_u64 v[6:7], v[2:3], 0, v[0:1]
	v_ashrrev_i32_e32 v0, 3, v40
	s_waitcnt lgkmcnt(4)
	v_lshl_or_b32 v3, v12, 16, v11
	v_lshlrev_b32_e32 v11, 1, v0
	v_add3_u32 v11, 32, v11, v10
	v_lshl_or_b32 v2, v9, 16, v5
	s_waitcnt lgkmcnt(2)
	v_lshl_or_b32 v4, v14, 16, v13
	s_waitcnt lgkmcnt(0)
	v_lshl_or_b32 v5, v16, 16, v15
	ds_read_u16 v12, v11 offset:17408
	ds_read_u16 v13, v11 offset:17680
	ds_read_u16 v14, v11 offset:17952
	ds_read_u16 v15, v11 offset:18224
	ds_read_u16 v16, v11 offset:21760
	ds_read_u16 v17, v11 offset:22032
	ds_read_u16 v18, v11 offset:22304
	ds_read_u16 v11, v11 offset:22576
	v_and_b32_e32 v85, 15, v8
	v_lshrrev_b32_e32 v8, 4, v8
	v_lshlrev_b32_e32 v8, 10, v8
	v_lshl_or_b32 v8, v85, 3, v8
	v_ashrrev_i32_e32 v9, 31, v8
	v_lshl_add_u64 v[8:9], v[8:9], 1, v[6:7]
	global_store_dwordx4 v[8:9], v[2:5], off
	v_and_b32_e32 v85, 15, v0
	v_lshrrev_b32_e32 v8, 4, v0
	v_lshlrev_b32_e32 v8, 10, v8
	v_lshl_or_b32 v8, v85, 3, v8
	v_ashrrev_i32_e32 v0, 3, v42
	s_waitcnt lgkmcnt(0)
	v_lshl_or_b32 v5, v11, 16, v18
	v_lshlrev_b32_e32 v11, 1, v0
	v_add3_u32 v11, 32, v11, v10
	v_lshl_or_b32 v2, v13, 16, v12
	v_lshl_or_b32 v3, v15, 16, v14
	v_lshl_or_b32 v4, v17, 16, v16
	ds_read_u16 v12, v11 offset:17408
	ds_read_u16 v13, v11 offset:17680
	ds_read_u16 v14, v11 offset:17952
	ds_read_u16 v15, v11 offset:18224
	ds_read_u16 v16, v11 offset:21760
	ds_read_u16 v17, v11 offset:22032
	ds_read_u16 v18, v11 offset:22304
	ds_read_u16 v11, v11 offset:22576
	v_ashrrev_i32_e32 v9, 31, v8
	v_lshl_add_u64 v[8:9], v[8:9], 1, v[6:7]
	global_store_dwordx4 v[8:9], v[2:5], off
	v_and_b32_e32 v85, 15, v0
	v_lshrrev_b32_e32 v8, 4, v0
	v_lshlrev_b32_e32 v8, 10, v8
	v_lshl_or_b32 v8, v85, 3, v8
	v_ashrrev_i32_e32 v0, 3, v43
	s_waitcnt lgkmcnt(0)
	v_lshl_or_b32 v5, v11, 16, v18
	v_lshlrev_b32_e32 v11, 1, v0
	v_add3_u32 v10, 32, v11, v10
	v_lshl_or_b32 v2, v13, 16, v12
	v_lshl_or_b32 v3, v15, 16, v14
	v_lshl_or_b32 v4, v17, 16, v16
	ds_read_u16 v11, v10 offset:17408
	ds_read_u16 v12, v10 offset:17680
	ds_read_u16 v13, v10 offset:17952
	ds_read_u16 v14, v10 offset:18224
	ds_read_u16 v15, v10 offset:21760
	ds_read_u16 v16, v10 offset:22032
	ds_read_u16 v17, v10 offset:22304
	ds_read_u16 v10, v10 offset:22576
	v_ashrrev_i32_e32 v9, 31, v8
	v_lshl_add_u64 v[8:9], v[8:9], 1, v[6:7]
	global_store_dwordx4 v[8:9], v[2:5], off
	v_and_b32_e32 v85, 15, v0
	v_lshrrev_b32_e32 v8, 4, v0
	v_lshlrev_b32_e32 v8, 10, v8
	v_lshl_or_b32 v8, v85, 3, v8
	v_ashrrev_i32_e32 v9, 31, v8
	s_waitcnt lgkmcnt(6)
	v_lshl_or_b32 v2, v12, 16, v11
	s_waitcnt lgkmcnt(4)
	v_lshl_or_b32 v3, v14, 16, v13
	s_waitcnt lgkmcnt(2)
	v_lshl_or_b32 v4, v16, 16, v15
	s_waitcnt lgkmcnt(0)
	v_lshl_or_b32 v5, v10, 16, v17
	v_lshl_add_u64 v[6:7], v[8:9], 1, v[6:7]
	s_add_i32 s0, 32, 0x11000
	global_store_dwordx4 v[6:7], v[2:5], off
	v_mov_b32 v0, 0
	v_cmp_gt_i32_e32 vcc, s49, v34
	s_lshl_b32 s62, s7, 1
	v_lshl_add_u32 v3, v0, 2, s0
	ds_read2st64_b32 v[4:5], v3 offset1:1
	v_lshl_add_u32 v2, v34, 1, 32
	v_add_u32_e32 v3, 0x4300, v2
	v_add_u32_e32 v2, 0x8800, v2
	v_cndmask_b32_e32 v2, v3, v2, vcc
	s_waitcnt lgkmcnt(0)
	v_mul_f32_e32 v3, 0x3fb8aa3b, v5
	ds_read_u16 v5, v2
	v_exp_f32_e32 v3, v3
	s_cmp_lt_i32 s44, 1
	s_waitcnt lgkmcnt(0)
	v_lshlrev_b32_e32 v5, 16, v5
	v_cndmask_b32_e64 v3, v3, 1.0, vcc
	v_mul_f32_e32 v4, v4, v5
	v_mul_f32_e32 v4, v3, v4
	s_nop 0
	v_lshlrev_b32_e32 v3, 2, v0
	v_add_u32_e32 v5, s0, v3
	ds_read2_b32 v[10:11], v5 offset0:1 offset1:65
	v_add_u32_e32 v3, 32, v3
	ds_read_b128 v[6:9], v3 offset:52496
	s_waitcnt lgkmcnt(1)
	v_mul_f32_e32 v5, 0x3fb8aa3b, v11
	ds_read_u16 v11, v2 offset:272
	v_exp_f32_e32 v5, v5
	s_waitcnt lgkmcnt(1)
	v_mul_f32_e32 v6, v4, v6
	v_cndmask_b32_e64 v3, v5, 1.0, vcc
	s_waitcnt lgkmcnt(0)
	v_lshlrev_b32_e32 v5, 16, v11
	v_mul_f32_e32 v5, v10, v5
	v_fma_f32 v5, v3, v5, -v6
	v_fmac_f32_e32 v5, 0x80000000, v7
	v_fmac_f32_e32 v5, 0x80000000, v8
	v_fmac_f32_e32 v5, 0x80000000, v9
	ds_read_u16 v12, v2 offset:544
	v_lshlrev_b32_e32 v3, 2, v0
	v_add_u32_e32 v6, s0, v3
	ds_read2_b32 v[10:11], v6 offset0:2 offset1:66
	v_add_u32_e32 v3, 32, v3
	s_waitcnt lgkmcnt(0)
	v_mul_f32_e32 v6, 0x3fb8aa3b, v11
	v_exp_f32_e32 v11, v6
	ds_read_b128 v[6:9], v3 offset:52768
	v_cndmask_b32_e64 v3, v11, 1.0, vcc
	v_lshlrev_b32_e32 v11, 16, v12
	v_mul_f32_e32 v10, v10, v11
	s_waitcnt lgkmcnt(0)
	v_mul_f32_e32 v6, v4, v6
	v_fma_f32 v3, v3, v10, -v6
	v_fma_f32 v6, -v5, v7, v3
	v_fmac_f32_e32 v6, 0x80000000, v8
	v_fmac_f32_e32 v6, 0x80000000, v9
	s_nop 0
	v_lshlrev_b32_e32 v3, 2, v0
	v_add_u32_e32 v7, s0, v3
	ds_read2_b32 v[12:13], v7 offset0:3 offset1:67
	v_add_u32_e32 v3, 32, v3
	ds_read_b128 v[8:11], v3 offset:53040
	s_waitcnt lgkmcnt(1)
	v_mul_f32_e32 v7, 0x3fb8aa3b, v13
	ds_read_u16 v13, v2 offset:816
	v_exp_f32_e32 v7, v7
	s_waitcnt lgkmcnt(1)
; DEVI float bf2f(bf16_t b) { return __uint_as_float(((unsigned)b) << 16); }
; DEVI void prep_item(const Params& p, int j, int n, int h, char* smem) {
;     ...
; #pragma unroll
;     for (int i = 0; i < 64; ++i) {
;       const float* amz = am + zero;
;       const float* sbz = sbeta + zero;
;       const float eg = __expf(sbz[64 + i]);
;       float acc = bf2f(*(const unsigned short*)(src + i * 272)) * sbz[i] * (isu ? 1.0f : eg);
; #pragma unroll
;       for (int j4 = 0; j4 < (i + 3) / 4; ++j4) {
;         const f32x4 a = *(const f32x4*)(amz + i * 68 + j4 * 4);
;         acc -= a[0] * x[j4 * 4 + 0];
;         acc -= a[1] * x[j4 * 4 + 1];
;         acc -= a[2] * x[j4 * 4 + 2];
;         acc -= a[3] * x[j4 * 4 + 3];
;       }
;       asm volatile("" : "+v"(zero), "+v"(acc));
;       x[i] = acc;
;     }
	v_mul_f32_e32 v8, v4, v8
	v_cndmask_b32_e64 v3, v7, 1.0, vcc
	s_waitcnt lgkmcnt(0)
	v_lshlrev_b32_e32 v7, 16, v13
	v_mul_f32_e32 v7, v12, v7
	v_fma_f32 v3, v3, v7, -v8
	v_fma_f32 v3, -v5, v9, v3
	v_fma_f32 v7, -v6, v10, v3
	v_fmac_f32_e32 v7, 0x80000000, v11
	ds_read_u16 v14, v2 offset:1088
	v_lshlrev_b32_e32 v3, 2, v0
	v_add_u32_e32 v8, s0, v3
	ds_read2_b32 v[12:13], v8 offset0:4 offset1:68
	v_add_u32_e32 v3, 32, v3
	s_waitcnt lgkmcnt(0)
	v_mul_f32_e32 v8, 0x3fb8aa3b, v13
	v_exp_f32_e32 v13, v8
	ds_read_b128 v[8:11], v3 offset:53312
	v_cndmask_b32_e64 v3, v13, 1.0, vcc
	v_lshlrev_b32_e32 v13, 16, v14
	v_mul_f32_e32 v12, v12, v13
	s_waitcnt lgkmcnt(0)
	v_mul_f32_e32 v8, v4, v8
	v_fma_f32 v3, v3, v12, -v8
	v_fma_f32 v3, -v5, v9, v3
	v_fma_f32 v3, -v6, v10, v3
	v_fma_f32 v8, -v7, v11, v3
	s_nop 0
	v_lshlrev_b32_e32 v3, 2, v0
	v_add_u32_e32 v9, s0, v3
	ds_read2_b32 v[14:15], v9 offset0:5 offset1:69
	v_add_u32_e32 v3, 32, v3
	ds_read_b128 v[10:13], v3 offset:53584
	s_waitcnt lgkmcnt(1)
	v_mul_f32_e32 v9, 0x3fb8aa3b, v15
	ds_read_u16 v15, v2 offset:1360
	v_exp_f32_e32 v9, v9
	s_waitcnt lgkmcnt(0)
	v_lshlrev_b32_e32 v15, 16, v15
	v_cndmask_b32_e64 v9, v9, 1.0, vcc
	v_mul_f32_e32 v18, v14, v15
	ds_read_b128 v[14:17], v3 offset:53600
	v_mul_f32_e32 v3, v4, v10
	v_fma_f32 v3, v9, v18, -v3
	v_fma_f32 v3, -v5, v11, v3
	v_fma_f32 v3, -v6, v12, v3
	v_fma_f32 v3, -v7, v13, v3
	s_waitcnt lgkmcnt(0)
	v_fma_f32 v9, -v8, v14, v3
	v_fmac_f32_e32 v9, 0x80000000, v15
	v_fmac_f32_e32 v9, 0x80000000, v16
	v_fmac_f32_e32 v9, 0x80000000, v17
	ds_read_u16 v16, v2 offset:1632
	v_lshlrev_b32_e32 v3, 2, v0
	v_add_u32_e32 v10, s0, v3
	ds_read2_b32 v[14:15], v10 offset0:6 offset1:70
	v_add_u32_e32 v3, 32, v3
	s_waitcnt lgkmcnt(0)
	v_mul_f32_e32 v10, 0x3fb8aa3b, v15
	v_exp_f32_e32 v15, v10
	ds_read_b128 v[10:13], v3 offset:53856
	v_cndmask_b32_e64 v18, v15, 1.0, vcc
	v_lshlrev_b32_e32 v15, 16, v16
	v_mul_f32_e32 v19, v14, v15
	ds_read_b128 v[14:17], v3 offset:53872
	s_waitcnt lgkmcnt(1)
	v_mul_f32_e32 v3, v4, v10
	v_fma_f32 v3, v18, v19, -v3
	v_fma_f32 v3, -v5, v11, v3
	v_fma_f32 v3, -v6, v12, v3
	v_fma_f32 v3, -v7, v13, v3
	s_waitcnt lgkmcnt(0)
	v_fma_f32 v3, -v8, v14, v3
	v_fma_f32 v10, -v9, v15, v3
	v_fmac_f32_e32 v10, 0x80000000, v16
	v_fmac_f32_e32 v10, 0x80000000, v17
	s_nop 0
	v_lshlrev_b32_e32 v3, 2, v0
	v_add_u32_e32 v11, s0, v3
	ds_read2_b32 v[16:17], v11 offset0:7 offset1:71
	v_add_u32_e32 v3, 32, v3
	ds_read_b128 v[12:15], v3 offset:54128
	s_waitcnt lgkmcnt(1)
	v_mul_f32_e32 v11, 0x3fb8aa3b, v17
	ds_read_u16 v17, v2 offset:1904
	v_exp_f32_e32 v11, v11
	s_waitcnt lgkmcnt(0)
	v_lshlrev_b32_e32 v17, 16, v17
	v_cndmask_b32_e64 v11, v11, 1.0, vcc
	v_mul_f32_e32 v20, v16, v17
	ds_read_b128 v[16:19], v3 offset:54144
	v_mul_f32_e32 v3, v4, v12
	v_fma_f32 v3, v11, v20, -v3
	v_fma_f32 v3, -v5, v13, v3
	v_fma_f32 v3, -v6, v14, v3
	v_fma_f32 v3, -v7, v15, v3
	s_waitcnt lgkmcnt(0)
	v_fma_f32 v3, -v8, v16, v3
	v_fma_f32 v3, -v9, v17, v3
	v_fma_f32 v11, -v10, v18, v3
	v_fmac_f32_e32 v11, 0x80000000, v19
	ds_read_u16 v18, v2 offset:2176
	v_lshlrev_b32_e32 v3, 2, v0
	v_add_u32_e32 v12, s0, v3
	ds_read2_b32 v[16:17], v12 offset0:8 offset1:72
	v_add_u32_e32 v3, 32, v3
	s_waitcnt lgkmcnt(0)
	v_mul_f32_e32 v12, 0x3fb8aa3b, v17
	v_exp_f32_e32 v17, v12
	ds_read_b128 v[12:15], v3 offset:54400
	v_cndmask_b32_e64 v20, v17, 1.0, vcc
	v_lshlrev_b32_e32 v17, 16, v18
	v_mul_f32_e32 v21, v16, v17
	ds_read_b128 v[16:19], v3 offset:54416
	s_waitcnt lgkmcnt(1)
	v_mul_f32_e32 v3, v4, v12
	v_fma_f32 v3, v20, v21, -v3
	v_fma_f32 v3, -v5, v13, v3
	v_fma_f32 v3, -v6, v14, v3
	v_fma_f32 v3, -v7, v15, v3
	s_waitcnt lgkmcnt(0)
	v_fma_f32 v3, -v8, v16, v3
	v_fma_f32 v3, -v9, v17, v3
	v_fma_f32 v3, -v10, v18, v3
	v_fma_f32 v12, -v11, v19, v3
	s_nop 0
	v_lshlrev_b32_e32 v3, 2, v0
	v_add_u32_e32 v13, s0, v3
	ds_read2_b32 v[18:19], v13 offset0:9 offset1:73
	v_add_u32_e32 v3, 32, v3
	ds_read_b128 v[14:17], v3 offset:54672
	s_waitcnt lgkmcnt(1)
	v_mul_f32_e32 v13, 0x3fb8aa3b, v19
	ds_read_u16 v19, v2 offset:2448
	v_exp_f32_e32 v13, v13
	s_waitcnt lgkmcnt(0)
	v_lshlrev_b32_e32 v19, 16, v19
	v_cndmask_b32_e64 v13, v13, 1.0, vcc
	v_mul_f32_e32 v26, v18, v19
	ds_read_b128 v[18:21], v3 offset:54688
	ds_read_b128 v[22:25], v3 offset:54704
	v_mul_f32_e32 v3, v4, v14
	v_fma_f32 v3, v13, v26, -v3
	v_fma_f32 v3, -v5, v15, v3
	v_fma_f32 v3, -v6, v16, v3
	v_fma_f32 v3, -v7, v17, v3
	s_waitcnt lgkmcnt(1)
	v_fma_f32 v3, -v8, v18, v3
	v_fma_f32 v3, -v9, v19, v3
	v_fma_f32 v3, -v10, v20, v3
	v_fma_f32 v3, -v11, v21, v3
	s_waitcnt lgkmcnt(0)
	v_fma_f32 v13, -v12, v22, v3
	v_fmac_f32_e32 v13, 0x80000000, v23
	v_fmac_f32_e32 v13, 0x80000000, v24
	v_fmac_f32_e32 v13, 0x80000000, v25
	s_nop 0
	v_lshlrev_b32_e32 v3, 2, v0
	v_add_u32_e32 v14, s0, v3
	ds_read2_b32 v[18:19], v14 offset0:10 offset1:74
	v_add_u32_e32 v3, 32, v3
	s_waitcnt lgkmcnt(0)
	v_mul_f32_e32 v14, 0x3fb8aa3b, v19
	v_exp_f32_e32 v14, v14
	ds_read_u16 v19, v2 offset:2720
	v_cndmask_b32_e64 v26, v14, 1.0, vcc
	ds_read_b128 v[14:17], v3 offset:54944
	s_waitcnt lgkmcnt(1)
	v_lshlrev_b32_e32 v19, 16, v19
	v_mul_f32_e32 v27, v18, v19
	ds_read_b128 v[18:21], v3 offset:54960
	ds_read_b128 v[22:25], v3 offset:54976
	s_waitcnt lgkmcnt(2)
	v_mul_f32_e32 v3, v4, v14
	v_fma_f32 v3, v26, v27, -v3
	v_fma_f32 v3, -v5, v15, v3
	v_fma_f32 v3, -v6, v16, v3
	v_fma_f32 v3, -v7, v17, v3
	s_waitcnt lgkmcnt(1)
	v_fma_f32 v3, -v8, v18, v3
	v_fma_f32 v3, -v9, v19, v3
	v_fma_f32 v3, -v10, v20, v3
	v_fma_f32 v3, -v11, v21, v3
	s_waitcnt lgkmcnt(0)
; DEVI float bf2f(bf16_t b) { return __uint_as_float(((unsigned)b) << 16); }
; DEVI void prep_item(const Params& p, int j, int n, int h, char* smem) {
;     ...
; #pragma unroll
;     for (int i = 0; i < 64; ++i) {
;       const float* amz = am + zero;
;       const float* sbz = sbeta + zero;
;       const float eg = __expf(sbz[64 + i]);
;       float acc = bf2f(*(const unsigned short*)(src + i * 272)) * sbz[i] * (isu ? 1.0f : eg);
; #pragma unroll
;       for (int j4 = 0; j4 < (i + 3) / 4; ++j4) {
;         const f32x4 a = *(const f32x4*)(amz + i * 68 + j4 * 4);
;         acc -= a[0] * x[j4 * 4 + 0];
;         acc -= a[1] * x[j4 * 4 + 1];
;         acc -= a[2] * x[j4 * 4 + 2];
;         acc -= a[3] * x[j4 * 4 + 3];
;       }
;       asm volatile("" : "+v"(zero), "+v"(acc));
;       x[i] = acc;
;     }
	v_fma_f32 v3, -v12, v22, v3
	v_fma_f32 v14, -v13, v23, v3
	v_fmac_f32_e32 v14, 0x80000000, v24
	v_fmac_f32_e32 v14, 0x80000000, v25
	s_nop 0
	v_lshlrev_b32_e32 v3, 2, v0
	v_add_u32_e32 v15, s0, v3
	ds_read2_b32 v[20:21], v15 offset0:11 offset1:75
	v_add_u32_e32 v3, 32, v3
	ds_read_b128 v[16:19], v3 offset:55216
	s_waitcnt lgkmcnt(1)
	v_mul_f32_e32 v15, 0x3fb8aa3b, v21
	ds_read_u16 v21, v2 offset:2992
	v_exp_f32_e32 v15, v15
	s_waitcnt lgkmcnt(0)
	v_lshlrev_b32_e32 v21, 16, v21
	v_cndmask_b32_e64 v15, v15, 1.0, vcc
	v_mul_f32_e32 v28, v20, v21
	ds_read_b128 v[20:23], v3 offset:55232
	ds_read_b128 v[24:27], v3 offset:55248
	v_mul_f32_e32 v3, v4, v16
	v_fma_f32 v3, v15, v28, -v3
	v_fma_f32 v3, -v5, v17, v3
	v_fma_f32 v3, -v6, v18, v3
	v_fma_f32 v3, -v7, v19, v3
	s_waitcnt lgkmcnt(1)
	v_fma_f32 v3, -v8, v20, v3
	v_fma_f32 v3, -v9, v21, v3
	v_fma_f32 v3, -v10, v22, v3
	v_fma_f32 v3, -v11, v23, v3
	s_waitcnt lgkmcnt(0)
	v_fma_f32 v3, -v12, v24, v3
	v_fma_f32 v3, -v13, v25, v3
	v_fma_f32 v15, -v14, v26, v3
	v_fmac_f32_e32 v15, 0x80000000, v27
	s_nop 0
	v_lshlrev_b32_e32 v3, 2, v0
	v_add_u32_e32 v16, s0, v3
	ds_read2_b32 v[20:21], v16 offset0:12 offset1:76
	v_add_u32_e32 v3, 32, v3
	s_waitcnt lgkmcnt(0)
	v_mul_f32_e32 v16, 0x3fb8aa3b, v21
	v_exp_f32_e32 v16, v16
	ds_read_u16 v21, v2 offset:3264
	v_cndmask_b32_e64 v28, v16, 1.0, vcc
	ds_read_b128 v[16:19], v3 offset:55488
	s_waitcnt lgkmcnt(1)
	v_lshlrev_b32_e32 v21, 16, v21
	v_mul_f32_e32 v29, v20, v21
	ds_read_b128 v[20:23], v3 offset:55504
	ds_read_b128 v[24:27], v3 offset:55520
	s_waitcnt lgkmcnt(2)
	v_mul_f32_e32 v3, v4, v16
	v_fma_f32 v3, v28, v29, -v3
	v_fma_f32 v3, -v5, v17, v3
	v_fma_f32 v3, -v6, v18, v3
	v_fma_f32 v3, -v7, v19, v3
	s_waitcnt lgkmcnt(1)
	v_fma_f32 v3, -v8, v20, v3
	v_fma_f32 v3, -v9, v21, v3
	v_fma_f32 v3, -v10, v22, v3
	v_fma_f32 v3, -v11, v23, v3
	s_waitcnt lgkmcnt(0)
	v_fma_f32 v3, -v12, v24, v3
	v_fma_f32 v3, -v13, v25, v3
	v_fma_f32 v3, -v14, v26, v3
	v_fma_f32 v16, -v15, v27, v3
	ds_read_u16 v18, v2 offset:3536
	v_lshlrev_b32_e32 v3, 2, v0
	v_add_u32_e32 v17, s0, v3
	ds_read2_b32 v[22:23], v17 offset0:13 offset1:77
	v_add_u32_e32 v3, 32, v3
	s_waitcnt lgkmcnt(0)
	v_mul_f32_e32 v17, 0x3fb8aa3b, v23
	v_lshlrev_b32_e32 v23, 16, v18
	ds_read_b128 v[18:21], v3 offset:55760
	v_exp_f32_e32 v17, v17
	v_mul_f32_e32 v35, v22, v23
	ds_read_b128 v[22:25], v3 offset:55776
	ds_read_b128 v[26:29], v3 offset:55792
	ds_read_b128 v[30:33], v3 offset:55808
	v_cndmask_b32_e64 v17, v17, 1.0, vcc
	s_waitcnt lgkmcnt(3)
	v_mul_f32_e32 v3, v4, v18
	v_fma_f32 v3, v17, v35, -v3
	v_fma_f32 v3, -v5, v19, v3
	v_fma_f32 v3, -v6, v20, v3
	v_fma_f32 v3, -v7, v21, v3
	s_waitcnt lgkmcnt(2)
	v_fma_f32 v3, -v8, v22, v3
	v_fma_f32 v3, -v9, v23, v3
	v_fma_f32 v3, -v10, v24, v3
	v_fma_f32 v3, -v11, v25, v3
	s_waitcnt lgkmcnt(1)
	v_fma_f32 v3, -v12, v26, v3
	v_fma_f32 v3, -v13, v27, v3
	v_fma_f32 v3, -v14, v28, v3
	v_fma_f32 v3, -v15, v29, v3
	s_waitcnt lgkmcnt(0)
	v_fma_f32 v17, -v16, v30, v3
	v_fmac_f32_e32 v17, 0x80000000, v31
	v_fmac_f32_e32 v17, 0x80000000, v32
	v_fmac_f32_e32 v17, 0x80000000, v33
	ds_read_u16 v19, v2 offset:3808
	v_lshlrev_b32_e32 v3, 2, v0
	v_add_u32_e32 v18, s0, v3
	ds_read2_b32 v[22:23], v18 offset0:14 offset1:78
	v_add_u32_e32 v3, 32, v3
	s_waitcnt lgkmcnt(0)
	v_mul_f32_e32 v18, 0x3fb8aa3b, v23
	v_exp_f32_e32 v18, v18
	v_lshlrev_b32_e32 v23, 16, v19
	v_mul_f32_e32 v36, v22, v23
	v_cndmask_b32_e64 v35, v18, 1.0, vcc
	ds_read_b128 v[18:21], v3 offset:56032
	ds_read_b128 v[22:25], v3 offset:56048
	ds_read_b128 v[26:29], v3 offset:56064
	ds_read_b128 v[30:33], v3 offset:56080
	s_waitcnt lgkmcnt(3)
	v_mul_f32_e32 v3, v4, v18
	v_fma_f32 v3, v35, v36, -v3
	v_fma_f32 v3, -v5, v19, v3
	v_fma_f32 v3, -v6, v20, v3
	v_fma_f32 v3, -v7, v21, v3
	s_waitcnt lgkmcnt(2)
	v_fma_f32 v3, -v8, v22, v3
	v_fma_f32 v3, -v9, v23, v3
	v_fma_f32 v3, -v10, v24, v3
	v_fma_f32 v3, -v11, v25, v3
	s_waitcnt lgkmcnt(1)
	v_fma_f32 v3, -v12, v26, v3
	v_fma_f32 v3, -v13, v27, v3
	v_fma_f32 v3, -v14, v28, v3
	v_fma_f32 v3, -v15, v29, v3
	s_waitcnt lgkmcnt(0)
	v_fma_f32 v3, -v16, v30, v3
	v_fma_f32 v18, -v17, v31, v3
	v_fmac_f32_e32 v18, 0x80000000, v32
	v_fmac_f32_e32 v18, 0x80000000, v33
	ds_read_u16 v20, v2 offset:4080
	v_lshlrev_b32_e32 v3, 2, v0
	v_add_u32_e32 v19, s0, v3
	ds_read2_b32 v[24:25], v19 offset0:15 offset1:79
	v_add_u32_e32 v3, 32, v3
	s_waitcnt lgkmcnt(0)
	v_mul_f32_e32 v19, 0x3fb8aa3b, v25
	v_lshlrev_b32_e32 v25, 16, v20
	ds_read_b128 v[20:23], v3 offset:56304
	v_exp_f32_e32 v19, v19
	v_mul_f32_e32 v32, v24, v25
	ds_read_b128 v[24:27], v3 offset:56320
	ds_read_b128 v[28:31], v3 offset:56336
	ds_read_b128 v[36:39], v3 offset:56352
	v_cndmask_b32_e64 v19, v19, 1.0, vcc
	s_waitcnt lgkmcnt(3)
	v_mul_f32_e32 v3, v4, v20
	v_fma_f32 v3, v19, v32, -v3
	v_fma_f32 v3, -v5, v21, v3
	v_fma_f32 v3, -v6, v22, v3
	v_fma_f32 v3, -v7, v23, v3
	s_waitcnt lgkmcnt(2)
	v_fma_f32 v3, -v8, v24, v3
	v_fma_f32 v3, -v9, v25, v3
	v_fma_f32 v3, -v10, v26, v3
	v_fma_f32 v3, -v11, v27, v3
	s_waitcnt lgkmcnt(1)
	v_fma_f32 v3, -v12, v28, v3
	v_fma_f32 v3, -v13, v29, v3
	v_fma_f32 v3, -v14, v30, v3
	v_fma_f32 v3, -v15, v31, v3
	s_waitcnt lgkmcnt(0)
	v_fma_f32 v3, -v16, v36, v3
	v_fma_f32 v3, -v17, v37, v3
	v_fma_f32 v19, -v18, v38, v3
	v_fmac_f32_e32 v19, 0x80000000, v39
	ds_read_u16 v21, v2 offset:4352
	v_lshlrev_b32_e32 v3, 2, v0
	v_add_u32_e32 v20, s0, v3
	ds_read2_b32 v[24:25], v20 offset0:16 offset1:80
	v_add_u32_e32 v3, 32, v3
	s_waitcnt lgkmcnt(0)
	v_mul_f32_e32 v20, 0x3fb8aa3b, v25
	v_exp_f32_e32 v20, v20
	v_lshlrev_b32_e32 v25, 16, v21
	v_mul_f32_e32 v33, v24, v25
	v_cndmask_b32_e64 v32, v20, 1.0, vcc
	ds_read_b128 v[20:23], v3 offset:56576
	ds_read_b128 v[24:27], v3 offset:56592
	ds_read_b128 v[28:31], v3 offset:56608
	ds_read_b128 v[36:39], v3 offset:56624
	s_waitcnt lgkmcnt(3)
; DEVI float bf2f(bf16_t b) { return __uint_as_float(((unsigned)b) << 16); }
; DEVI void prep_item(const Params& p, int j, int n, int h, char* smem) {
;     ...
; #pragma unroll
;     for (int i = 0; i < 64; ++i) {
;       const float* amz = am + zero;
;       const float* sbz = sbeta + zero;
;       const float eg = __expf(sbz[64 + i]);
;       float acc = bf2f(*(const unsigned short*)(src + i * 272)) * sbz[i] * (isu ? 1.0f : eg);
; #pragma unroll
;       for (int j4 = 0; j4 < (i + 3) / 4; ++j4) {
;         const f32x4 a = *(const f32x4*)(amz + i * 68 + j4 * 4);
;         acc -= a[0] * x[j4 * 4 + 0];
;         acc -= a[1] * x[j4 * 4 + 1];
;         acc -= a[2] * x[j4 * 4 + 2];
;         acc -= a[3] * x[j4 * 4 + 3];
;       }
;       asm volatile("" : "+v"(zero), "+v"(acc));
;       x[i] = acc;
;     }
	v_mul_f32_e32 v3, v4, v20
	v_fma_f32 v3, v32, v33, -v3
	v_fma_f32 v3, -v5, v21, v3
	v_fma_f32 v3, -v6, v22, v3
	v_fma_f32 v3, -v7, v23, v3
	s_waitcnt lgkmcnt(2)
	v_fma_f32 v3, -v8, v24, v3
	v_fma_f32 v3, -v9, v25, v3
	v_fma_f32 v3, -v10, v26, v3
	v_fma_f32 v3, -v11, v27, v3
	s_waitcnt lgkmcnt(1)
	v_fma_f32 v3, -v12, v28, v3
	v_fma_f32 v3, -v13, v29, v3
	v_fma_f32 v3, -v14, v30, v3
	v_fma_f32 v3, -v15, v31, v3
	s_waitcnt lgkmcnt(0)
	v_fma_f32 v3, -v16, v36, v3
	v_fma_f32 v3, -v17, v37, v3
	v_fma_f32 v3, -v18, v38, v3
	v_fma_f32 v20, -v19, v39, v3
	ds_read_u16 v22, v2 offset:4624
	v_lshlrev_b32_e32 v3, 2, v0
	v_add_u32_e32 v21, s0, v3
	ds_read2_b32 v[26:27], v21 offset0:17 offset1:81
	v_add_u32_e32 v3, 32, v3
	s_waitcnt lgkmcnt(0)
	v_mul_f32_e32 v21, 0x3fb8aa3b, v27
	v_lshlrev_b32_e32 v27, 16, v22
	ds_read_b128 v[22:25], v3 offset:56848
	v_exp_f32_e32 v21, v21
	v_mul_f32_e32 v35, v26, v27
	ds_read_b128 v[26:29], v3 offset:56864
	ds_read_b128 v[30:33], v3 offset:56880
	ds_read_b128 v[36:39], v3 offset:56896
	v_cndmask_b32_e64 v21, v21, 1.0, vcc
	s_waitcnt lgkmcnt(3)
	v_mul_f32_e32 v22, v4, v22
	v_fma_f32 v21, v21, v35, -v22
	v_fma_f32 v21, -v5, v23, v21
	v_fma_f32 v21, -v6, v24, v21
	v_fma_f32 v21, -v7, v25, v21
	s_waitcnt lgkmcnt(2)
	v_fma_f32 v21, -v8, v26, v21
	v_fma_f32 v21, -v9, v27, v21
	v_fma_f32 v21, -v10, v28, v21
	v_fma_f32 v21, -v11, v29, v21
	s_waitcnt lgkmcnt(1)
	v_fma_f32 v21, -v12, v30, v21
	v_fma_f32 v21, -v13, v31, v21
	v_fma_f32 v21, -v14, v32, v21
	v_fma_f32 v21, -v15, v33, v21
	ds_read_b128 v[22:25], v3 offset:56912
	s_waitcnt lgkmcnt(1)
	v_fma_f32 v3, -v16, v36, v21
	v_fma_f32 v3, -v17, v37, v3
	v_fma_f32 v3, -v18, v38, v3
	v_fma_f32 v3, -v19, v39, v3
	s_waitcnt lgkmcnt(0)
	v_fma_f32 v21, -v20, v22, v3
	v_fmac_f32_e32 v21, 0x80000000, v23
	v_fmac_f32_e32 v21, 0x80000000, v24
	v_fmac_f32_e32 v21, 0x80000000, v25
	ds_read_u16 v23, v2 offset:4896
	v_lshlrev_b32_e32 v3, 2, v0
	v_add_u32_e32 v22, s0, v3
	ds_read2_b32 v[26:27], v22 offset0:18 offset1:82
	v_add_u32_e32 v3, 32, v3
	s_waitcnt lgkmcnt(0)
	v_mul_f32_e32 v22, 0x3fb8aa3b, v27
	v_exp_f32_e32 v22, v22
	v_lshlrev_b32_e32 v27, 16, v23
	v_mul_f32_e32 v40, v26, v27
	v_cndmask_b32_e64 v35, v22, 1.0, vcc
	ds_read_b128 v[22:25], v3 offset:57120
	ds_read_b128 v[26:29], v3 offset:57136
	ds_read_b128 v[30:33], v3 offset:57152
	ds_read_b128 v[36:39], v3 offset:57168
	s_waitcnt lgkmcnt(3)
	v_mul_f32_e32 v22, v4, v22
	v_fma_f32 v22, v35, v40, -v22
	v_fma_f32 v22, -v5, v23, v22
	v_fma_f32 v22, -v6, v24, v22
	v_fma_f32 v22, -v7, v25, v22
	s_waitcnt lgkmcnt(2)
	v_fma_f32 v22, -v8, v26, v22
	v_fma_f32 v22, -v9, v27, v22
	v_fma_f32 v22, -v10, v28, v22
	v_fma_f32 v22, -v11, v29, v22
	s_waitcnt lgkmcnt(1)
	v_fma_f32 v22, -v12, v30, v22
	v_fma_f32 v22, -v13, v31, v22
	v_fma_f32 v22, -v14, v32, v22
	v_fma_f32 v26, -v15, v33, v22
	ds_read_b128 v[22:25], v3 offset:57184
	s_waitcnt lgkmcnt(1)
	v_fma_f32 v3, -v16, v36, v26
	v_fma_f32 v3, -v17, v37, v3
	v_fma_f32 v3, -v18, v38, v3
	v_fma_f32 v3, -v19, v39, v3
	s_waitcnt lgkmcnt(0)
	v_fma_f32 v3, -v20, v22, v3
	v_fma_f32 v22, -v21, v23, v3
	v_fmac_f32_e32 v22, 0x80000000, v24
	v_fmac_f32_e32 v22, 0x80000000, v25
	ds_read_u16 v24, v2 offset:5168
	v_lshlrev_b32_e32 v3, 2, v0
	v_add_u32_e32 v23, s0, v3
	ds_read2_b32 v[28:29], v23 offset0:19 offset1:83
	v_add_u32_e32 v3, 32, v3
	s_waitcnt lgkmcnt(0)
	v_mul_f32_e32 v23, 0x3fb8aa3b, v29
	v_lshlrev_b32_e32 v29, 16, v24
	ds_read_b128 v[24:27], v3 offset:57392
	v_exp_f32_e32 v23, v23
	v_mul_f32_e32 v32, v28, v29
	ds_read_b128 v[28:31], v3 offset:57408
	ds_read_b128 v[36:39], v3 offset:57424
	ds_read_b128 v[40:43], v3 offset:57440
	v_cndmask_b32_e64 v23, v23, 1.0, vcc
	s_waitcnt lgkmcnt(3)
	v_mul_f32_e32 v24, v4, v24
	v_fma_f32 v23, v23, v32, -v24
	v_fma_f32 v23, -v5, v25, v23
	v_fma_f32 v23, -v6, v26, v23
	v_fma_f32 v23, -v7, v27, v23
	s_waitcnt lgkmcnt(2)
	v_fma_f32 v23, -v8, v28, v23
	v_fma_f32 v23, -v9, v29, v23
	v_fma_f32 v23, -v10, v30, v23
	v_fma_f32 v23, -v11, v31, v23
	s_waitcnt lgkmcnt(1)
	v_fma_f32 v23, -v12, v36, v23
	v_fma_f32 v23, -v13, v37, v23
	v_fma_f32 v23, -v14, v38, v23
	v_fma_f32 v23, -v15, v39, v23
	ds_read_b128 v[24:27], v3 offset:57456
	s_waitcnt lgkmcnt(1)
	v_fma_f32 v3, -v16, v40, v23
	v_fma_f32 v3, -v17, v41, v3
	v_fma_f32 v3, -v18, v42, v3
	v_fma_f32 v3, -v19, v43, v3
	s_waitcnt lgkmcnt(0)
	v_fma_f32 v3, -v20, v24, v3
	v_fma_f32 v3, -v21, v25, v3
	v_fma_f32 v23, -v22, v26, v3
	v_fmac_f32_e32 v23, 0x80000000, v27
	ds_read_u16 v25, v2 offset:5440
	v_lshlrev_b32_e32 v3, 2, v0
	v_add_u32_e32 v24, s0, v3
	ds_read2_b32 v[28:29], v24 offset0:20 offset1:84
	v_add_u32_e32 v3, 32, v3
	s_waitcnt lgkmcnt(0)
	v_mul_f32_e32 v24, 0x3fb8aa3b, v29
	v_exp_f32_e32 v24, v24
	v_lshlrev_b32_e32 v29, 16, v25
	v_mul_f32_e32 v33, v28, v29
	v_cndmask_b32_e64 v32, v24, 1.0, vcc
	ds_read_b128 v[24:27], v3 offset:57664
	ds_read_b128 v[28:31], v3 offset:57680
	ds_read_b128 v[36:39], v3 offset:57696
	ds_read_b128 v[40:43], v3 offset:57712
	s_waitcnt lgkmcnt(3)
	v_mul_f32_e32 v24, v4, v24
	v_fma_f32 v24, v32, v33, -v24
	v_fma_f32 v24, -v5, v25, v24
	v_fma_f32 v24, -v6, v26, v24
	v_fma_f32 v24, -v7, v27, v24
	s_waitcnt lgkmcnt(2)
	v_fma_f32 v24, -v8, v28, v24
	v_fma_f32 v24, -v9, v29, v24
	v_fma_f32 v24, -v10, v30, v24
	v_fma_f32 v24, -v11, v31, v24
	s_waitcnt lgkmcnt(1)
	v_fma_f32 v24, -v12, v36, v24
	v_fma_f32 v24, -v13, v37, v24
	v_fma_f32 v24, -v14, v38, v24
	v_fma_f32 v28, -v15, v39, v24
	ds_read_b128 v[24:27], v3 offset:57728
	s_waitcnt lgkmcnt(1)
	v_fma_f32 v3, -v16, v40, v28
	v_fma_f32 v3, -v17, v41, v3
	v_fma_f32 v3, -v18, v42, v3
	v_fma_f32 v3, -v19, v43, v3
	s_waitcnt lgkmcnt(0)
; DEVI float bf2f(bf16_t b) { return __uint_as_float(((unsigned)b) << 16); }
; DEVI void prep_item(const Params& p, int j, int n, int h, char* smem) {
;     ...
; #pragma unroll
;     for (int i = 0; i < 64; ++i) {
;       const float* amz = am + zero;
;       const float* sbz = sbeta + zero;
;       const float eg = __expf(sbz[64 + i]);
;       float acc = bf2f(*(const unsigned short*)(src + i * 272)) * sbz[i] * (isu ? 1.0f : eg);
; #pragma unroll
;       for (int j4 = 0; j4 < (i + 3) / 4; ++j4) {
;         const f32x4 a = *(const f32x4*)(amz + i * 68 + j4 * 4);
;         acc -= a[0] * x[j4 * 4 + 0];
;         acc -= a[1] * x[j4 * 4 + 1];
;         acc -= a[2] * x[j4 * 4 + 2];
;         acc -= a[3] * x[j4 * 4 + 3];
;       }
;       asm volatile("" : "+v"(zero), "+v"(acc));
;       x[i] = acc;
;     }
	v_fma_f32 v3, -v20, v24, v3
	v_fma_f32 v3, -v21, v25, v3
	v_fma_f32 v3, -v22, v26, v3
	v_fma_f32 v24, -v23, v27, v3
	ds_read_u16 v26, v2 offset:5712
	v_lshlrev_b32_e32 v3, 2, v0
	v_add_u32_e32 v25, s0, v3
	ds_read2_b32 v[30:31], v25 offset0:21 offset1:85
	v_add_u32_e32 v3, 32, v3
	s_waitcnt lgkmcnt(0)
	v_mul_f32_e32 v25, 0x3fb8aa3b, v31
	v_lshlrev_b32_e32 v31, 16, v26
	ds_read_b128 v[26:29], v3 offset:57936
	v_exp_f32_e32 v25, v25
	v_mul_f32_e32 v35, v30, v31
	ds_read_b128 v[30:33], v3 offset:57952
	ds_read_b128 v[36:39], v3 offset:57968
	ds_read_b128 v[40:43], v3 offset:57984
	v_cndmask_b32_e64 v25, v25, 1.0, vcc
	s_waitcnt lgkmcnt(3)
	v_mul_f32_e32 v26, v4, v26
	v_fma_f32 v25, v25, v35, -v26
	v_fma_f32 v25, -v5, v27, v25
	v_fma_f32 v25, -v6, v28, v25
	v_fma_f32 v25, -v7, v29, v25
	s_waitcnt lgkmcnt(2)
	v_fma_f32 v25, -v8, v30, v25
	v_fma_f32 v25, -v9, v31, v25
	v_fma_f32 v25, -v10, v32, v25
	v_fma_f32 v25, -v11, v33, v25
	s_waitcnt lgkmcnt(1)
	v_fma_f32 v25, -v12, v36, v25
	v_fma_f32 v25, -v13, v37, v25
	v_fma_f32 v25, -v14, v38, v25
	v_fma_f32 v25, -v15, v39, v25
	ds_read_b128 v[26:29], v3 offset:58000
	s_waitcnt lgkmcnt(1)
	v_fma_f32 v25, -v16, v40, v25
	v_fma_f32 v25, -v17, v41, v25
	v_fma_f32 v25, -v18, v42, v25
	v_fma_f32 v25, -v19, v43, v25
	ds_read_b128 v[30:33], v3 offset:58016
	s_waitcnt lgkmcnt(1)
	v_fma_f32 v3, -v20, v26, v25
	v_fma_f32 v3, -v21, v27, v3
	v_fma_f32 v3, -v22, v28, v3
	v_fma_f32 v3, -v23, v29, v3
	s_waitcnt lgkmcnt(0)
	v_fma_f32 v25, -v24, v30, v3
	v_fmac_f32_e32 v25, 0x80000000, v31
	v_fmac_f32_e32 v25, 0x80000000, v32
	v_fmac_f32_e32 v25, 0x80000000, v33
	ds_read_u16 v27, v2 offset:5984
	v_lshlrev_b32_e32 v3, 2, v0
	v_add_u32_e32 v26, s0, v3
	ds_read2_b32 v[30:31], v26 offset0:22 offset1:86
	v_add_u32_e32 v3, 32, v3
	s_waitcnt lgkmcnt(0)
	v_mul_f32_e32 v26, 0x3fb8aa3b, v31
	v_exp_f32_e32 v26, v26
	v_lshlrev_b32_e32 v31, 16, v27
	v_mul_f32_e32 v44, v30, v31
	v_cndmask_b32_e64 v35, v26, 1.0, vcc
	ds_read_b128 v[26:29], v3 offset:58208
	ds_read_b128 v[30:33], v3 offset:58224
	ds_read_b128 v[36:39], v3 offset:58240
	ds_read_b128 v[40:43], v3 offset:58256
	s_waitcnt lgkmcnt(3)
	v_mul_f32_e32 v26, v4, v26
	v_fma_f32 v26, v35, v44, -v26
	v_fma_f32 v26, -v5, v27, v26
	v_fma_f32 v26, -v6, v28, v26
	v_fma_f32 v26, -v7, v29, v26
	s_waitcnt lgkmcnt(2)
	v_fma_f32 v26, -v8, v30, v26
	v_fma_f32 v26, -v9, v31, v26
	v_fma_f32 v26, -v10, v32, v26
	v_fma_f32 v26, -v11, v33, v26
	s_waitcnt lgkmcnt(1)
	v_fma_f32 v26, -v12, v36, v26
	v_fma_f32 v26, -v13, v37, v26
	v_fma_f32 v26, -v14, v38, v26
	v_fma_f32 v26, -v15, v39, v26
	s_waitcnt lgkmcnt(0)
	v_fma_f32 v30, -v16, v40, v26
	ds_read_b128 v[26:29], v3 offset:58272
	v_fma_f32 v30, -v17, v41, v30
	v_fma_f32 v30, -v18, v42, v30
	v_fma_f32 v35, -v19, v43, v30
	ds_read_b128 v[30:33], v3 offset:58288
	s_waitcnt lgkmcnt(1)
	v_fma_f32 v3, -v20, v26, v35
	v_fma_f32 v3, -v21, v27, v3
	v_fma_f32 v3, -v22, v28, v3
	v_fma_f32 v3, -v23, v29, v3
	s_waitcnt lgkmcnt(0)
	v_fma_f32 v3, -v24, v30, v3
	v_fma_f32 v26, -v25, v31, v3
	v_fmac_f32_e32 v26, 0x80000000, v32
	v_fmac_f32_e32 v26, 0x80000000, v33
	ds_read_u16 v28, v2 offset:6256
	v_lshlrev_b32_e32 v3, 2, v0
	v_add_u32_e32 v27, s0, v3
	ds_read2_b32 v[32:33], v27 offset0:23 offset1:87
	v_add_u32_e32 v3, 32, v3
	s_waitcnt lgkmcnt(0)
	v_mul_f32_e32 v27, 0x3fb8aa3b, v33
	v_lshlrev_b32_e32 v33, 16, v28
	ds_read_b128 v[28:31], v3 offset:58480
	v_exp_f32_e32 v27, v27
	v_mul_f32_e32 v32, v32, v33
	ds_read_b128 v[36:39], v3 offset:58496
	ds_read_b128 v[40:43], v3 offset:58512
	ds_read_b128 v[44:47], v3 offset:58528
	v_cndmask_b32_e64 v27, v27, 1.0, vcc
	s_waitcnt lgkmcnt(3)
	v_mul_f32_e32 v28, v4, v28
	v_fma_f32 v27, v27, v32, -v28
	v_fma_f32 v27, -v5, v29, v27
	v_fma_f32 v27, -v6, v30, v27
	v_fma_f32 v27, -v7, v31, v27
	s_waitcnt lgkmcnt(2)
	v_fma_f32 v27, -v8, v36, v27
	v_fma_f32 v27, -v9, v37, v27
	v_fma_f32 v27, -v10, v38, v27
	v_fma_f32 v27, -v11, v39, v27
	s_waitcnt lgkmcnt(1)
	v_fma_f32 v27, -v12, v40, v27
	v_fma_f32 v27, -v13, v41, v27
	v_fma_f32 v27, -v14, v42, v27
	v_fma_f32 v27, -v15, v43, v27
	ds_read_b128 v[28:31], v3 offset:58544
	s_waitcnt lgkmcnt(1)
	v_fma_f32 v27, -v16, v44, v27
	v_fma_f32 v27, -v17, v45, v27
	v_fma_f32 v27, -v18, v46, v27
	v_fma_f32 v27, -v19, v47, v27
	ds_read_b128 v[36:39], v3 offset:58560
	s_waitcnt lgkmcnt(1)
	v_fma_f32 v3, -v20, v28, v27
	v_fma_f32 v3, -v21, v29, v3
	v_fma_f32 v3, -v22, v30, v3
	v_fma_f32 v3, -v23, v31, v3
	s_waitcnt lgkmcnt(0)
	v_fma_f32 v3, -v24, v36, v3
	v_fma_f32 v3, -v25, v37, v3
	v_fma_f32 v27, -v26, v38, v3
	v_fmac_f32_e32 v27, 0x80000000, v39
	ds_read_u16 v29, v2 offset:6528
	v_lshlrev_b32_e32 v3, 2, v0
	v_add_u32_e32 v28, s0, v3
	ds_read2_b32 v[32:33], v28 offset0:24 offset1:88
	v_add_u32_e32 v3, 32, v3
	s_waitcnt lgkmcnt(1)
	v_lshlrev_b32_e32 v35, 16, v29
	s_waitcnt lgkmcnt(0)
	v_mul_f32_e32 v28, 0x3fb8aa3b, v33
	v_exp_f32_e32 v28, v28
	v_mul_f32_e32 v32, v32, v35
	v_cndmask_b32_e64 v33, v28, 1.0, vcc
	ds_read_b128 v[28:31], v3 offset:58752
	ds_read_b128 v[36:39], v3 offset:58768
	ds_read_b128 v[40:43], v3 offset:58784
	ds_read_b128 v[44:47], v3 offset:58800
	s_waitcnt lgkmcnt(3)
	v_mul_f32_e32 v28, v4, v28
	v_fma_f32 v28, v33, v32, -v28
	v_fma_f32 v28, -v5, v29, v28
	v_fma_f32 v28, -v6, v30, v28
	v_fma_f32 v28, -v7, v31, v28
	s_waitcnt lgkmcnt(2)
	v_fma_f32 v28, -v8, v36, v28
	v_fma_f32 v28, -v9, v37, v28
	v_fma_f32 v28, -v10, v38, v28
	v_fma_f32 v28, -v11, v39, v28
	s_waitcnt lgkmcnt(1)
	v_fma_f32 v28, -v12, v40, v28
	v_fma_f32 v28, -v13, v41, v28
	v_fma_f32 v28, -v14, v42, v28
	v_fma_f32 v28, -v15, v43, v28
	s_waitcnt lgkmcnt(0)
; DEVI float bf2f(bf16_t b) { return __uint_as_float(((unsigned)b) << 16); }
; DEVI void prep_item(const Params& p, int j, int n, int h, char* smem) {
;     ...
; #pragma unroll
;     for (int i = 0; i < 64; ++i) {
;       const float* amz = am + zero;
;       const float* sbz = sbeta + zero;
;       const float eg = __expf(sbz[64 + i]);
;       float acc = bf2f(*(const unsigned short*)(src + i * 272)) * sbz[i] * (isu ? 1.0f : eg);
; #pragma unroll
;       for (int j4 = 0; j4 < (i + 3) / 4; ++j4) {
;         const f32x4 a = *(const f32x4*)(amz + i * 68 + j4 * 4);
;         acc -= a[0] * x[j4 * 4 + 0];
;         acc -= a[1] * x[j4 * 4 + 1];
;         acc -= a[2] * x[j4 * 4 + 2];
;         acc -= a[3] * x[j4 * 4 + 3];
;       }
;       asm volatile("" : "+v"(zero), "+v"(acc));
;       x[i] = acc;
;     }
	v_fma_f32 v32, -v16, v44, v28
	ds_read_b128 v[28:31], v3 offset:58816
	v_fma_f32 v32, -v17, v45, v32
	v_fma_f32 v32, -v18, v46, v32
	v_fma_f32 v32, -v19, v47, v32
	ds_read_b128 v[36:39], v3 offset:58832
	s_waitcnt lgkmcnt(1)
	v_fma_f32 v3, -v20, v28, v32
	v_fma_f32 v3, -v21, v29, v3
	v_fma_f32 v3, -v22, v30, v3
	v_fma_f32 v3, -v23, v31, v3
	s_waitcnt lgkmcnt(0)
	v_fma_f32 v3, -v24, v36, v3
	v_fma_f32 v3, -v25, v37, v3
	v_fma_f32 v3, -v26, v38, v3
	v_fma_f32 v28, -v27, v39, v3
	ds_read_u16 v30, v2 offset:6800
	v_lshlrev_b32_e32 v3, 2, v0
	v_add_u32_e32 v29, s0, v3
	ds_read2_b32 v[36:37], v29 offset0:25 offset1:89
	v_add_u32_e32 v3, 32, v3
	s_waitcnt lgkmcnt(1)
	v_lshlrev_b32_e32 v35, 16, v30
	ds_read_b128 v[30:33], v3 offset:59024
	s_waitcnt lgkmcnt(1)
	v_mul_f32_e32 v29, 0x3fb8aa3b, v37
	v_exp_f32_e32 v29, v29
	v_mul_f32_e32 v35, v36, v35
	s_waitcnt lgkmcnt(0)
	v_mul_f32_e32 v30, v4, v30
	ds_read_b128 v[36:39], v3 offset:59040
	ds_read_b128 v[40:43], v3 offset:59056
	ds_read_b128 v[44:47], v3 offset:59072
	v_cndmask_b32_e64 v29, v29, 1.0, vcc
	v_fma_f32 v29, v29, v35, -v30
	v_fma_f32 v29, -v5, v31, v29
	v_fma_f32 v29, -v6, v32, v29
	v_fma_f32 v29, -v7, v33, v29
	s_waitcnt lgkmcnt(2)
	v_fma_f32 v29, -v8, v36, v29
	v_fma_f32 v29, -v9, v37, v29
	v_fma_f32 v29, -v10, v38, v29
	v_fma_f32 v29, -v11, v39, v29
	s_waitcnt lgkmcnt(1)
	v_fma_f32 v29, -v12, v40, v29
	v_fma_f32 v29, -v13, v41, v29
	v_fma_f32 v29, -v14, v42, v29
	v_fma_f32 v29, -v15, v43, v29
	ds_read_b128 v[30:33], v3 offset:59088
	s_waitcnt lgkmcnt(1)
	v_fma_f32 v29, -v16, v44, v29
	v_fma_f32 v29, -v17, v45, v29
	v_fma_f32 v29, -v18, v46, v29
	v_fma_f32 v29, -v19, v47, v29
	ds_read_b128 v[36:39], v3 offset:59104
	s_waitcnt lgkmcnt(1)
	v_fma_f32 v29, -v20, v30, v29
	v_fma_f32 v29, -v21, v31, v29
	v_fma_f32 v29, -v22, v32, v29
	v_fma_f32 v29, -v23, v33, v29
	ds_read_b128 v[30:33], v3 offset:59120
	s_waitcnt lgkmcnt(1)
	v_fma_f32 v3, -v24, v36, v29
	v_fma_f32 v3, -v25, v37, v3
	v_fma_f32 v3, -v26, v38, v3
	v_fma_f32 v3, -v27, v39, v3
	s_waitcnt lgkmcnt(0)
	v_fma_f32 v29, -v28, v30, v3
	v_fmac_f32_e32 v29, 0x80000000, v31
	v_fmac_f32_e32 v29, 0x80000000, v32
	v_fmac_f32_e32 v29, 0x80000000, v33
	ds_read_u16 v31, v2 offset:7072
	v_lshlrev_b32_e32 v3, 2, v0
	v_add_u32_e32 v30, s0, v3
	ds_read2_b32 v[36:37], v30 offset0:26 offset1:90
	v_add_u32_e32 v3, 32, v3
	s_waitcnt lgkmcnt(0)
	v_mul_f32_e32 v30, 0x3fb8aa3b, v37
	v_exp_f32_e32 v30, v30
	v_lshlrev_b32_e32 v37, 16, v31
	v_mul_f32_e32 v48, v36, v37
	v_cndmask_b32_e64 v35, v30, 1.0, vcc
	ds_read_b128 v[30:33], v3 offset:59296
	ds_read_b128 v[36:39], v3 offset:59312
	ds_read_b128 v[40:43], v3 offset:59328
	ds_read_b128 v[44:47], v3 offset:59344
	s_waitcnt lgkmcnt(3)
	v_mul_f32_e32 v30, v4, v30
	v_fma_f32 v30, v35, v48, -v30
	v_fma_f32 v30, -v5, v31, v30
	v_fma_f32 v30, -v6, v32, v30
	v_fma_f32 v30, -v7, v33, v30
	s_waitcnt lgkmcnt(2)
	v_fma_f32 v30, -v8, v36, v30
	v_fma_f32 v30, -v9, v37, v30
	v_fma_f32 v30, -v10, v38, v30
	v_fma_f32 v30, -v11, v39, v30
	s_waitcnt lgkmcnt(1)
	v_fma_f32 v30, -v12, v40, v30
	v_fma_f32 v30, -v13, v41, v30
	v_fma_f32 v30, -v14, v42, v30
	v_fma_f32 v30, -v15, v43, v30
	s_waitcnt lgkmcnt(0)
	v_fma_f32 v35, -v16, v44, v30
	ds_read_b128 v[30:33], v3 offset:59360
	v_fma_f32 v35, -v17, v45, v35
	v_fma_f32 v35, -v18, v46, v35
	v_fma_f32 v35, -v19, v47, v35
	ds_read_b128 v[36:39], v3 offset:59376
	s_waitcnt lgkmcnt(1)
	v_fma_f32 v30, -v20, v30, v35
	v_fma_f32 v30, -v21, v31, v30
	v_fma_f32 v30, -v22, v32, v30
	v_fma_f32 v35, -v23, v33, v30
	ds_read_b128 v[30:33], v3 offset:59392
	s_waitcnt lgkmcnt(1)
	v_fma_f32 v3, -v24, v36, v35
	v_fma_f32 v3, -v25, v37, v3
	v_fma_f32 v3, -v26, v38, v3
	v_fma_f32 v3, -v27, v39, v3
	s_waitcnt lgkmcnt(0)
	v_fma_f32 v3, -v28, v30, v3
	v_fma_f32 v30, -v29, v31, v3
	v_fmac_f32_e32 v30, 0x80000000, v32
	v_fmac_f32_e32 v30, 0x80000000, v33
	s_nop 0
	v_lshlrev_b32_e32 v3, 2, v0
	v_add_u32_e32 v31, s0, v3
	ds_read2_b32 v[32:33], v31 offset0:27 offset1:91
	v_add_u32_e32 v3, 32, v3
	ds_read_b128 v[36:39], v3 offset:59568
	s_waitcnt lgkmcnt(1)
	v_mul_f32_e32 v31, 0x3fb8aa3b, v33
	ds_read_u16 v33, v2 offset:7344
	v_exp_f32_e32 v31, v31
	ds_read_b128 v[40:43], v3 offset:59584
	ds_read_b128 v[44:47], v3 offset:59600
	ds_read_b128 v[48:51], v3 offset:59616
	s_waitcnt lgkmcnt(3)
	v_lshlrev_b32_e32 v33, 16, v33
	v_cndmask_b32_e64 v31, v31, 1.0, vcc
	v_mul_f32_e32 v32, v32, v33
	v_mul_f32_e32 v33, v4, v36
	v_fma_f32 v31, v31, v32, -v33
	v_fma_f32 v31, -v5, v37, v31
	v_fma_f32 v31, -v6, v38, v31
	v_fma_f32 v31, -v7, v39, v31
	s_waitcnt lgkmcnt(2)
	v_fma_f32 v31, -v8, v40, v31
	v_fma_f32 v31, -v9, v41, v31
	v_fma_f32 v31, -v10, v42, v31
	v_fma_f32 v31, -v11, v43, v31
	s_waitcnt lgkmcnt(1)
	v_fma_f32 v31, -v12, v44, v31
	v_fma_f32 v31, -v13, v45, v31
	v_fma_f32 v31, -v14, v46, v31
	v_fma_f32 v31, -v15, v47, v31
	ds_read_b128 v[36:39], v3 offset:59632
	s_waitcnt lgkmcnt(1)
	v_fma_f32 v31, -v16, v48, v31
	v_fma_f32 v31, -v17, v49, v31
	v_fma_f32 v31, -v18, v50, v31
	v_fma_f32 v31, -v19, v51, v31
	ds_read_b128 v[40:43], v3 offset:59648
	s_waitcnt lgkmcnt(1)
	v_fma_f32 v31, -v20, v36, v31
	v_fma_f32 v31, -v21, v37, v31
	v_fma_f32 v31, -v22, v38, v31
	v_fma_f32 v31, -v23, v39, v31
	ds_read_b128 v[36:39], v3 offset:59664
	s_waitcnt lgkmcnt(1)
	v_fma_f32 v3, -v24, v40, v31
	v_fma_f32 v3, -v25, v41, v3
	v_fma_f32 v3, -v26, v42, v3
	v_fma_f32 v3, -v27, v43, v3
	s_waitcnt lgkmcnt(0)
	v_fma_f32 v3, -v28, v36, v3
	v_fma_f32 v3, -v29, v37, v3
	v_fma_f32 v31, -v30, v38, v3
	v_fmac_f32_e32 v31, 0x80000000, v39
	ds_read_u16 v35, v2 offset:7616
	v_lshlrev_b32_e32 v3, 2, v0
	v_add_u32_e32 v32, s0, v3
	ds_read2_b32 v[32:33], v32 offset0:28 offset1:92
	v_add_u32_e32 v3, 32, v3
	ds_read_b128 v[36:39], v3 offset:59840
	s_waitcnt lgkmcnt(2)
; DEVI float bf2f(bf16_t b) { return __uint_as_float(((unsigned)b) << 16); }
; DEVI void prep_item(const Params& p, int j, int n, int h, char* smem) {
;     ...
; #pragma unroll
;     for (int i = 0; i < 64; ++i) {
;       const float* amz = am + zero;
;       const float* sbz = sbeta + zero;
;       const float eg = __expf(sbz[64 + i]);
;       float acc = bf2f(*(const unsigned short*)(src + i * 272)) * sbz[i] * (isu ? 1.0f : eg);
; #pragma unroll
;       for (int j4 = 0; j4 < (i + 3) / 4; ++j4) {
;         const f32x4 a = *(const f32x4*)(amz + i * 68 + j4 * 4);
;         acc -= a[0] * x[j4 * 4 + 0];
;         acc -= a[1] * x[j4 * 4 + 1];
;         acc -= a[2] * x[j4 * 4 + 2];
;         acc -= a[3] * x[j4 * 4 + 3];
;       }
;       asm volatile("" : "+v"(zero), "+v"(acc));
;       x[i] = acc;
;     }
	v_lshlrev_b32_e32 v35, 16, v35
	ds_read_b128 v[40:43], v3 offset:59856
	ds_read_b128 v[44:47], v3 offset:59872
	ds_read_b128 v[48:51], v3 offset:59888
	s_waitcnt lgkmcnt(4)
	v_mul_f32_e32 v33, 0x3fb8aa3b, v33
	v_exp_f32_e32 v33, v33
	v_mul_f32_e32 v32, v32, v35
	s_waitcnt lgkmcnt(3)
	v_mul_f32_e32 v35, v4, v36
	v_cndmask_b32_e64 v33, v33, 1.0, vcc
	v_fma_f32 v32, v33, v32, -v35
	v_fma_f32 v32, -v5, v37, v32
	v_fma_f32 v32, -v6, v38, v32
	v_fma_f32 v32, -v7, v39, v32
	s_waitcnt lgkmcnt(2)
	v_fma_f32 v32, -v8, v40, v32
	v_fma_f32 v32, -v9, v41, v32
	v_fma_f32 v32, -v10, v42, v32
	v_fma_f32 v32, -v11, v43, v32
	s_waitcnt lgkmcnt(1)
	v_fma_f32 v32, -v12, v44, v32
	v_fma_f32 v32, -v13, v45, v32
	v_fma_f32 v32, -v14, v46, v32
	v_fma_f32 v32, -v15, v47, v32
	ds_read_b128 v[36:39], v3 offset:59904
	s_waitcnt lgkmcnt(1)
	v_fma_f32 v32, -v16, v48, v32
	v_fma_f32 v32, -v17, v49, v32
	v_fma_f32 v32, -v18, v50, v32
	v_fma_f32 v32, -v19, v51, v32
	ds_read_b128 v[40:43], v3 offset:59920
	s_waitcnt lgkmcnt(1)
	v_fma_f32 v32, -v20, v36, v32
	v_fma_f32 v32, -v21, v37, v32
	v_fma_f32 v32, -v22, v38, v32
	v_fma_f32 v32, -v23, v39, v32
	ds_read_b128 v[36:39], v3 offset:59936
	s_waitcnt lgkmcnt(1)
	v_fma_f32 v3, -v24, v40, v32
	v_fma_f32 v3, -v25, v41, v3
	v_fma_f32 v3, -v26, v42, v3
	v_fma_f32 v3, -v27, v43, v3
	s_waitcnt lgkmcnt(0)
	v_fma_f32 v3, -v28, v36, v3
	v_fma_f32 v3, -v29, v37, v3
	v_fma_f32 v3, -v30, v38, v3
	v_fma_f32 v32, -v31, v39, v3
	ds_read_u16 v35, v2 offset:7888
	v_lshlrev_b32_e32 v3, 2, v0
	v_add_u32_e32 v33, s0, v3
	ds_read2_b32 v[40:41], v33 offset0:29 offset1:93
	v_add_u32_e32 v3, 32, v3
	ds_read_b128 v[36:39], v3 offset:60112
	s_waitcnt lgkmcnt(2)
	v_lshlrev_b32_e32 v35, 16, v35
	s_waitcnt lgkmcnt(1)
	v_mul_f32_e32 v33, 0x3fb8aa3b, v41
	v_exp_f32_e32 v33, v33
	v_mul_f32_e32 v35, v40, v35
	s_waitcnt lgkmcnt(0)
	v_mul_f32_e32 v36, v4, v36
	ds_read_b128 v[40:43], v3 offset:60128
	ds_read_b128 v[44:47], v3 offset:60144
	ds_read_b128 v[48:51], v3 offset:60160
	v_cndmask_b32_e64 v33, v33, 1.0, vcc
	v_fma_f32 v33, v33, v35, -v36
	v_fma_f32 v33, -v5, v37, v33
	v_fma_f32 v33, -v6, v38, v33
	v_fma_f32 v33, -v7, v39, v33
	s_waitcnt lgkmcnt(2)
	v_fma_f32 v33, -v8, v40, v33
	v_fma_f32 v33, -v9, v41, v33
	v_fma_f32 v33, -v10, v42, v33
	v_fma_f32 v33, -v11, v43, v33
	s_waitcnt lgkmcnt(1)
	v_fma_f32 v33, -v12, v44, v33
	v_fma_f32 v33, -v13, v45, v33
	v_fma_f32 v33, -v14, v46, v33
	v_fma_f32 v33, -v15, v47, v33
	ds_read_b128 v[36:39], v3 offset:60176
	s_waitcnt lgkmcnt(1)
	v_fma_f32 v33, -v16, v48, v33
	v_fma_f32 v33, -v17, v49, v33
	v_fma_f32 v33, -v18, v50, v33
	v_fma_f32 v33, -v19, v51, v33
	ds_read_b128 v[40:43], v3 offset:60192
	s_waitcnt lgkmcnt(1)
	v_fma_f32 v33, -v20, v36, v33
	v_fma_f32 v33, -v21, v37, v33
	v_fma_f32 v33, -v22, v38, v33
	v_fma_f32 v33, -v23, v39, v33
	ds_read_b128 v[36:39], v3 offset:60208
	s_waitcnt lgkmcnt(1)
	v_fma_f32 v33, -v24, v40, v33
	v_fma_f32 v33, -v25, v41, v33
	v_fma_f32 v33, -v26, v42, v33
	v_fma_f32 v33, -v27, v43, v33
	ds_read_b128 v[40:43], v3 offset:60224
	s_waitcnt lgkmcnt(1)
	v_fma_f32 v3, -v28, v36, v33
	v_fma_f32 v3, -v29, v37, v3
	v_fma_f32 v3, -v30, v38, v3
	v_fma_f32 v3, -v31, v39, v3
	s_waitcnt lgkmcnt(0)
	v_fma_f32 v33, -v32, v40, v3
	v_fmac_f32_e32 v33, 0x80000000, v41
	v_fmac_f32_e32 v33, 0x80000000, v42
	v_fmac_f32_e32 v33, 0x80000000, v43
	ds_read_u16 v36, v2 offset:8160
	v_lshlrev_b32_e32 v3, 2, v0
	v_add_u32_e32 v35, s0, v3
	ds_read2_b32 v[40:41], v35 offset0:30 offset1:94
	v_add_u32_e32 v3, 32, v3
	s_waitcnt lgkmcnt(0)
	v_mul_f32_e32 v35, 0x3fb8aa3b, v41
	v_lshlrev_b32_e32 v41, 16, v36
	ds_read_b128 v[36:39], v3 offset:60384
	v_exp_f32_e32 v35, v35
	v_mul_f32_e32 v52, v40, v41
	ds_read_b128 v[40:43], v3 offset:60400
	ds_read_b128 v[44:47], v3 offset:60416
	ds_read_b128 v[48:51], v3 offset:60432
	v_cndmask_b32_e64 v35, v35, 1.0, vcc
	s_waitcnt lgkmcnt(3)
	v_mul_f32_e32 v36, v4, v36
	v_fma_f32 v35, v35, v52, -v36
	v_fma_f32 v35, -v5, v37, v35
	v_fma_f32 v35, -v6, v38, v35
	v_fma_f32 v35, -v7, v39, v35
	s_waitcnt lgkmcnt(2)
	v_fma_f32 v35, -v8, v40, v35
	v_fma_f32 v35, -v9, v41, v35
	v_fma_f32 v35, -v10, v42, v35
	v_fma_f32 v35, -v11, v43, v35
	s_waitcnt lgkmcnt(1)
	v_fma_f32 v35, -v12, v44, v35
	v_fma_f32 v35, -v13, v45, v35
	v_fma_f32 v35, -v14, v46, v35
	v_fma_f32 v35, -v15, v47, v35
	ds_read_b128 v[36:39], v3 offset:60448
	s_waitcnt lgkmcnt(1)
	v_fma_f32 v35, -v16, v48, v35
	v_fma_f32 v35, -v17, v49, v35
	v_fma_f32 v35, -v18, v50, v35
	v_fma_f32 v35, -v19, v51, v35
	ds_read_b128 v[40:43], v3 offset:60464
	s_waitcnt lgkmcnt(1)
	v_fma_f32 v35, -v20, v36, v35
	v_fma_f32 v35, -v21, v37, v35
	v_fma_f32 v35, -v22, v38, v35
	v_fma_f32 v35, -v23, v39, v35
	ds_read_b128 v[36:39], v3 offset:60480
	s_waitcnt lgkmcnt(1)
	v_fma_f32 v35, -v24, v40, v35
	v_fma_f32 v35, -v25, v41, v35
	v_fma_f32 v35, -v26, v42, v35
	v_fma_f32 v35, -v27, v43, v35
	ds_read_b128 v[40:43], v3 offset:60496
	s_waitcnt lgkmcnt(1)
	v_fma_f32 v3, -v28, v36, v35
	v_fma_f32 v3, -v29, v37, v3
	v_fma_f32 v3, -v30, v38, v3
	v_fma_f32 v3, -v31, v39, v3
	s_waitcnt lgkmcnt(0)
	v_fma_f32 v3, -v32, v40, v3
	v_fma_f32 v35, -v33, v41, v3
	v_fmac_f32_e32 v35, 0x80000000, v42
	v_fmac_f32_e32 v35, 0x80000000, v43
	ds_read_u16 v37, v2 offset:8432
	v_lshlrev_b32_e32 v3, 2, v0
	v_add_u32_e32 v36, s0, v3
	ds_read2_b32 v[40:41], v36 offset0:31 offset1:95
	v_add_u32_e32 v3, 32, v3
	s_waitcnt lgkmcnt(0)
	v_mul_f32_e32 v36, 0x3fb8aa3b, v41
	v_exp_f32_e32 v36, v36
	v_lshlrev_b32_e32 v41, 16, v37
	v_mul_f32_e32 v53, v40, v41
	v_cndmask_b32_e64 v52, v36, 1.0, vcc
	ds_read_b128 v[36:39], v3 offset:60656
	ds_read_b128 v[40:43], v3 offset:60672
	ds_read_b128 v[44:47], v3 offset:60688
	ds_read_b128 v[48:51], v3 offset:60704
	s_waitcnt lgkmcnt(3)
; DEVI float bf2f(bf16_t b) { return __uint_as_float(((unsigned)b) << 16); }
; DEVI void prep_item(const Params& p, int j, int n, int h, char* smem) {
;     ...
; #pragma unroll
;     for (int i = 0; i < 64; ++i) {
;       const float* amz = am + zero;
;       const float* sbz = sbeta + zero;
;       const float eg = __expf(sbz[64 + i]);
;       float acc = bf2f(*(const unsigned short*)(src + i * 272)) * sbz[i] * (isu ? 1.0f : eg);
; #pragma unroll
;       for (int j4 = 0; j4 < (i + 3) / 4; ++j4) {
;         const f32x4 a = *(const f32x4*)(amz + i * 68 + j4 * 4);
;         acc -= a[0] * x[j4 * 4 + 0];
;         acc -= a[1] * x[j4 * 4 + 1];
;         acc -= a[2] * x[j4 * 4 + 2];
;         acc -= a[3] * x[j4 * 4 + 3];
;       }
;       asm volatile("" : "+v"(zero), "+v"(acc));
;       x[i] = acc;
;     }
	v_mul_f32_e32 v36, v4, v36
	v_fma_f32 v36, v52, v53, -v36
	v_fma_f32 v36, -v5, v37, v36
	v_fma_f32 v36, -v6, v38, v36
	v_fma_f32 v36, -v7, v39, v36
	s_waitcnt lgkmcnt(2)
	v_fma_f32 v36, -v8, v40, v36
	v_fma_f32 v36, -v9, v41, v36
	v_fma_f32 v36, -v10, v42, v36
	v_fma_f32 v36, -v11, v43, v36
	s_waitcnt lgkmcnt(1)
	v_fma_f32 v36, -v12, v44, v36
	v_fma_f32 v36, -v13, v45, v36
	v_fma_f32 v36, -v14, v46, v36
	v_fma_f32 v36, -v15, v47, v36
	s_waitcnt lgkmcnt(0)
	v_fma_f32 v40, -v16, v48, v36
	ds_read_b128 v[36:39], v3 offset:60720
	v_fma_f32 v40, -v17, v49, v40
	v_fma_f32 v40, -v18, v50, v40
	v_fma_f32 v44, -v19, v51, v40
	ds_read_b128 v[40:43], v3 offset:60736
	s_waitcnt lgkmcnt(1)
	v_fma_f32 v36, -v20, v36, v44
	v_fma_f32 v36, -v21, v37, v36
	v_fma_f32 v36, -v22, v38, v36
	v_fma_f32 v36, -v23, v39, v36
	s_waitcnt lgkmcnt(0)
	v_fma_f32 v40, -v24, v40, v36
	ds_read_b128 v[36:39], v3 offset:60752
	v_fma_f32 v40, -v25, v41, v40
	v_fma_f32 v40, -v26, v42, v40
	v_fma_f32 v44, -v27, v43, v40
	ds_read_b128 v[40:43], v3 offset:60768
	s_waitcnt lgkmcnt(1)
	v_fma_f32 v3, -v28, v36, v44
	v_fma_f32 v3, -v29, v37, v3
	v_fma_f32 v3, -v30, v38, v3
	v_fma_f32 v3, -v31, v39, v3
	s_waitcnt lgkmcnt(0)
	v_fma_f32 v3, -v32, v40, v3
	v_fma_f32 v3, -v33, v41, v3
	v_fma_f32 v36, -v35, v42, v3
	v_fmac_f32_e32 v36, 0x80000000, v43
	ds_read_u16 v38, v2 offset:8704
	v_lshlrev_b32_e32 v3, 2, v0
	v_add_u32_e32 v37, s0, v3
	ds_read2_b32 v[42:43], v37 offset0:32 offset1:96
	v_add_u32_e32 v3, 32, v3
	s_waitcnt lgkmcnt(0)
	v_mul_f32_e32 v37, 0x3fb8aa3b, v43
	v_lshlrev_b32_e32 v43, 16, v38
	ds_read_b128 v[38:41], v3 offset:60928
	v_exp_f32_e32 v37, v37
	v_mul_f32_e32 v54, v42, v43
	ds_read_b128 v[42:45], v3 offset:60944
	ds_read_b128 v[46:49], v3 offset:60960
	ds_read_b128 v[50:53], v3 offset:60976
	v_cndmask_b32_e64 v37, v37, 1.0, vcc
	s_waitcnt lgkmcnt(3)
	v_mul_f32_e32 v38, v4, v38
	v_fma_f32 v37, v37, v54, -v38
	v_fma_f32 v37, -v5, v39, v37
	v_fma_f32 v37, -v6, v40, v37
	v_fma_f32 v37, -v7, v41, v37
	s_waitcnt lgkmcnt(2)
	v_fma_f32 v37, -v8, v42, v37
	v_fma_f32 v37, -v9, v43, v37
	v_fma_f32 v37, -v10, v44, v37
	v_fma_f32 v37, -v11, v45, v37
	s_waitcnt lgkmcnt(1)
	v_fma_f32 v37, -v12, v46, v37
	v_fma_f32 v37, -v13, v47, v37
	v_fma_f32 v37, -v14, v48, v37
	v_fma_f32 v37, -v15, v49, v37
	ds_read_b128 v[38:41], v3 offset:60992
	s_waitcnt lgkmcnt(1)
	v_fma_f32 v37, -v16, v50, v37
	v_fma_f32 v37, -v17, v51, v37
	v_fma_f32 v37, -v18, v52, v37
	v_fma_f32 v37, -v19, v53, v37
	ds_read_b128 v[42:45], v3 offset:61008
	s_waitcnt lgkmcnt(1)
	v_fma_f32 v37, -v20, v38, v37
	v_fma_f32 v37, -v21, v39, v37
	v_fma_f32 v37, -v22, v40, v37
	v_fma_f32 v37, -v23, v41, v37
	ds_read_b128 v[38:41], v3 offset:61024
	s_waitcnt lgkmcnt(1)
	v_fma_f32 v37, -v24, v42, v37
	v_fma_f32 v37, -v25, v43, v37
	v_fma_f32 v37, -v26, v44, v37
	v_fma_f32 v37, -v27, v45, v37
	ds_read_b128 v[42:45], v3 offset:61040
	s_waitcnt lgkmcnt(1)
	v_fma_f32 v3, -v28, v38, v37
	v_fma_f32 v3, -v29, v39, v3
	v_fma_f32 v3, -v30, v40, v3
	v_fma_f32 v3, -v31, v41, v3
	s_waitcnt lgkmcnt(0)
	v_fma_f32 v3, -v32, v42, v3
	v_fma_f32 v3, -v33, v43, v3
	v_fma_f32 v3, -v35, v44, v3
	v_fma_f32 v37, -v36, v45, v3
	ds_read_u16 v39, v2 offset:8976
	v_lshlrev_b32_e32 v3, 2, v0
	v_add_u32_e32 v38, s0, v3
	ds_read2_b32 v[42:43], v38 offset0:33 offset1:97
	v_add_u32_e32 v3, 32, v3
	s_waitcnt lgkmcnt(0)
	v_mul_f32_e32 v38, 0x3fb8aa3b, v43
	v_exp_f32_e32 v38, v38
	v_lshlrev_b32_e32 v43, 16, v39
	v_mul_f32_e32 v55, v42, v43
	v_cndmask_b32_e64 v54, v38, 1.0, vcc
	ds_read_b128 v[38:41], v3 offset:61200
	ds_read_b128 v[42:45], v3 offset:61216
	ds_read_b128 v[46:49], v3 offset:61232
	ds_read_b128 v[50:53], v3 offset:61248
	s_waitcnt lgkmcnt(3)
	v_mul_f32_e32 v38, v4, v38
	v_fma_f32 v38, v54, v55, -v38
	v_fma_f32 v38, -v5, v39, v38
	v_fma_f32 v38, -v6, v40, v38
	v_fma_f32 v38, -v7, v41, v38
	s_waitcnt lgkmcnt(2)
	v_fma_f32 v38, -v8, v42, v38
	v_fma_f32 v38, -v9, v43, v38
	v_fma_f32 v38, -v10, v44, v38
	v_fma_f32 v38, -v11, v45, v38
	s_waitcnt lgkmcnt(1)
	v_fma_f32 v38, -v12, v46, v38
	v_fma_f32 v38, -v13, v47, v38
	v_fma_f32 v38, -v14, v48, v38
	v_fma_f32 v38, -v15, v49, v38
	s_waitcnt lgkmcnt(0)
	v_fma_f32 v42, -v16, v50, v38
	ds_read_b128 v[38:41], v3 offset:61264
	v_fma_f32 v42, -v17, v51, v42
	v_fma_f32 v42, -v18, v52, v42
	v_fma_f32 v46, -v19, v53, v42
	ds_read_b128 v[42:45], v3 offset:61280
	s_waitcnt lgkmcnt(1)
	v_fma_f32 v38, -v20, v38, v46
	v_fma_f32 v38, -v21, v39, v38
	v_fma_f32 v38, -v22, v40, v38
	v_fma_f32 v38, -v23, v41, v38
	s_waitcnt lgkmcnt(0)
	v_fma_f32 v42, -v24, v42, v38
	ds_read_b128 v[38:41], v3 offset:61296
	v_fma_f32 v42, -v25, v43, v42
	v_fma_f32 v42, -v26, v44, v42
	v_fma_f32 v46, -v27, v45, v42
	ds_read_b128 v[42:45], v3 offset:61312
	s_waitcnt lgkmcnt(1)
	v_fma_f32 v38, -v28, v38, v46
	v_fma_f32 v38, -v29, v39, v38
	v_fma_f32 v38, -v30, v40, v38
	v_fma_f32 v46, -v31, v41, v38
	ds_read_b128 v[38:41], v3 offset:61328
	s_waitcnt lgkmcnt(1)
	v_fma_f32 v3, -v32, v42, v46
	v_fma_f32 v3, -v33, v43, v3
	v_fma_f32 v3, -v35, v44, v3
	v_fma_f32 v3, -v36, v45, v3
	s_waitcnt lgkmcnt(0)
	v_fma_f32 v38, -v37, v38, v3
	v_fmac_f32_e32 v38, 0x80000000, v39
	v_fmac_f32_e32 v38, 0x80000000, v40
	v_fmac_f32_e32 v38, 0x80000000, v41
	ds_read_u16 v40, v2 offset:9248
	v_lshlrev_b32_e32 v3, 2, v0
	v_add_u32_e32 v39, s0, v3
	ds_read2_b32 v[44:45], v39 offset0:34 offset1:98
	v_add_u32_e32 v3, 32, v3
	s_waitcnt lgkmcnt(0)
	v_mul_f32_e32 v39, 0x3fb8aa3b, v45
	v_lshlrev_b32_e32 v45, 16, v40
	ds_read_b128 v[40:43], v3 offset:61472
	v_exp_f32_e32 v39, v39
	v_mul_f32_e32 v56, v44, v45
	ds_read_b128 v[44:47], v3 offset:61488
	ds_read_b128 v[48:51], v3 offset:61504
	ds_read_b128 v[52:55], v3 offset:61520
	v_cndmask_b32_e64 v39, v39, 1.0, vcc
	s_waitcnt lgkmcnt(3)
; DEVI float bf2f(bf16_t b) { return __uint_as_float(((unsigned)b) << 16); }
; DEVI void prep_item(const Params& p, int j, int n, int h, char* smem) {
;     ...
; #pragma unroll
;     for (int i = 0; i < 64; ++i) {
;       const float* amz = am + zero;
;       const float* sbz = sbeta + zero;
;       const float eg = __expf(sbz[64 + i]);
;       float acc = bf2f(*(const unsigned short*)(src + i * 272)) * sbz[i] * (isu ? 1.0f : eg);
; #pragma unroll
;       for (int j4 = 0; j4 < (i + 3) / 4; ++j4) {
;         const f32x4 a = *(const f32x4*)(amz + i * 68 + j4 * 4);
;         acc -= a[0] * x[j4 * 4 + 0];
;         acc -= a[1] * x[j4 * 4 + 1];
;         acc -= a[2] * x[j4 * 4 + 2];
;         acc -= a[3] * x[j4 * 4 + 3];
;       }
;       asm volatile("" : "+v"(zero), "+v"(acc));
;       x[i] = acc;
;     }
	v_mul_f32_e32 v40, v4, v40
	v_fma_f32 v39, v39, v56, -v40
	v_fma_f32 v39, -v5, v41, v39
	v_fma_f32 v39, -v6, v42, v39
	v_fma_f32 v39, -v7, v43, v39
	s_waitcnt lgkmcnt(2)
	v_fma_f32 v39, -v8, v44, v39
	v_fma_f32 v39, -v9, v45, v39
	v_fma_f32 v39, -v10, v46, v39
	v_fma_f32 v39, -v11, v47, v39
	s_waitcnt lgkmcnt(1)
	v_fma_f32 v39, -v12, v48, v39
	v_fma_f32 v39, -v13, v49, v39
	v_fma_f32 v39, -v14, v50, v39
	v_fma_f32 v39, -v15, v51, v39
	ds_read_b128 v[40:43], v3 offset:61536
	s_waitcnt lgkmcnt(1)
	v_fma_f32 v39, -v16, v52, v39
	v_fma_f32 v39, -v17, v53, v39
	v_fma_f32 v39, -v18, v54, v39
	v_fma_f32 v39, -v19, v55, v39
	ds_read_b128 v[44:47], v3 offset:61552
	s_waitcnt lgkmcnt(1)
	v_fma_f32 v39, -v20, v40, v39
	v_fma_f32 v39, -v21, v41, v39
	v_fma_f32 v39, -v22, v42, v39
	v_fma_f32 v39, -v23, v43, v39
	ds_read_b128 v[40:43], v3 offset:61568
	s_waitcnt lgkmcnt(1)
	v_fma_f32 v39, -v24, v44, v39
	v_fma_f32 v39, -v25, v45, v39
	v_fma_f32 v39, -v26, v46, v39
	v_fma_f32 v39, -v27, v47, v39
	ds_read_b128 v[44:47], v3 offset:61584
	s_waitcnt lgkmcnt(1)
	v_fma_f32 v39, -v28, v40, v39
	v_fma_f32 v39, -v29, v41, v39
	v_fma_f32 v39, -v30, v42, v39
	v_fma_f32 v39, -v31, v43, v39
	ds_read_b128 v[40:43], v3 offset:61600
	s_waitcnt lgkmcnt(1)
	v_fma_f32 v3, -v32, v44, v39
	v_fma_f32 v3, -v33, v45, v3
	v_fma_f32 v3, -v35, v46, v3
	v_fma_f32 v3, -v36, v47, v3
	s_waitcnt lgkmcnt(0)
	v_fma_f32 v3, -v37, v40, v3
	v_fma_f32 v39, -v38, v41, v3
	v_fmac_f32_e32 v39, 0x80000000, v42
	v_fmac_f32_e32 v39, 0x80000000, v43
	ds_read_u16 v41, v2 offset:9520
	v_lshlrev_b32_e32 v3, 2, v0
	v_add_u32_e32 v40, s0, v3
	ds_read2_b32 v[44:45], v40 offset0:35 offset1:99
	v_add_u32_e32 v3, 32, v3
	s_waitcnt lgkmcnt(0)
	v_mul_f32_e32 v40, 0x3fb8aa3b, v45
	v_exp_f32_e32 v40, v40
	v_lshlrev_b32_e32 v45, 16, v41
	v_mul_f32_e32 v57, v44, v45
	v_cndmask_b32_e64 v56, v40, 1.0, vcc
	ds_read_b128 v[40:43], v3 offset:61744
	ds_read_b128 v[44:47], v3 offset:61760
	ds_read_b128 v[48:51], v3 offset:61776
	ds_read_b128 v[52:55], v3 offset:61792
	s_waitcnt lgkmcnt(3)
	v_mul_f32_e32 v40, v4, v40
	v_fma_f32 v40, v56, v57, -v40
	v_fma_f32 v40, -v5, v41, v40
	v_fma_f32 v40, -v6, v42, v40
	v_fma_f32 v40, -v7, v43, v40
	s_waitcnt lgkmcnt(2)
	v_fma_f32 v40, -v8, v44, v40
	v_fma_f32 v40, -v9, v45, v40
	v_fma_f32 v40, -v10, v46, v40
	v_fma_f32 v40, -v11, v47, v40
	s_waitcnt lgkmcnt(1)
	v_fma_f32 v40, -v12, v48, v40
	v_fma_f32 v40, -v13, v49, v40
	v_fma_f32 v40, -v14, v50, v40
	v_fma_f32 v40, -v15, v51, v40
	s_waitcnt lgkmcnt(0)
	v_fma_f32 v44, -v16, v52, v40
	ds_read_b128 v[40:43], v3 offset:61808
	v_fma_f32 v44, -v17, v53, v44
	v_fma_f32 v44, -v18, v54, v44
	v_fma_f32 v48, -v19, v55, v44
	ds_read_b128 v[44:47], v3 offset:61824
	s_waitcnt lgkmcnt(1)
	v_fma_f32 v40, -v20, v40, v48
	v_fma_f32 v40, -v21, v41, v40
	v_fma_f32 v40, -v22, v42, v40
	v_fma_f32 v40, -v23, v43, v40
	s_waitcnt lgkmcnt(0)
	v_fma_f32 v44, -v24, v44, v40
	ds_read_b128 v[40:43], v3 offset:61840
	v_fma_f32 v44, -v25, v45, v44
	v_fma_f32 v44, -v26, v46, v44
	v_fma_f32 v48, -v27, v47, v44
	ds_read_b128 v[44:47], v3 offset:61856
	s_waitcnt lgkmcnt(1)
	v_fma_f32 v40, -v28, v40, v48
	v_fma_f32 v40, -v29, v41, v40
	v_fma_f32 v40, -v30, v42, v40
	v_fma_f32 v48, -v31, v43, v40
	ds_read_b128 v[40:43], v3 offset:61872
	s_waitcnt lgkmcnt(1)
	v_fma_f32 v3, -v32, v44, v48
	v_fma_f32 v3, -v33, v45, v3
	v_fma_f32 v3, -v35, v46, v3
	v_fma_f32 v3, -v36, v47, v3
	s_waitcnt lgkmcnt(0)
	v_fma_f32 v3, -v37, v40, v3
	v_fma_f32 v3, -v38, v41, v3
	v_fma_f32 v40, -v39, v42, v3
	v_fmac_f32_e32 v40, 0x80000000, v43
	ds_read_u16 v42, v2 offset:9792
	v_lshlrev_b32_e32 v3, 2, v0
	v_add_u32_e32 v41, s0, v3
	ds_read2_b32 v[46:47], v41 offset0:36 offset1:100
	v_add_u32_e32 v3, 32, v3
	s_waitcnt lgkmcnt(0)
	v_mul_f32_e32 v41, 0x3fb8aa3b, v47
	v_lshlrev_b32_e32 v47, 16, v42
	ds_read_b128 v[42:45], v3 offset:62016
	v_exp_f32_e32 v41, v41
	v_mul_f32_e32 v58, v46, v47
	ds_read_b128 v[46:49], v3 offset:62032
	ds_read_b128 v[50:53], v3 offset:62048
	ds_read_b128 v[54:57], v3 offset:62064
	v_cndmask_b32_e64 v41, v41, 1.0, vcc
	s_waitcnt lgkmcnt(3)
	v_mul_f32_e32 v42, v4, v42
	v_fma_f32 v41, v41, v58, -v42
	v_fma_f32 v41, -v5, v43, v41
	v_fma_f32 v41, -v6, v44, v41
	v_fma_f32 v41, -v7, v45, v41
	s_waitcnt lgkmcnt(2)
	v_fma_f32 v41, -v8, v46, v41
	v_fma_f32 v41, -v9, v47, v41
	v_fma_f32 v41, -v10, v48, v41
	v_fma_f32 v41, -v11, v49, v41
	s_waitcnt lgkmcnt(1)
	v_fma_f32 v41, -v12, v50, v41
	v_fma_f32 v41, -v13, v51, v41
	v_fma_f32 v41, -v14, v52, v41
	v_fma_f32 v41, -v15, v53, v41
	ds_read_b128 v[42:45], v3 offset:62080
	s_waitcnt lgkmcnt(1)
	v_fma_f32 v41, -v16, v54, v41
	v_fma_f32 v41, -v17, v55, v41
	v_fma_f32 v41, -v18, v56, v41
	v_fma_f32 v41, -v19, v57, v41
	ds_read_b128 v[46:49], v3 offset:62096
	s_waitcnt lgkmcnt(1)
	v_fma_f32 v41, -v20, v42, v41
	v_fma_f32 v41, -v21, v43, v41
	v_fma_f32 v41, -v22, v44, v41
	v_fma_f32 v41, -v23, v45, v41
	ds_read_b128 v[42:45], v3 offset:62112
	s_waitcnt lgkmcnt(1)
	v_fma_f32 v41, -v24, v46, v41
	v_fma_f32 v41, -v25, v47, v41
	v_fma_f32 v41, -v26, v48, v41
	v_fma_f32 v41, -v27, v49, v41
	ds_read_b128 v[46:49], v3 offset:62128
	s_waitcnt lgkmcnt(1)
	v_fma_f32 v41, -v28, v42, v41
	v_fma_f32 v41, -v29, v43, v41
	v_fma_f32 v41, -v30, v44, v41
	v_fma_f32 v41, -v31, v45, v41
	ds_read_b128 v[42:45], v3 offset:62144
	s_waitcnt lgkmcnt(1)
	v_fma_f32 v3, -v32, v46, v41
	v_fma_f32 v3, -v33, v47, v3
	v_fma_f32 v3, -v35, v48, v3
	v_fma_f32 v3, -v36, v49, v3
	s_waitcnt lgkmcnt(0)
	v_fma_f32 v3, -v37, v42, v3
	v_fma_f32 v3, -v38, v43, v3
	v_fma_f32 v3, -v39, v44, v3
	v_fma_f32 v41, -v40, v45, v3
	ds_read_u16 v43, v2 offset:10064
	v_lshlrev_b32_e32 v3, 2, v0
	v_add_u32_e32 v42, s0, v3
	ds_read2_b32 v[46:47], v42 offset0:37 offset1:101
	v_add_u32_e32 v3, 32, v3
	s_waitcnt lgkmcnt(0)
; DEVI float bf2f(bf16_t b) { return __uint_as_float(((unsigned)b) << 16); }
; DEVI void prep_item(const Params& p, int j, int n, int h, char* smem) {
;     ...
; #pragma unroll
;     for (int i = 0; i < 64; ++i) {
;       const float* amz = am + zero;
;       const float* sbz = sbeta + zero;
;       const float eg = __expf(sbz[64 + i]);
;       float acc = bf2f(*(const unsigned short*)(src + i * 272)) * sbz[i] * (isu ? 1.0f : eg);
; #pragma unroll
;       for (int j4 = 0; j4 < (i + 3) / 4; ++j4) {
;         const f32x4 a = *(const f32x4*)(amz + i * 68 + j4 * 4);
;         acc -= a[0] * x[j4 * 4 + 0];
;         acc -= a[1] * x[j4 * 4 + 1];
;         acc -= a[2] * x[j4 * 4 + 2];
;         acc -= a[3] * x[j4 * 4 + 3];
;       }
;       asm volatile("" : "+v"(zero), "+v"(acc));
;       x[i] = acc;
;     }
	v_mul_f32_e32 v42, 0x3fb8aa3b, v47
	v_exp_f32_e32 v42, v42
	v_lshlrev_b32_e32 v47, 16, v43
	v_mul_f32_e32 v59, v46, v47
	v_cndmask_b32_e64 v58, v42, 1.0, vcc
	ds_read_b128 v[42:45], v3 offset:62288
	ds_read_b128 v[46:49], v3 offset:62304
	ds_read_b128 v[50:53], v3 offset:62320
	ds_read_b128 v[54:57], v3 offset:62336
	s_waitcnt lgkmcnt(3)
	v_mul_f32_e32 v42, v4, v42
	v_fma_f32 v42, v58, v59, -v42
	v_fma_f32 v42, -v5, v43, v42
	v_fma_f32 v42, -v6, v44, v42
	v_fma_f32 v42, -v7, v45, v42
	s_waitcnt lgkmcnt(2)
	v_fma_f32 v42, -v8, v46, v42
	v_fma_f32 v42, -v9, v47, v42
	v_fma_f32 v42, -v10, v48, v42
	v_fma_f32 v42, -v11, v49, v42
	s_waitcnt lgkmcnt(1)
	v_fma_f32 v42, -v12, v50, v42
	v_fma_f32 v42, -v13, v51, v42
	v_fma_f32 v42, -v14, v52, v42
	v_fma_f32 v42, -v15, v53, v42
	s_waitcnt lgkmcnt(0)
	v_fma_f32 v46, -v16, v54, v42
	ds_read_b128 v[42:45], v3 offset:62352
	v_fma_f32 v46, -v17, v55, v46
	v_fma_f32 v46, -v18, v56, v46
	v_fma_f32 v50, -v19, v57, v46
	ds_read_b128 v[46:49], v3 offset:62368
	s_waitcnt lgkmcnt(1)
	v_fma_f32 v42, -v20, v42, v50
	v_fma_f32 v42, -v21, v43, v42
	v_fma_f32 v42, -v22, v44, v42
	v_fma_f32 v42, -v23, v45, v42
	s_waitcnt lgkmcnt(0)
	v_fma_f32 v46, -v24, v46, v42
	ds_read_b128 v[42:45], v3 offset:62384
	v_fma_f32 v46, -v25, v47, v46
	v_fma_f32 v46, -v26, v48, v46
	v_fma_f32 v50, -v27, v49, v46
	ds_read_b128 v[46:49], v3 offset:62400
	s_waitcnt lgkmcnt(1)
	v_fma_f32 v42, -v28, v42, v50
	v_fma_f32 v42, -v29, v43, v42
	v_fma_f32 v42, -v30, v44, v42
	v_fma_f32 v42, -v31, v45, v42
	s_waitcnt lgkmcnt(0)
	v_fma_f32 v46, -v32, v46, v42
	ds_read_b128 v[42:45], v3 offset:62416
	v_fma_f32 v46, -v33, v47, v46
	v_fma_f32 v46, -v35, v48, v46
	v_fma_f32 v50, -v36, v49, v46
	ds_read_b128 v[46:49], v3 offset:62432
	s_waitcnt lgkmcnt(1)
	v_fma_f32 v3, -v37, v42, v50
	v_fma_f32 v3, -v38, v43, v3
	v_fma_f32 v3, -v39, v44, v3
	v_fma_f32 v3, -v40, v45, v3
	s_waitcnt lgkmcnt(0)
	v_fma_f32 v42, -v41, v46, v3
	v_fmac_f32_e32 v42, 0x80000000, v47
	v_fmac_f32_e32 v42, 0x80000000, v48
	v_fmac_f32_e32 v42, 0x80000000, v49
	ds_read_u16 v44, v2 offset:10336
	v_lshlrev_b32_e32 v3, 2, v0
	v_add_u32_e32 v43, s0, v3
	ds_read2_b32 v[48:49], v43 offset0:38 offset1:102
	v_add_u32_e32 v3, 32, v3
	s_waitcnt lgkmcnt(0)
	v_mul_f32_e32 v43, 0x3fb8aa3b, v49
	v_lshlrev_b32_e32 v49, 16, v44
	ds_read_b128 v[44:47], v3 offset:62560
	v_exp_f32_e32 v43, v43
	v_mul_f32_e32 v60, v48, v49
	ds_read_b128 v[48:51], v3 offset:62576
	ds_read_b128 v[52:55], v3 offset:62592
	ds_read_b128 v[56:59], v3 offset:62608
	v_cndmask_b32_e64 v43, v43, 1.0, vcc
	s_waitcnt lgkmcnt(3)
	v_mul_f32_e32 v44, v4, v44
	v_fma_f32 v43, v43, v60, -v44
	v_fma_f32 v43, -v5, v45, v43
	v_fma_f32 v43, -v6, v46, v43
	v_fma_f32 v43, -v7, v47, v43
	s_waitcnt lgkmcnt(2)
	v_fma_f32 v43, -v8, v48, v43
	v_fma_f32 v43, -v9, v49, v43
	v_fma_f32 v43, -v10, v50, v43
	v_fma_f32 v43, -v11, v51, v43
	s_waitcnt lgkmcnt(1)
	v_fma_f32 v43, -v12, v52, v43
	v_fma_f32 v43, -v13, v53, v43
	v_fma_f32 v43, -v14, v54, v43
	v_fma_f32 v43, -v15, v55, v43
	ds_read_b128 v[44:47], v3 offset:62624
	s_waitcnt lgkmcnt(1)
	v_fma_f32 v43, -v16, v56, v43
	v_fma_f32 v43, -v17, v57, v43
	v_fma_f32 v43, -v18, v58, v43
	v_fma_f32 v43, -v19, v59, v43
	ds_read_b128 v[48:51], v3 offset:62640
	s_waitcnt lgkmcnt(1)
	v_fma_f32 v43, -v20, v44, v43
	v_fma_f32 v43, -v21, v45, v43
	v_fma_f32 v43, -v22, v46, v43
	v_fma_f32 v43, -v23, v47, v43
	ds_read_b128 v[44:47], v3 offset:62656
	s_waitcnt lgkmcnt(1)
	v_fma_f32 v43, -v24, v48, v43
	v_fma_f32 v43, -v25, v49, v43
	v_fma_f32 v43, -v26, v50, v43
	v_fma_f32 v43, -v27, v51, v43
	ds_read_b128 v[48:51], v3 offset:62672
	s_waitcnt lgkmcnt(1)
	v_fma_f32 v43, -v28, v44, v43
	v_fma_f32 v43, -v29, v45, v43
	v_fma_f32 v43, -v30, v46, v43
	v_fma_f32 v43, -v31, v47, v43
	ds_read_b128 v[44:47], v3 offset:62688
	s_waitcnt lgkmcnt(1)
	v_fma_f32 v43, -v32, v48, v43
	v_fma_f32 v43, -v33, v49, v43
	v_fma_f32 v43, -v35, v50, v43
	v_fma_f32 v43, -v36, v51, v43
	ds_read_b128 v[48:51], v3 offset:62704
	s_waitcnt lgkmcnt(1)
	v_fma_f32 v3, -v37, v44, v43
	v_fma_f32 v3, -v38, v45, v3
	v_fma_f32 v3, -v39, v46, v3
	v_fma_f32 v3, -v40, v47, v3
	s_waitcnt lgkmcnt(0)
	v_fma_f32 v3, -v41, v48, v3
	v_fma_f32 v43, -v42, v49, v3
	v_fmac_f32_e32 v43, 0x80000000, v50
	v_fmac_f32_e32 v43, 0x80000000, v51
	ds_read_u16 v45, v2 offset:10608
	v_lshlrev_b32_e32 v3, 2, v0
	v_add_u32_e32 v44, s0, v3
	ds_read2_b32 v[48:49], v44 offset0:39 offset1:103
	v_add_u32_e32 v3, 32, v3
	s_waitcnt lgkmcnt(0)
	v_mul_f32_e32 v44, 0x3fb8aa3b, v49
	v_exp_f32_e32 v44, v44
	v_lshlrev_b32_e32 v49, 16, v45
	v_mul_f32_e32 v61, v48, v49
	v_cndmask_b32_e64 v60, v44, 1.0, vcc
	ds_read_b128 v[44:47], v3 offset:62832
	ds_read_b128 v[48:51], v3 offset:62848
	ds_read_b128 v[52:55], v3 offset:62864
	ds_read_b128 v[56:59], v3 offset:62880
	s_waitcnt lgkmcnt(3)
	v_mul_f32_e32 v44, v4, v44
	v_fma_f32 v44, v60, v61, -v44
	v_fma_f32 v44, -v5, v45, v44
	v_fma_f32 v44, -v6, v46, v44
	v_fma_f32 v44, -v7, v47, v44
	s_waitcnt lgkmcnt(2)
	v_fma_f32 v44, -v8, v48, v44
	v_fma_f32 v44, -v9, v49, v44
	v_fma_f32 v44, -v10, v50, v44
	v_fma_f32 v44, -v11, v51, v44
	s_waitcnt lgkmcnt(1)
	v_fma_f32 v44, -v12, v52, v44
	v_fma_f32 v44, -v13, v53, v44
	v_fma_f32 v44, -v14, v54, v44
	v_fma_f32 v44, -v15, v55, v44
	s_waitcnt lgkmcnt(0)
	v_fma_f32 v48, -v16, v56, v44
	ds_read_b128 v[44:47], v3 offset:62896
	v_fma_f32 v48, -v17, v57, v48
	v_fma_f32 v48, -v18, v58, v48
	v_fma_f32 v52, -v19, v59, v48
	ds_read_b128 v[48:51], v3 offset:62912
	s_waitcnt lgkmcnt(1)
	v_fma_f32 v44, -v20, v44, v52
	v_fma_f32 v44, -v21, v45, v44
	v_fma_f32 v44, -v22, v46, v44
	v_fma_f32 v44, -v23, v47, v44
	s_waitcnt lgkmcnt(0)
; DEVI float bf2f(bf16_t b) { return __uint_as_float(((unsigned)b) << 16); }
; DEVI void prep_item(const Params& p, int j, int n, int h, char* smem) {
;     ...
; #pragma unroll
;     for (int i = 0; i < 64; ++i) {
;       const float* amz = am + zero;
;       const float* sbz = sbeta + zero;
;       const float eg = __expf(sbz[64 + i]);
;       float acc = bf2f(*(const unsigned short*)(src + i * 272)) * sbz[i] * (isu ? 1.0f : eg);
; #pragma unroll
;       for (int j4 = 0; j4 < (i + 3) / 4; ++j4) {
;         const f32x4 a = *(const f32x4*)(amz + i * 68 + j4 * 4);
;         acc -= a[0] * x[j4 * 4 + 0];
;         acc -= a[1] * x[j4 * 4 + 1];
;         acc -= a[2] * x[j4 * 4 + 2];
;         acc -= a[3] * x[j4 * 4 + 3];
;       }
;       asm volatile("" : "+v"(zero), "+v"(acc));
;       x[i] = acc;
;     }
	v_fma_f32 v48, -v24, v48, v44
	ds_read_b128 v[44:47], v3 offset:62928
	v_fma_f32 v48, -v25, v49, v48
	v_fma_f32 v48, -v26, v50, v48
	v_fma_f32 v52, -v27, v51, v48
	ds_read_b128 v[48:51], v3 offset:62944
	s_waitcnt lgkmcnt(1)
	v_fma_f32 v44, -v28, v44, v52
	v_fma_f32 v44, -v29, v45, v44
	v_fma_f32 v44, -v30, v46, v44
	v_fma_f32 v44, -v31, v47, v44
	s_waitcnt lgkmcnt(0)
	v_fma_f32 v48, -v32, v48, v44
	ds_read_b128 v[44:47], v3 offset:62960
	v_fma_f32 v48, -v33, v49, v48
	v_fma_f32 v48, -v35, v50, v48
	v_fma_f32 v52, -v36, v51, v48
	ds_read_b128 v[48:51], v3 offset:62976
	s_waitcnt lgkmcnt(1)
	v_fma_f32 v3, -v37, v44, v52
	v_fma_f32 v3, -v38, v45, v3
	v_fma_f32 v3, -v39, v46, v3
	v_fma_f32 v3, -v40, v47, v3
	s_waitcnt lgkmcnt(0)
	v_fma_f32 v3, -v41, v48, v3
	v_fma_f32 v3, -v42, v49, v3
	v_fma_f32 v44, -v43, v50, v3
	v_fmac_f32_e32 v44, 0x80000000, v51
	ds_read_u16 v46, v2 offset:10880
	v_lshlrev_b32_e32 v3, 2, v0
	v_add_u32_e32 v45, s0, v3
	ds_read2_b32 v[50:51], v45 offset0:40 offset1:104
	v_add_u32_e32 v3, 32, v3
	s_waitcnt lgkmcnt(0)
	v_mul_f32_e32 v45, 0x3fb8aa3b, v51
	v_lshlrev_b32_e32 v51, 16, v46
	ds_read_b128 v[46:49], v3 offset:63104
	v_exp_f32_e32 v45, v45
	v_mul_f32_e32 v62, v50, v51
	ds_read_b128 v[50:53], v3 offset:63120
	ds_read_b128 v[54:57], v3 offset:63136
	ds_read_b128 v[58:61], v3 offset:63152
	v_cndmask_b32_e64 v45, v45, 1.0, vcc
	s_waitcnt lgkmcnt(3)
	v_mul_f32_e32 v46, v4, v46
	v_fma_f32 v45, v45, v62, -v46
	v_fma_f32 v45, -v5, v47, v45
	v_fma_f32 v45, -v6, v48, v45
	v_fma_f32 v45, -v7, v49, v45
	s_waitcnt lgkmcnt(2)
	v_fma_f32 v45, -v8, v50, v45
	v_fma_f32 v45, -v9, v51, v45
	v_fma_f32 v45, -v10, v52, v45
	v_fma_f32 v45, -v11, v53, v45
	s_waitcnt lgkmcnt(1)
	v_fma_f32 v45, -v12, v54, v45
	v_fma_f32 v45, -v13, v55, v45
	v_fma_f32 v45, -v14, v56, v45
	v_fma_f32 v45, -v15, v57, v45
	ds_read_b128 v[46:49], v3 offset:63168
	s_waitcnt lgkmcnt(1)
	v_fma_f32 v45, -v16, v58, v45
	v_fma_f32 v45, -v17, v59, v45
	v_fma_f32 v45, -v18, v60, v45
	v_fma_f32 v45, -v19, v61, v45
	ds_read_b128 v[50:53], v3 offset:63184
	s_waitcnt lgkmcnt(1)
	v_fma_f32 v45, -v20, v46, v45
	v_fma_f32 v45, -v21, v47, v45
	v_fma_f32 v45, -v22, v48, v45
	v_fma_f32 v45, -v23, v49, v45
	ds_read_b128 v[46:49], v3 offset:63200
	s_waitcnt lgkmcnt(1)
	v_fma_f32 v45, -v24, v50, v45
	v_fma_f32 v45, -v25, v51, v45
	v_fma_f32 v45, -v26, v52, v45
	v_fma_f32 v45, -v27, v53, v45
	ds_read_b128 v[50:53], v3 offset:63216
	s_waitcnt lgkmcnt(1)
	v_fma_f32 v45, -v28, v46, v45
	v_fma_f32 v45, -v29, v47, v45
	v_fma_f32 v45, -v30, v48, v45
	v_fma_f32 v45, -v31, v49, v45
	ds_read_b128 v[46:49], v3 offset:63232
	s_waitcnt lgkmcnt(1)
	v_fma_f32 v45, -v32, v50, v45
	v_fma_f32 v45, -v33, v51, v45
	v_fma_f32 v45, -v35, v52, v45
	v_fma_f32 v45, -v36, v53, v45
	ds_read_b128 v[50:53], v3 offset:63248
	s_waitcnt lgkmcnt(1)
	v_fma_f32 v3, -v37, v46, v45
	v_fma_f32 v3, -v38, v47, v3
	v_fma_f32 v3, -v39, v48, v3
	v_fma_f32 v3, -v40, v49, v3
	s_waitcnt lgkmcnt(0)
	v_fma_f32 v3, -v41, v50, v3
	v_fma_f32 v3, -v42, v51, v3
	v_fma_f32 v3, -v43, v52, v3
	v_fma_f32 v45, -v44, v53, v3
	ds_read_u16 v47, v2 offset:11152
	v_lshlrev_b32_e32 v3, 2, v0
	v_add_u32_e32 v46, s0, v3
	ds_read2_b32 v[50:51], v46 offset0:41 offset1:105
	v_add_u32_e32 v3, 32, v3
	s_waitcnt lgkmcnt(0)
	v_mul_f32_e32 v46, 0x3fb8aa3b, v51
	v_exp_f32_e32 v46, v46
	v_lshlrev_b32_e32 v51, 16, v47
	v_mul_f32_e32 v63, v50, v51
	v_cndmask_b32_e64 v62, v46, 1.0, vcc
	ds_read_b128 v[46:49], v3 offset:63376
	ds_read_b128 v[50:53], v3 offset:63392
	ds_read_b128 v[54:57], v3 offset:63408
	ds_read_b128 v[58:61], v3 offset:63424
	s_waitcnt lgkmcnt(3)
	v_mul_f32_e32 v46, v4, v46
	v_fma_f32 v46, v62, v63, -v46
	v_fma_f32 v46, -v5, v47, v46
	v_fma_f32 v46, -v6, v48, v46
	v_fma_f32 v46, -v7, v49, v46
	s_waitcnt lgkmcnt(2)
	v_fma_f32 v46, -v8, v50, v46
	v_fma_f32 v46, -v9, v51, v46
	v_fma_f32 v46, -v10, v52, v46
	v_fma_f32 v46, -v11, v53, v46
	s_waitcnt lgkmcnt(1)
	v_fma_f32 v46, -v12, v54, v46
	v_fma_f32 v46, -v13, v55, v46
	v_fma_f32 v46, -v14, v56, v46
	v_fma_f32 v46, -v15, v57, v46
	s_waitcnt lgkmcnt(0)
	v_fma_f32 v50, -v16, v58, v46
	ds_read_b128 v[46:49], v3 offset:63440
	v_fma_f32 v50, -v17, v59, v50
	v_fma_f32 v50, -v18, v60, v50
	v_fma_f32 v54, -v19, v61, v50
	ds_read_b128 v[50:53], v3 offset:63456
	s_waitcnt lgkmcnt(1)
	v_fma_f32 v46, -v20, v46, v54
	v_fma_f32 v46, -v21, v47, v46
	v_fma_f32 v46, -v22, v48, v46
	v_fma_f32 v46, -v23, v49, v46
	s_waitcnt lgkmcnt(0)
	v_fma_f32 v50, -v24, v50, v46
	ds_read_b128 v[46:49], v3 offset:63472
	v_fma_f32 v50, -v25, v51, v50
	v_fma_f32 v50, -v26, v52, v50
	v_fma_f32 v54, -v27, v53, v50
	ds_read_b128 v[50:53], v3 offset:63488
	s_waitcnt lgkmcnt(1)
	v_fma_f32 v46, -v28, v46, v54
	v_fma_f32 v46, -v29, v47, v46
	v_fma_f32 v46, -v30, v48, v46
	v_fma_f32 v46, -v31, v49, v46
	s_waitcnt lgkmcnt(0)
	v_fma_f32 v50, -v32, v50, v46
	ds_read_b128 v[46:49], v3 offset:63504
	v_fma_f32 v50, -v33, v51, v50
	v_fma_f32 v50, -v35, v52, v50
	v_fma_f32 v54, -v36, v53, v50
	ds_read_b128 v[50:53], v3 offset:63520
	s_waitcnt lgkmcnt(1)
	v_fma_f32 v46, -v37, v46, v54
	v_fma_f32 v46, -v38, v47, v46
	v_fma_f32 v46, -v39, v48, v46
	v_fma_f32 v54, -v40, v49, v46
	ds_read_b128 v[46:49], v3 offset:63536
	s_waitcnt lgkmcnt(1)
	v_fma_f32 v3, -v41, v50, v54
	v_fma_f32 v3, -v42, v51, v3
	v_fma_f32 v3, -v43, v52, v3
	v_fma_f32 v3, -v44, v53, v3
	s_waitcnt lgkmcnt(0)
	v_fma_f32 v46, -v45, v46, v3
	v_fmac_f32_e32 v46, 0x80000000, v47
	v_fmac_f32_e32 v46, 0x80000000, v48
	v_fmac_f32_e32 v46, 0x80000000, v49
	ds_read_u16 v48, v2 offset:11424
	v_lshlrev_b32_e32 v3, 2, v0
	v_add_u32_e32 v47, s0, v3
	ds_read2_b32 v[52:53], v47 offset0:42 offset1:106
	v_add_u32_e32 v3, 32, v3
	s_waitcnt lgkmcnt(0)
; DEVI float bf2f(bf16_t b) { return __uint_as_float(((unsigned)b) << 16); }
; DEVI void prep_item(const Params& p, int j, int n, int h, char* smem) {
;     ...
; #pragma unroll
;     for (int i = 0; i < 64; ++i) {
;       const float* amz = am + zero;
;       const float* sbz = sbeta + zero;
;       const float eg = __expf(sbz[64 + i]);
;       float acc = bf2f(*(const unsigned short*)(src + i * 272)) * sbz[i] * (isu ? 1.0f : eg);
; #pragma unroll
;       for (int j4 = 0; j4 < (i + 3) / 4; ++j4) {
;         const f32x4 a = *(const f32x4*)(amz + i * 68 + j4 * 4);
;         acc -= a[0] * x[j4 * 4 + 0];
;         acc -= a[1] * x[j4 * 4 + 1];
;         acc -= a[2] * x[j4 * 4 + 2];
;         acc -= a[3] * x[j4 * 4 + 3];
;       }
;       asm volatile("" : "+v"(zero), "+v"(acc));
;       x[i] = acc;
;     }
	v_mul_f32_e32 v47, 0x3fb8aa3b, v53
	v_lshlrev_b32_e32 v53, 16, v48
	ds_read_b128 v[48:51], v3 offset:63648
	v_exp_f32_e32 v47, v47
	v_mul_f32_e32 v64, v52, v53
	ds_read_b128 v[52:55], v3 offset:63664
	ds_read_b128 v[56:59], v3 offset:63680
	ds_read_b128 v[60:63], v3 offset:63696
	v_cndmask_b32_e64 v47, v47, 1.0, vcc
	s_waitcnt lgkmcnt(3)
	v_mul_f32_e32 v48, v4, v48
	v_fma_f32 v47, v47, v64, -v48
	v_fma_f32 v47, -v5, v49, v47
	v_fma_f32 v47, -v6, v50, v47
	v_fma_f32 v47, -v7, v51, v47
	s_waitcnt lgkmcnt(2)
	v_fma_f32 v47, -v8, v52, v47
	v_fma_f32 v47, -v9, v53, v47
	v_fma_f32 v47, -v10, v54, v47
	v_fma_f32 v47, -v11, v55, v47
	s_waitcnt lgkmcnt(1)
	v_fma_f32 v47, -v12, v56, v47
	v_fma_f32 v47, -v13, v57, v47
	v_fma_f32 v47, -v14, v58, v47
	v_fma_f32 v47, -v15, v59, v47
	ds_read_b128 v[48:51], v3 offset:63712
	s_waitcnt lgkmcnt(1)
	v_fma_f32 v47, -v16, v60, v47
	v_fma_f32 v47, -v17, v61, v47
	v_fma_f32 v47, -v18, v62, v47
	v_fma_f32 v47, -v19, v63, v47
	ds_read_b128 v[52:55], v3 offset:63728
	s_waitcnt lgkmcnt(1)
	v_fma_f32 v47, -v20, v48, v47
	v_fma_f32 v47, -v21, v49, v47
	v_fma_f32 v47, -v22, v50, v47
	v_fma_f32 v47, -v23, v51, v47
	ds_read_b128 v[48:51], v3 offset:63744
	s_waitcnt lgkmcnt(1)
	v_fma_f32 v47, -v24, v52, v47
	v_fma_f32 v47, -v25, v53, v47
	v_fma_f32 v47, -v26, v54, v47
	v_fma_f32 v47, -v27, v55, v47
	ds_read_b128 v[52:55], v3 offset:63760
	s_waitcnt lgkmcnt(1)
	v_fma_f32 v47, -v28, v48, v47
	v_fma_f32 v47, -v29, v49, v47
	v_fma_f32 v47, -v30, v50, v47
	v_fma_f32 v47, -v31, v51, v47
	ds_read_b128 v[48:51], v3 offset:63776
	s_waitcnt lgkmcnt(1)
	v_fma_f32 v47, -v32, v52, v47
	v_fma_f32 v47, -v33, v53, v47
	v_fma_f32 v47, -v35, v54, v47
	v_fma_f32 v47, -v36, v55, v47
	ds_read_b128 v[52:55], v3 offset:63792
	s_waitcnt lgkmcnt(1)
	v_fma_f32 v47, -v37, v48, v47
	v_fma_f32 v47, -v38, v49, v47
	v_fma_f32 v47, -v39, v50, v47
	v_fma_f32 v47, -v40, v51, v47
	ds_read_b128 v[48:51], v3 offset:63808
	s_waitcnt lgkmcnt(1)
	v_fma_f32 v3, -v41, v52, v47
	v_fma_f32 v3, -v42, v53, v3
	v_fma_f32 v3, -v43, v54, v3
	v_fma_f32 v3, -v44, v55, v3
	s_waitcnt lgkmcnt(0)
	v_fma_f32 v3, -v45, v48, v3
	v_fma_f32 v47, -v46, v49, v3
	v_fmac_f32_e32 v47, 0x80000000, v50
	v_fmac_f32_e32 v47, 0x80000000, v51
	ds_read_u16 v49, v2 offset:11696
	v_lshlrev_b32_e32 v3, 2, v0
	v_add_u32_e32 v48, s0, v3
	ds_read2_b32 v[52:53], v48 offset0:43 offset1:107
	v_add_u32_e32 v3, 32, v3
	s_waitcnt lgkmcnt(0)
	v_mul_f32_e32 v48, 0x3fb8aa3b, v53
	v_exp_f32_e32 v48, v48
	v_lshlrev_b32_e32 v53, 16, v49
	v_mul_f32_e32 v65, v52, v53
	v_cndmask_b32_e64 v64, v48, 1.0, vcc
	ds_read_b128 v[48:51], v3 offset:63920
	ds_read_b128 v[52:55], v3 offset:63936
	ds_read_b128 v[56:59], v3 offset:63952
	ds_read_b128 v[60:63], v3 offset:63968
	s_waitcnt lgkmcnt(3)
	v_mul_f32_e32 v48, v4, v48
	v_fma_f32 v48, v64, v65, -v48
	v_fma_f32 v48, -v5, v49, v48
	v_fma_f32 v48, -v6, v50, v48
	v_fma_f32 v48, -v7, v51, v48
	s_waitcnt lgkmcnt(2)
	v_fma_f32 v48, -v8, v52, v48
	v_fma_f32 v48, -v9, v53, v48
	v_fma_f32 v48, -v10, v54, v48
	v_fma_f32 v48, -v11, v55, v48
	s_waitcnt lgkmcnt(1)
	v_fma_f32 v48, -v12, v56, v48
	v_fma_f32 v48, -v13, v57, v48
	v_fma_f32 v48, -v14, v58, v48
	v_fma_f32 v48, -v15, v59, v48
	s_waitcnt lgkmcnt(0)
	v_fma_f32 v52, -v16, v60, v48
	ds_read_b128 v[48:51], v3 offset:63984
	v_fma_f32 v52, -v17, v61, v52
	v_fma_f32 v52, -v18, v62, v52
	v_fma_f32 v56, -v19, v63, v52
	ds_read_b128 v[52:55], v3 offset:64000
	s_waitcnt lgkmcnt(1)
	v_fma_f32 v48, -v20, v48, v56
	v_fma_f32 v48, -v21, v49, v48
	v_fma_f32 v48, -v22, v50, v48
	v_fma_f32 v48, -v23, v51, v48
	s_waitcnt lgkmcnt(0)
	v_fma_f32 v52, -v24, v52, v48
	ds_read_b128 v[48:51], v3 offset:64016
	v_fma_f32 v52, -v25, v53, v52
	v_fma_f32 v52, -v26, v54, v52
	v_fma_f32 v56, -v27, v55, v52
	ds_read_b128 v[52:55], v3 offset:64032
	s_waitcnt lgkmcnt(1)
	v_fma_f32 v48, -v28, v48, v56
	v_fma_f32 v48, -v29, v49, v48
	v_fma_f32 v48, -v30, v50, v48
	v_fma_f32 v48, -v31, v51, v48
	s_waitcnt lgkmcnt(0)
	v_fma_f32 v52, -v32, v52, v48
	ds_read_b128 v[48:51], v3 offset:64048
	v_fma_f32 v52, -v33, v53, v52
	v_fma_f32 v52, -v35, v54, v52
	v_fma_f32 v56, -v36, v55, v52
	ds_read_b128 v[52:55], v3 offset:64064
	s_waitcnt lgkmcnt(1)
	v_fma_f32 v48, -v37, v48, v56
	v_fma_f32 v48, -v38, v49, v48
	v_fma_f32 v48, -v39, v50, v48
	v_fma_f32 v56, -v40, v51, v48
	ds_read_b128 v[48:51], v3 offset:64080
	s_waitcnt lgkmcnt(1)
	v_fma_f32 v3, -v41, v52, v56
	v_fma_f32 v3, -v42, v53, v3
	v_fma_f32 v3, -v43, v54, v3
	v_fma_f32 v3, -v44, v55, v3
	s_waitcnt lgkmcnt(0)
	v_fma_f32 v3, -v45, v48, v3
	v_fma_f32 v3, -v46, v49, v3
	v_fma_f32 v48, -v47, v50, v3
	v_fmac_f32_e32 v48, 0x80000000, v51
	ds_read_u16 v50, v2 offset:11968
	v_lshlrev_b32_e32 v3, 2, v0
	v_add_u32_e32 v49, s0, v3
	ds_read2_b32 v[54:55], v49 offset0:44 offset1:108
	v_add_u32_e32 v3, 32, v3
	s_waitcnt lgkmcnt(0)
	v_mul_f32_e32 v49, 0x3fb8aa3b, v55
	v_lshlrev_b32_e32 v55, 16, v50
	ds_read_b128 v[50:53], v3 offset:64192
	v_exp_f32_e32 v49, v49
	v_mul_f32_e32 v66, v54, v55
	ds_read_b128 v[54:57], v3 offset:64208
	ds_read_b128 v[58:61], v3 offset:64224
	ds_read_b128 v[62:65], v3 offset:64240
	v_cndmask_b32_e64 v49, v49, 1.0, vcc
	s_waitcnt lgkmcnt(3)
	v_mul_f32_e32 v50, v4, v50
	v_fma_f32 v49, v49, v66, -v50
	v_fma_f32 v49, -v5, v51, v49
	v_fma_f32 v49, -v6, v52, v49
	v_fma_f32 v49, -v7, v53, v49
	s_waitcnt lgkmcnt(2)
	v_fma_f32 v49, -v8, v54, v49
	v_fma_f32 v49, -v9, v55, v49
	v_fma_f32 v49, -v10, v56, v49
	v_fma_f32 v49, -v11, v57, v49
	s_waitcnt lgkmcnt(1)
	v_fma_f32 v49, -v12, v58, v49
	v_fma_f32 v49, -v13, v59, v49
	v_fma_f32 v49, -v14, v60, v49
	v_fma_f32 v49, -v15, v61, v49
	ds_read_b128 v[50:53], v3 offset:64256
	s_waitcnt lgkmcnt(1)
; DEVI float bf2f(bf16_t b) { return __uint_as_float(((unsigned)b) << 16); }
; DEVI void prep_item(const Params& p, int j, int n, int h, char* smem) {
;     ...
; #pragma unroll
;     for (int i = 0; i < 64; ++i) {
;       const float* amz = am + zero;
;       const float* sbz = sbeta + zero;
;       const float eg = __expf(sbz[64 + i]);
;       float acc = bf2f(*(const unsigned short*)(src + i * 272)) * sbz[i] * (isu ? 1.0f : eg);
; #pragma unroll
;       for (int j4 = 0; j4 < (i + 3) / 4; ++j4) {
;         const f32x4 a = *(const f32x4*)(amz + i * 68 + j4 * 4);
;         acc -= a[0] * x[j4 * 4 + 0];
;         acc -= a[1] * x[j4 * 4 + 1];
;         acc -= a[2] * x[j4 * 4 + 2];
;         acc -= a[3] * x[j4 * 4 + 3];
;       }
;       asm volatile("" : "+v"(zero), "+v"(acc));
;       x[i] = acc;
;     }
	v_fma_f32 v49, -v16, v62, v49
	v_fma_f32 v49, -v17, v63, v49
	v_fma_f32 v49, -v18, v64, v49
	v_fma_f32 v49, -v19, v65, v49
	ds_read_b128 v[54:57], v3 offset:64272
	s_waitcnt lgkmcnt(1)
	v_fma_f32 v49, -v20, v50, v49
	v_fma_f32 v49, -v21, v51, v49
	v_fma_f32 v49, -v22, v52, v49
	v_fma_f32 v49, -v23, v53, v49
	ds_read_b128 v[50:53], v3 offset:64288
	s_waitcnt lgkmcnt(1)
	v_fma_f32 v49, -v24, v54, v49
	v_fma_f32 v49, -v25, v55, v49
	v_fma_f32 v49, -v26, v56, v49
	v_fma_f32 v49, -v27, v57, v49
	ds_read_b128 v[54:57], v3 offset:64304
	s_waitcnt lgkmcnt(1)
	v_fma_f32 v49, -v28, v50, v49
	v_fma_f32 v49, -v29, v51, v49
	v_fma_f32 v49, -v30, v52, v49
	v_fma_f32 v49, -v31, v53, v49
	ds_read_b128 v[50:53], v3 offset:64320
	s_waitcnt lgkmcnt(1)
	v_fma_f32 v49, -v32, v54, v49
	v_fma_f32 v49, -v33, v55, v49
	v_fma_f32 v49, -v35, v56, v49
	v_fma_f32 v49, -v36, v57, v49
	ds_read_b128 v[54:57], v3 offset:64336
	s_waitcnt lgkmcnt(1)
	v_fma_f32 v49, -v37, v50, v49
	v_fma_f32 v49, -v38, v51, v49
	v_fma_f32 v49, -v39, v52, v49
	v_fma_f32 v49, -v40, v53, v49
	ds_read_b128 v[50:53], v3 offset:64352
	s_waitcnt lgkmcnt(1)
	v_fma_f32 v3, -v41, v54, v49
	v_fma_f32 v3, -v42, v55, v3
	v_fma_f32 v3, -v43, v56, v3
	v_fma_f32 v3, -v44, v57, v3
	s_waitcnt lgkmcnt(0)
	v_fma_f32 v3, -v45, v50, v3
	v_fma_f32 v3, -v46, v51, v3
	v_fma_f32 v3, -v47, v52, v3
	v_fma_f32 v49, -v48, v53, v3
	ds_read_u16 v51, v2 offset:12240
	v_lshlrev_b32_e32 v3, 2, v0
	v_add_u32_e32 v50, s0, v3
	ds_read2_b32 v[54:55], v50 offset0:45 offset1:109
	v_add_u32_e32 v3, 32, v3
	s_waitcnt lgkmcnt(0)
	v_mul_f32_e32 v50, 0x3fb8aa3b, v55
	v_exp_f32_e32 v50, v50
	v_lshlrev_b32_e32 v55, 16, v51
	v_mul_f32_e32 v67, v54, v55
	v_cndmask_b32_e64 v66, v50, 1.0, vcc
	ds_read_b128 v[50:53], v3 offset:64464
	ds_read_b128 v[54:57], v3 offset:64480
	ds_read_b128 v[58:61], v3 offset:64496
	ds_read_b128 v[62:65], v3 offset:64512
	s_waitcnt lgkmcnt(3)
	v_mul_f32_e32 v50, v4, v50
	v_fma_f32 v50, v66, v67, -v50
	v_fma_f32 v50, -v5, v51, v50
	v_fma_f32 v50, -v6, v52, v50
	v_fma_f32 v50, -v7, v53, v50
	s_waitcnt lgkmcnt(2)
	v_fma_f32 v50, -v8, v54, v50
	v_fma_f32 v50, -v9, v55, v50
	v_fma_f32 v50, -v10, v56, v50
	v_fma_f32 v50, -v11, v57, v50
	s_waitcnt lgkmcnt(1)
	v_fma_f32 v50, -v12, v58, v50
	v_fma_f32 v50, -v13, v59, v50
	v_fma_f32 v50, -v14, v60, v50
	v_fma_f32 v50, -v15, v61, v50
	s_waitcnt lgkmcnt(0)
	v_fma_f32 v54, -v16, v62, v50
	ds_read_b128 v[50:53], v3 offset:64528
	v_fma_f32 v54, -v17, v63, v54
	v_fma_f32 v54, -v18, v64, v54
	v_fma_f32 v58, -v19, v65, v54
	ds_read_b128 v[54:57], v3 offset:64544
	s_waitcnt lgkmcnt(1)
	v_fma_f32 v50, -v20, v50, v58
	v_fma_f32 v50, -v21, v51, v50
	v_fma_f32 v50, -v22, v52, v50
	v_fma_f32 v50, -v23, v53, v50
	s_waitcnt lgkmcnt(0)
	v_fma_f32 v54, -v24, v54, v50
	ds_read_b128 v[50:53], v3 offset:64560
	v_fma_f32 v54, -v25, v55, v54
	v_fma_f32 v54, -v26, v56, v54
	v_fma_f32 v58, -v27, v57, v54
	ds_read_b128 v[54:57], v3 offset:64576
	s_waitcnt lgkmcnt(1)
	v_fma_f32 v50, -v28, v50, v58
	v_fma_f32 v50, -v29, v51, v50
	v_fma_f32 v50, -v30, v52, v50
	v_fma_f32 v50, -v31, v53, v50
	s_waitcnt lgkmcnt(0)
	v_fma_f32 v54, -v32, v54, v50
	ds_read_b128 v[50:53], v3 offset:64592
	v_fma_f32 v54, -v33, v55, v54
	v_fma_f32 v54, -v35, v56, v54
	v_fma_f32 v58, -v36, v57, v54
	ds_read_b128 v[54:57], v3 offset:64608
	s_waitcnt lgkmcnt(1)
	v_fma_f32 v50, -v37, v50, v58
	v_fma_f32 v50, -v38, v51, v50
	v_fma_f32 v50, -v39, v52, v50
	v_fma_f32 v50, -v40, v53, v50
	s_waitcnt lgkmcnt(0)
	v_fma_f32 v54, -v41, v54, v50
	ds_read_b128 v[50:53], v3 offset:64624
	v_fma_f32 v54, -v42, v55, v54
	v_fma_f32 v54, -v43, v56, v54
	v_fma_f32 v58, -v44, v57, v54
	ds_read_b128 v[54:57], v3 offset:64640
	s_waitcnt lgkmcnt(1)
	v_fma_f32 v3, -v45, v50, v58
	v_fma_f32 v3, -v46, v51, v3
	v_fma_f32 v3, -v47, v52, v3
	v_fma_f32 v3, -v48, v53, v3
	s_waitcnt lgkmcnt(0)
	v_fma_f32 v50, -v49, v54, v3
	v_fmac_f32_e32 v50, 0x80000000, v55
	v_fmac_f32_e32 v50, 0x80000000, v56
	v_fmac_f32_e32 v50, 0x80000000, v57
	ds_read_u16 v52, v2 offset:12512
	v_lshlrev_b32_e32 v3, 2, v0
	v_add_u32_e32 v51, s0, v3
	ds_read2_b32 v[56:57], v51 offset0:46 offset1:110
	v_add_u32_e32 v3, 32, v3
	s_waitcnt lgkmcnt(0)
	v_mul_f32_e32 v51, 0x3fb8aa3b, v57
	v_lshlrev_b32_e32 v57, 16, v52
	ds_read_b128 v[52:55], v3 offset:64736
	v_exp_f32_e32 v51, v51
	v_mul_f32_e32 v68, v56, v57
	ds_read_b128 v[56:59], v3 offset:64752
	ds_read_b128 v[60:63], v3 offset:64768
	ds_read_b128 v[64:67], v3 offset:64784
	v_cndmask_b32_e64 v51, v51, 1.0, vcc
	s_waitcnt lgkmcnt(3)
	v_mul_f32_e32 v52, v4, v52
	v_fma_f32 v51, v51, v68, -v52
	v_fma_f32 v51, -v5, v53, v51
	v_fma_f32 v51, -v6, v54, v51
	v_fma_f32 v51, -v7, v55, v51
	s_waitcnt lgkmcnt(2)
	v_fma_f32 v51, -v8, v56, v51
	v_fma_f32 v51, -v9, v57, v51
	v_fma_f32 v51, -v10, v58, v51
	v_fma_f32 v51, -v11, v59, v51
	s_waitcnt lgkmcnt(1)
	v_fma_f32 v51, -v12, v60, v51
	v_fma_f32 v51, -v13, v61, v51
	v_fma_f32 v51, -v14, v62, v51
	v_fma_f32 v51, -v15, v63, v51
	ds_read_b128 v[52:55], v3 offset:64800
	s_waitcnt lgkmcnt(1)
	v_fma_f32 v51, -v16, v64, v51
	v_fma_f32 v51, -v17, v65, v51
	v_fma_f32 v51, -v18, v66, v51
	v_fma_f32 v51, -v19, v67, v51
	ds_read_b128 v[56:59], v3 offset:64816
	s_waitcnt lgkmcnt(1)
	v_fma_f32 v51, -v20, v52, v51
	v_fma_f32 v51, -v21, v53, v51
	v_fma_f32 v51, -v22, v54, v51
	v_fma_f32 v51, -v23, v55, v51
	ds_read_b128 v[52:55], v3 offset:64832
	s_waitcnt lgkmcnt(1)
	v_fma_f32 v51, -v24, v56, v51
	v_fma_f32 v51, -v25, v57, v51
	v_fma_f32 v51, -v26, v58, v51
	v_fma_f32 v51, -v27, v59, v51
	ds_read_b128 v[56:59], v3 offset:64848
	s_waitcnt lgkmcnt(1)
; DEVI float bf2f(bf16_t b) { return __uint_as_float(((unsigned)b) << 16); }
; DEVI void prep_item(const Params& p, int j, int n, int h, char* smem) {
;     ...
; #pragma unroll
;     for (int i = 0; i < 64; ++i) {
;       const float* amz = am + zero;
;       const float* sbz = sbeta + zero;
;       const float eg = __expf(sbz[64 + i]);
;       float acc = bf2f(*(const unsigned short*)(src + i * 272)) * sbz[i] * (isu ? 1.0f : eg);
; #pragma unroll
;       for (int j4 = 0; j4 < (i + 3) / 4; ++j4) {
;         const f32x4 a = *(const f32x4*)(amz + i * 68 + j4 * 4);
;         acc -= a[0] * x[j4 * 4 + 0];
;         acc -= a[1] * x[j4 * 4 + 1];
;         acc -= a[2] * x[j4 * 4 + 2];
;         acc -= a[3] * x[j4 * 4 + 3];
;       }
;       asm volatile("" : "+v"(zero), "+v"(acc));
;       x[i] = acc;
;     }
	v_fma_f32 v51, -v28, v52, v51
	v_fma_f32 v51, -v29, v53, v51
	v_fma_f32 v51, -v30, v54, v51
	v_fma_f32 v51, -v31, v55, v51
	ds_read_b128 v[52:55], v3 offset:64864
	s_waitcnt lgkmcnt(1)
	v_fma_f32 v51, -v32, v56, v51
	v_fma_f32 v51, -v33, v57, v51
	v_fma_f32 v51, -v35, v58, v51
	v_fma_f32 v51, -v36, v59, v51
	ds_read_b128 v[56:59], v3 offset:64880
	s_waitcnt lgkmcnt(1)
	v_fma_f32 v51, -v37, v52, v51
	v_fma_f32 v51, -v38, v53, v51
	v_fma_f32 v51, -v39, v54, v51
	v_fma_f32 v51, -v40, v55, v51
	ds_read_b128 v[52:55], v3 offset:64896
	s_waitcnt lgkmcnt(1)
	v_fma_f32 v51, -v41, v56, v51
	v_fma_f32 v51, -v42, v57, v51
	v_fma_f32 v51, -v43, v58, v51
	v_fma_f32 v51, -v44, v59, v51
	ds_read_b128 v[56:59], v3 offset:64912
	s_waitcnt lgkmcnt(1)
	v_fma_f32 v3, -v45, v52, v51
	v_fma_f32 v3, -v46, v53, v3
	v_fma_f32 v3, -v47, v54, v3
	v_fma_f32 v3, -v48, v55, v3
	s_waitcnt lgkmcnt(0)
	v_fma_f32 v3, -v49, v56, v3
	v_fma_f32 v51, -v50, v57, v3
	v_fmac_f32_e32 v51, 0x80000000, v58
	v_fmac_f32_e32 v51, 0x80000000, v59
	ds_read_u16 v53, v2 offset:12784
	v_lshlrev_b32_e32 v3, 2, v0
	v_add_u32_e32 v52, s0, v3
	ds_read2_b32 v[56:57], v52 offset0:47 offset1:111
	v_add_u32_e32 v3, 32, v3
	s_waitcnt lgkmcnt(0)
	v_mul_f32_e32 v52, 0x3fb8aa3b, v57
	v_exp_f32_e32 v52, v52
	v_lshlrev_b32_e32 v57, 16, v53
	v_mul_f32_e32 v69, v56, v57
	v_cndmask_b32_e64 v68, v52, 1.0, vcc
	ds_read_b128 v[52:55], v3 offset:65008
	ds_read_b128 v[56:59], v3 offset:65024
	ds_read_b128 v[60:63], v3 offset:65040
	ds_read_b128 v[64:67], v3 offset:65056
	s_waitcnt lgkmcnt(3)
	v_mul_f32_e32 v52, v4, v52
	v_fma_f32 v52, v68, v69, -v52
	v_fma_f32 v52, -v5, v53, v52
	v_fma_f32 v52, -v6, v54, v52
	v_fma_f32 v52, -v7, v55, v52
	s_waitcnt lgkmcnt(2)
	v_fma_f32 v52, -v8, v56, v52
	v_fma_f32 v52, -v9, v57, v52
	v_fma_f32 v52, -v10, v58, v52
	v_fma_f32 v52, -v11, v59, v52
	s_waitcnt lgkmcnt(1)
	v_fma_f32 v52, -v12, v60, v52
	v_fma_f32 v52, -v13, v61, v52
	v_fma_f32 v52, -v14, v62, v52
	v_fma_f32 v52, -v15, v63, v52
	s_waitcnt lgkmcnt(0)
	v_fma_f32 v56, -v16, v64, v52
	ds_read_b128 v[52:55], v3 offset:65072
	v_fma_f32 v56, -v17, v65, v56
	v_fma_f32 v56, -v18, v66, v56
	v_fma_f32 v60, -v19, v67, v56
	ds_read_b128 v[56:59], v3 offset:65088
	s_waitcnt lgkmcnt(1)
	v_fma_f32 v52, -v20, v52, v60
	v_fma_f32 v52, -v21, v53, v52
	v_fma_f32 v52, -v22, v54, v52
	v_fma_f32 v52, -v23, v55, v52
	s_waitcnt lgkmcnt(0)
	v_fma_f32 v56, -v24, v56, v52
	ds_read_b128 v[52:55], v3 offset:65104
	v_fma_f32 v56, -v25, v57, v56
	v_fma_f32 v56, -v26, v58, v56
	v_fma_f32 v60, -v27, v59, v56
	ds_read_b128 v[56:59], v3 offset:65120
	s_waitcnt lgkmcnt(1)
	v_fma_f32 v52, -v28, v52, v60
	v_fma_f32 v52, -v29, v53, v52
	v_fma_f32 v52, -v30, v54, v52
	v_fma_f32 v52, -v31, v55, v52
	s_waitcnt lgkmcnt(0)
	v_fma_f32 v56, -v32, v56, v52
	ds_read_b128 v[52:55], v3 offset:65136
	v_fma_f32 v56, -v33, v57, v56
	v_fma_f32 v56, -v35, v58, v56
	v_fma_f32 v60, -v36, v59, v56
	ds_read_b128 v[56:59], v3 offset:65152
	s_waitcnt lgkmcnt(1)
	v_fma_f32 v52, -v37, v52, v60
	v_fma_f32 v52, -v38, v53, v52
	v_fma_f32 v52, -v39, v54, v52
	v_fma_f32 v52, -v40, v55, v52
	s_waitcnt lgkmcnt(0)
	v_fma_f32 v56, -v41, v56, v52
	ds_read_b128 v[52:55], v3 offset:65168
	v_fma_f32 v56, -v42, v57, v56
	v_fma_f32 v56, -v43, v58, v56
	v_fma_f32 v60, -v44, v59, v56
	ds_read_b128 v[56:59], v3 offset:65184
	s_waitcnt lgkmcnt(1)
	v_fma_f32 v3, -v45, v52, v60
	v_fma_f32 v3, -v46, v53, v3
	v_fma_f32 v3, -v47, v54, v3
	v_fma_f32 v3, -v48, v55, v3
	s_waitcnt lgkmcnt(0)
	v_fma_f32 v3, -v49, v56, v3
	v_fma_f32 v3, -v50, v57, v3
	v_fma_f32 v52, -v51, v58, v3
	v_fmac_f32_e32 v52, 0x80000000, v59
	ds_read_u16 v54, v2 offset:13056
	v_lshlrev_b32_e32 v3, 2, v0
	v_add_u32_e32 v53, s0, v3
	ds_read2_b32 v[58:59], v53 offset0:48 offset1:112
	v_add_u32_e32 v3, 32, v3
	s_waitcnt lgkmcnt(0)
	v_mul_f32_e32 v53, 0x3fb8aa3b, v59
	v_lshlrev_b32_e32 v59, 16, v54
	ds_read_b128 v[54:57], v3 offset:65280
	v_exp_f32_e32 v53, v53
	v_mul_f32_e32 v70, v58, v59
	ds_read_b128 v[58:61], v3 offset:65296
	ds_read_b128 v[62:65], v3 offset:65312
	ds_read_b128 v[66:69], v3 offset:65328
	v_cndmask_b32_e64 v53, v53, 1.0, vcc
	s_waitcnt lgkmcnt(3)
	v_mul_f32_e32 v54, v4, v54
	v_fma_f32 v53, v53, v70, -v54
	v_fma_f32 v53, -v5, v55, v53
	v_fma_f32 v53, -v6, v56, v53
	v_fma_f32 v53, -v7, v57, v53
	s_waitcnt lgkmcnt(2)
	v_fma_f32 v53, -v8, v58, v53
	v_fma_f32 v53, -v9, v59, v53
	v_fma_f32 v53, -v10, v60, v53
	v_fma_f32 v53, -v11, v61, v53
	s_waitcnt lgkmcnt(1)
	v_fma_f32 v53, -v12, v62, v53
	v_fma_f32 v53, -v13, v63, v53
	v_fma_f32 v53, -v14, v64, v53
	v_fma_f32 v53, -v15, v65, v53
	ds_read_b128 v[54:57], v3 offset:65344
	s_waitcnt lgkmcnt(1)
	v_fma_f32 v53, -v16, v66, v53
	v_fma_f32 v53, -v17, v67, v53
	v_fma_f32 v53, -v18, v68, v53
	v_fma_f32 v53, -v19, v69, v53
	ds_read_b128 v[58:61], v3 offset:65360
	s_waitcnt lgkmcnt(1)
	v_fma_f32 v53, -v20, v54, v53
	v_fma_f32 v53, -v21, v55, v53
	v_fma_f32 v53, -v22, v56, v53
	v_fma_f32 v53, -v23, v57, v53
	ds_read_b128 v[54:57], v3 offset:65376
	s_waitcnt lgkmcnt(1)
	v_fma_f32 v53, -v24, v58, v53
	v_fma_f32 v53, -v25, v59, v53
	v_fma_f32 v53, -v26, v60, v53
	v_fma_f32 v53, -v27, v61, v53
	ds_read_b128 v[58:61], v3 offset:65392
	s_waitcnt lgkmcnt(1)
	v_fma_f32 v53, -v28, v54, v53
	v_fma_f32 v53, -v29, v55, v53
	v_fma_f32 v53, -v30, v56, v53
	v_fma_f32 v53, -v31, v57, v53
	ds_read_b128 v[54:57], v3 offset:65408
	s_waitcnt lgkmcnt(1)
	v_fma_f32 v53, -v32, v58, v53
	v_fma_f32 v53, -v33, v59, v53
	v_fma_f32 v53, -v35, v60, v53
	v_fma_f32 v53, -v36, v61, v53
	ds_read_b128 v[58:61], v3 offset:65424
	s_waitcnt lgkmcnt(1)
; DEVI float bf2f(bf16_t b) { return __uint_as_float(((unsigned)b) << 16); }
; DEVI void prep_item(const Params& p, int j, int n, int h, char* smem) {
;     ...
; #pragma unroll
;     for (int i = 0; i < 64; ++i) {
;       const float* amz = am + zero;
;       const float* sbz = sbeta + zero;
;       const float eg = __expf(sbz[64 + i]);
;       float acc = bf2f(*(const unsigned short*)(src + i * 272)) * sbz[i] * (isu ? 1.0f : eg);
; #pragma unroll
;       for (int j4 = 0; j4 < (i + 3) / 4; ++j4) {
;         const f32x4 a = *(const f32x4*)(amz + i * 68 + j4 * 4);
;         acc -= a[0] * x[j4 * 4 + 0];
;         acc -= a[1] * x[j4 * 4 + 1];
;         acc -= a[2] * x[j4 * 4 + 2];
;         acc -= a[3] * x[j4 * 4 + 3];
;       }
;       asm volatile("" : "+v"(zero), "+v"(acc));
;       x[i] = acc;
;     }
	v_fma_f32 v53, -v37, v54, v53
	v_fma_f32 v53, -v38, v55, v53
	v_fma_f32 v53, -v39, v56, v53
	v_fma_f32 v53, -v40, v57, v53
	ds_read_b128 v[54:57], v3 offset:65440
	s_waitcnt lgkmcnt(1)
	v_fma_f32 v53, -v41, v58, v53
	v_fma_f32 v53, -v42, v59, v53
	v_fma_f32 v53, -v43, v60, v53
	v_fma_f32 v53, -v44, v61, v53
	ds_read_b128 v[58:61], v3 offset:65456
	s_waitcnt lgkmcnt(1)
	v_fma_f32 v3, -v45, v54, v53
	v_fma_f32 v3, -v46, v55, v3
	v_fma_f32 v3, -v47, v56, v3
	v_fma_f32 v3, -v48, v57, v3
	s_waitcnt lgkmcnt(0)
	v_fma_f32 v3, -v49, v58, v3
	v_fma_f32 v3, -v50, v59, v3
	v_fma_f32 v3, -v51, v60, v3
	v_fma_f32 v53, -v52, v61, v3
	ds_read_u16 v55, v2 offset:13328
	v_lshlrev_b32_e32 v3, 2, v0
	v_add_u32_e32 v54, s0, v3
	ds_read2_b32 v[58:59], v54 offset0:49 offset1:113
	v_add_u32_e32 v3, 32, v3
	v_add_u32_e32 v3, 0xcc00, v3
	s_waitcnt lgkmcnt(0)
	v_mul_f32_e32 v54, 0x3fb8aa3b, v59
	v_exp_f32_e32 v54, v54
	v_lshlrev_b32_e32 v59, 16, v55
	v_mul_f32_e32 v71, v58, v59
	v_cndmask_b32_e64 v70, v54, 1.0, vcc
	ds_read_b128 v[54:57], v3 offset:13328
	ds_read_b128 v[58:61], v3 offset:13344
	ds_read_b128 v[62:65], v3 offset:13360
	ds_read_b128 v[66:69], v3 offset:13376
	s_waitcnt lgkmcnt(3)
	v_mul_f32_e32 v54, v4, v54
	v_fma_f32 v54, v70, v71, -v54
	v_fma_f32 v54, -v5, v55, v54
	v_fma_f32 v54, -v6, v56, v54
	v_fma_f32 v54, -v7, v57, v54
	s_waitcnt lgkmcnt(2)
	v_fma_f32 v54, -v8, v58, v54
	v_fma_f32 v54, -v9, v59, v54
	v_fma_f32 v54, -v10, v60, v54
	v_fma_f32 v54, -v11, v61, v54
	s_waitcnt lgkmcnt(1)
	v_fma_f32 v54, -v12, v62, v54
	v_fma_f32 v54, -v13, v63, v54
	v_fma_f32 v54, -v14, v64, v54
	v_fma_f32 v54, -v15, v65, v54
	s_waitcnt lgkmcnt(0)
	v_fma_f32 v58, -v16, v66, v54
	ds_read_b128 v[54:57], v3 offset:13392
	v_fma_f32 v58, -v17, v67, v58
	v_fma_f32 v58, -v18, v68, v58
	v_fma_f32 v62, -v19, v69, v58
	ds_read_b128 v[58:61], v3 offset:13408
	s_waitcnt lgkmcnt(1)
	v_fma_f32 v54, -v20, v54, v62
	v_fma_f32 v54, -v21, v55, v54
	v_fma_f32 v54, -v22, v56, v54
	v_fma_f32 v54, -v23, v57, v54
	s_waitcnt lgkmcnt(0)
	v_fma_f32 v58, -v24, v58, v54
	ds_read_b128 v[54:57], v3 offset:13424
	v_fma_f32 v58, -v25, v59, v58
	v_fma_f32 v58, -v26, v60, v58
	v_fma_f32 v62, -v27, v61, v58
	ds_read_b128 v[58:61], v3 offset:13440
	s_waitcnt lgkmcnt(1)
	v_fma_f32 v54, -v28, v54, v62
	v_fma_f32 v54, -v29, v55, v54
	v_fma_f32 v54, -v30, v56, v54
	v_fma_f32 v54, -v31, v57, v54
	s_waitcnt lgkmcnt(0)
	v_fma_f32 v58, -v32, v58, v54
	ds_read_b128 v[54:57], v3 offset:13456
	v_fma_f32 v58, -v33, v59, v58
	v_fma_f32 v58, -v35, v60, v58
	v_fma_f32 v62, -v36, v61, v58
	ds_read_b128 v[58:61], v3 offset:13472
	s_waitcnt lgkmcnt(1)
	v_fma_f32 v54, -v37, v54, v62
	v_fma_f32 v54, -v38, v55, v54
	v_fma_f32 v54, -v39, v56, v54
	v_fma_f32 v54, -v40, v57, v54
	s_waitcnt lgkmcnt(0)
	v_fma_f32 v58, -v41, v58, v54
	ds_read_b128 v[54:57], v3 offset:13488
	v_fma_f32 v58, -v42, v59, v58
	v_fma_f32 v58, -v43, v60, v58
	v_fma_f32 v62, -v44, v61, v58
	ds_read_b128 v[58:61], v3 offset:13504
	s_waitcnt lgkmcnt(1)
	v_fma_f32 v54, -v45, v54, v62
	v_fma_f32 v54, -v46, v55, v54
	v_fma_f32 v54, -v47, v56, v54
	v_fma_f32 v62, -v48, v57, v54
	ds_read_b128 v[54:57], v3 offset:13520
	s_waitcnt lgkmcnt(1)
	v_fma_f32 v3, -v49, v58, v62
	v_fma_f32 v3, -v50, v59, v3
	v_fma_f32 v3, -v51, v60, v3
	v_fma_f32 v3, -v52, v61, v3
	s_waitcnt lgkmcnt(0)
	v_fma_f32 v54, -v53, v54, v3
	v_fmac_f32_e32 v54, 0x80000000, v55
	v_fmac_f32_e32 v54, 0x80000000, v56
	v_fmac_f32_e32 v54, 0x80000000, v57
	ds_read_u16 v56, v2 offset:13600
	v_lshlrev_b32_e32 v3, 2, v0
	v_add_u32_e32 v55, s0, v3
	ds_read2_b32 v[60:61], v55 offset0:50 offset1:114
	v_add_u32_e32 v3, 32, v3
	v_add_u32_e32 v3, 0xcc00, v3
	s_waitcnt lgkmcnt(0)
	v_mul_f32_e32 v55, 0x3fb8aa3b, v61
	v_lshlrev_b32_e32 v61, 16, v56
	ds_read_b128 v[56:59], v3 offset:13600
	v_exp_f32_e32 v55, v55
	v_mul_f32_e32 v72, v60, v61
	ds_read_b128 v[60:63], v3 offset:13616
	ds_read_b128 v[64:67], v3 offset:13632
	ds_read_b128 v[68:71], v3 offset:13648
	v_cndmask_b32_e64 v55, v55, 1.0, vcc
	s_waitcnt lgkmcnt(3)
	v_mul_f32_e32 v56, v4, v56
	v_fma_f32 v55, v55, v72, -v56
	v_fma_f32 v55, -v5, v57, v55
	v_fma_f32 v55, -v6, v58, v55
	v_fma_f32 v55, -v7, v59, v55
	s_waitcnt lgkmcnt(2)
	v_fma_f32 v55, -v8, v60, v55
	v_fma_f32 v55, -v9, v61, v55
	v_fma_f32 v55, -v10, v62, v55
	v_fma_f32 v55, -v11, v63, v55
	s_waitcnt lgkmcnt(1)
	v_fma_f32 v55, -v12, v64, v55
	v_fma_f32 v55, -v13, v65, v55
	v_fma_f32 v55, -v14, v66, v55
	v_fma_f32 v55, -v15, v67, v55
	ds_read_b128 v[56:59], v3 offset:13664
	s_waitcnt lgkmcnt(1)
	v_fma_f32 v55, -v16, v68, v55
	v_fma_f32 v55, -v17, v69, v55
	v_fma_f32 v55, -v18, v70, v55
	v_fma_f32 v55, -v19, v71, v55
	ds_read_b128 v[60:63], v3 offset:13680
	s_waitcnt lgkmcnt(1)
	v_fma_f32 v55, -v20, v56, v55
	v_fma_f32 v55, -v21, v57, v55
	v_fma_f32 v55, -v22, v58, v55
	v_fma_f32 v55, -v23, v59, v55
	ds_read_b128 v[56:59], v3 offset:13696
	s_waitcnt lgkmcnt(1)
	v_fma_f32 v55, -v24, v60, v55
	v_fma_f32 v55, -v25, v61, v55
	v_fma_f32 v55, -v26, v62, v55
	v_fma_f32 v55, -v27, v63, v55
	ds_read_b128 v[60:63], v3 offset:13712
	s_waitcnt lgkmcnt(1)
	v_fma_f32 v55, -v28, v56, v55
	v_fma_f32 v55, -v29, v57, v55
	v_fma_f32 v55, -v30, v58, v55
	v_fma_f32 v55, -v31, v59, v55
	ds_read_b128 v[56:59], v3 offset:13728
	s_waitcnt lgkmcnt(1)
	v_fma_f32 v55, -v32, v60, v55
	v_fma_f32 v55, -v33, v61, v55
	v_fma_f32 v55, -v35, v62, v55
	v_fma_f32 v55, -v36, v63, v55
	ds_read_b128 v[60:63], v3 offset:13744
	s_waitcnt lgkmcnt(1)
	v_fma_f32 v55, -v37, v56, v55
	v_fma_f32 v55, -v38, v57, v55
	v_fma_f32 v55, -v39, v58, v55
	v_fma_f32 v55, -v40, v59, v55
	ds_read_b128 v[56:59], v3 offset:13760
	s_waitcnt lgkmcnt(1)
; DEVI float bf2f(bf16_t b) { return __uint_as_float(((unsigned)b) << 16); }
; DEVI void prep_item(const Params& p, int j, int n, int h, char* smem) {
;     ...
; #pragma unroll
;     for (int i = 0; i < 64; ++i) {
;       const float* amz = am + zero;
;       const float* sbz = sbeta + zero;
;       const float eg = __expf(sbz[64 + i]);
;       float acc = bf2f(*(const unsigned short*)(src + i * 272)) * sbz[i] * (isu ? 1.0f : eg);
; #pragma unroll
;       for (int j4 = 0; j4 < (i + 3) / 4; ++j4) {
;         const f32x4 a = *(const f32x4*)(amz + i * 68 + j4 * 4);
;         acc -= a[0] * x[j4 * 4 + 0];
;         acc -= a[1] * x[j4 * 4 + 1];
;         acc -= a[2] * x[j4 * 4 + 2];
;         acc -= a[3] * x[j4 * 4 + 3];
;       }
;       asm volatile("" : "+v"(zero), "+v"(acc));
;       x[i] = acc;
;     }
	v_fma_f32 v55, -v41, v60, v55
	v_fma_f32 v55, -v42, v61, v55
	v_fma_f32 v55, -v43, v62, v55
	v_fma_f32 v55, -v44, v63, v55
	ds_read_b128 v[60:63], v3 offset:13776
	s_waitcnt lgkmcnt(1)
	v_fma_f32 v55, -v45, v56, v55
	v_fma_f32 v55, -v46, v57, v55
	v_fma_f32 v55, -v47, v58, v55
	v_fma_f32 v55, -v48, v59, v55
	ds_read_b128 v[56:59], v3 offset:13792
	s_waitcnt lgkmcnt(1)
	v_fma_f32 v3, -v49, v60, v55
	v_fma_f32 v3, -v50, v61, v3
	v_fma_f32 v3, -v51, v62, v3
	v_fma_f32 v3, -v52, v63, v3
	s_waitcnt lgkmcnt(0)
	v_fma_f32 v3, -v53, v56, v3
	v_fma_f32 v55, -v54, v57, v3
	v_fmac_f32_e32 v55, 0x80000000, v58
	v_fmac_f32_e32 v55, 0x80000000, v59
	ds_read_u16 v57, v2 offset:13872
	v_lshlrev_b32_e32 v3, 2, v0
	v_add_u32_e32 v56, s0, v3
	ds_read2_b32 v[60:61], v56 offset0:51 offset1:115
	v_add_u32_e32 v3, 32, v3
	v_add_u32_e32 v3, 0xcc00, v3
	s_waitcnt lgkmcnt(0)
	v_mul_f32_e32 v56, 0x3fb8aa3b, v61
	v_exp_f32_e32 v56, v56
	v_lshlrev_b32_e32 v61, 16, v57
	v_mul_f32_e32 v73, v60, v61
	v_cndmask_b32_e64 v72, v56, 1.0, vcc
	ds_read_b128 v[56:59], v3 offset:13872
	ds_read_b128 v[60:63], v3 offset:13888
	ds_read_b128 v[64:67], v3 offset:13904
	ds_read_b128 v[68:71], v3 offset:13920
	s_waitcnt lgkmcnt(3)
	v_mul_f32_e32 v56, v4, v56
	v_fma_f32 v56, v72, v73, -v56
	v_fma_f32 v56, -v5, v57, v56
	v_fma_f32 v56, -v6, v58, v56
	v_fma_f32 v56, -v7, v59, v56
	s_waitcnt lgkmcnt(2)
	v_fma_f32 v56, -v8, v60, v56
	v_fma_f32 v56, -v9, v61, v56
	v_fma_f32 v56, -v10, v62, v56
	v_fma_f32 v56, -v11, v63, v56
	s_waitcnt lgkmcnt(1)
	v_fma_f32 v56, -v12, v64, v56
	v_fma_f32 v56, -v13, v65, v56
	v_fma_f32 v56, -v14, v66, v56
	v_fma_f32 v56, -v15, v67, v56
	s_waitcnt lgkmcnt(0)
	v_fma_f32 v60, -v16, v68, v56
	ds_read_b128 v[56:59], v3 offset:13936
	v_fma_f32 v60, -v17, v69, v60
	v_fma_f32 v60, -v18, v70, v60
	v_fma_f32 v64, -v19, v71, v60
	ds_read_b128 v[60:63], v3 offset:13952
	s_waitcnt lgkmcnt(1)
	v_fma_f32 v56, -v20, v56, v64
	v_fma_f32 v56, -v21, v57, v56
	v_fma_f32 v56, -v22, v58, v56
	v_fma_f32 v56, -v23, v59, v56
	s_waitcnt lgkmcnt(0)
	v_fma_f32 v60, -v24, v60, v56
	ds_read_b128 v[56:59], v3 offset:13968
	v_fma_f32 v60, -v25, v61, v60
	v_fma_f32 v60, -v26, v62, v60
	v_fma_f32 v64, -v27, v63, v60
	ds_read_b128 v[60:63], v3 offset:13984
	s_waitcnt lgkmcnt(1)
	v_fma_f32 v56, -v28, v56, v64
	v_fma_f32 v56, -v29, v57, v56
	v_fma_f32 v56, -v30, v58, v56
	v_fma_f32 v56, -v31, v59, v56
	s_waitcnt lgkmcnt(0)
	v_fma_f32 v60, -v32, v60, v56
	ds_read_b128 v[56:59], v3 offset:14000
	v_fma_f32 v60, -v33, v61, v60
	v_fma_f32 v60, -v35, v62, v60
	v_fma_f32 v64, -v36, v63, v60
	ds_read_b128 v[60:63], v3 offset:14016
	s_waitcnt lgkmcnt(1)
	v_fma_f32 v56, -v37, v56, v64
	v_fma_f32 v56, -v38, v57, v56
	v_fma_f32 v56, -v39, v58, v56
	v_fma_f32 v56, -v40, v59, v56
	s_waitcnt lgkmcnt(0)
	v_fma_f32 v60, -v41, v60, v56
	ds_read_b128 v[56:59], v3 offset:14032
	v_fma_f32 v60, -v42, v61, v60
	v_fma_f32 v60, -v43, v62, v60
	v_fma_f32 v64, -v44, v63, v60
	ds_read_b128 v[60:63], v3 offset:14048
	s_waitcnt lgkmcnt(1)
	v_fma_f32 v56, -v45, v56, v64
	v_fma_f32 v56, -v46, v57, v56
	v_fma_f32 v56, -v47, v58, v56
	v_fma_f32 v64, -v48, v59, v56
	ds_read_b128 v[56:59], v3 offset:14064
	s_waitcnt lgkmcnt(1)
	v_fma_f32 v3, -v49, v60, v64
	v_fma_f32 v3, -v50, v61, v3
	v_fma_f32 v3, -v51, v62, v3
	v_fma_f32 v3, -v52, v63, v3
	s_waitcnt lgkmcnt(0)
	v_fma_f32 v3, -v53, v56, v3
	v_fma_f32 v3, -v54, v57, v3
	v_fma_f32 v56, -v55, v58, v3
	v_fmac_f32_e32 v56, 0x80000000, v59
	ds_read_u16 v58, v2 offset:14144
	v_lshlrev_b32_e32 v3, 2, v0
	v_add_u32_e32 v57, s0, v3
	ds_read2_b32 v[62:63], v57 offset0:52 offset1:116
	v_add_u32_e32 v3, 32, v3
	v_add_u32_e32 v3, 0xcc00, v3
	s_waitcnt lgkmcnt(0)
	v_mul_f32_e32 v57, 0x3fb8aa3b, v63
	v_lshlrev_b32_e32 v63, 16, v58
	ds_read_b128 v[58:61], v3 offset:14144
	v_exp_f32_e32 v57, v57
	v_mul_f32_e32 v74, v62, v63
	ds_read_b128 v[62:65], v3 offset:14160
	ds_read_b128 v[66:69], v3 offset:14176
	ds_read_b128 v[70:73], v3 offset:14192
	v_cndmask_b32_e64 v57, v57, 1.0, vcc
	s_waitcnt lgkmcnt(3)
	v_mul_f32_e32 v58, v4, v58
	v_fma_f32 v57, v57, v74, -v58
	v_fma_f32 v57, -v5, v59, v57
	v_fma_f32 v57, -v6, v60, v57
	v_fma_f32 v57, -v7, v61, v57
	s_waitcnt lgkmcnt(2)
	v_fma_f32 v57, -v8, v62, v57
	v_fma_f32 v57, -v9, v63, v57
	v_fma_f32 v57, -v10, v64, v57
	v_fma_f32 v57, -v11, v65, v57
	s_waitcnt lgkmcnt(1)
	v_fma_f32 v57, -v12, v66, v57
	v_fma_f32 v57, -v13, v67, v57
	v_fma_f32 v57, -v14, v68, v57
	v_fma_f32 v57, -v15, v69, v57
	ds_read_b128 v[58:61], v3 offset:14208
	s_waitcnt lgkmcnt(1)
	v_fma_f32 v57, -v16, v70, v57
	v_fma_f32 v57, -v17, v71, v57
	v_fma_f32 v57, -v18, v72, v57
	v_fma_f32 v57, -v19, v73, v57
	ds_read_b128 v[62:65], v3 offset:14224
	s_waitcnt lgkmcnt(1)
	v_fma_f32 v57, -v20, v58, v57
	v_fma_f32 v57, -v21, v59, v57
	v_fma_f32 v57, -v22, v60, v57
	v_fma_f32 v57, -v23, v61, v57
	ds_read_b128 v[58:61], v3 offset:14240
	s_waitcnt lgkmcnt(1)
	v_fma_f32 v57, -v24, v62, v57
	v_fma_f32 v57, -v25, v63, v57
	v_fma_f32 v57, -v26, v64, v57
	v_fma_f32 v57, -v27, v65, v57
	ds_read_b128 v[62:65], v3 offset:14256
	s_waitcnt lgkmcnt(1)
	v_fma_f32 v57, -v28, v58, v57
	v_fma_f32 v57, -v29, v59, v57
	v_fma_f32 v57, -v30, v60, v57
	v_fma_f32 v57, -v31, v61, v57
	ds_read_b128 v[58:61], v3 offset:14272
	s_waitcnt lgkmcnt(1)
	v_fma_f32 v57, -v32, v62, v57
	v_fma_f32 v57, -v33, v63, v57
	v_fma_f32 v57, -v35, v64, v57
	v_fma_f32 v57, -v36, v65, v57
	ds_read_b128 v[62:65], v3 offset:14288
	s_waitcnt lgkmcnt(1)
	v_fma_f32 v57, -v37, v58, v57
	v_fma_f32 v57, -v38, v59, v57
	v_fma_f32 v57, -v39, v60, v57
	v_fma_f32 v57, -v40, v61, v57
	ds_read_b128 v[58:61], v3 offset:14304
	s_waitcnt lgkmcnt(1)
; DEVI float bf2f(bf16_t b) { return __uint_as_float(((unsigned)b) << 16); }
; DEVI void prep_item(const Params& p, int j, int n, int h, char* smem) {
;     ...
; #pragma unroll
;     for (int i = 0; i < 64; ++i) {
;       const float* amz = am + zero;
;       const float* sbz = sbeta + zero;
;       const float eg = __expf(sbz[64 + i]);
;       float acc = bf2f(*(const unsigned short*)(src + i * 272)) * sbz[i] * (isu ? 1.0f : eg);
; #pragma unroll
;       for (int j4 = 0; j4 < (i + 3) / 4; ++j4) {
;         const f32x4 a = *(const f32x4*)(amz + i * 68 + j4 * 4);
;         acc -= a[0] * x[j4 * 4 + 0];
;         acc -= a[1] * x[j4 * 4 + 1];
;         acc -= a[2] * x[j4 * 4 + 2];
;         acc -= a[3] * x[j4 * 4 + 3];
;       }
;       asm volatile("" : "+v"(zero), "+v"(acc));
;       x[i] = acc;
;     }
	v_fma_f32 v57, -v41, v62, v57
	v_fma_f32 v57, -v42, v63, v57
	v_fma_f32 v57, -v43, v64, v57
	v_fma_f32 v57, -v44, v65, v57
	ds_read_b128 v[62:65], v3 offset:14320
	s_waitcnt lgkmcnt(1)
	v_fma_f32 v57, -v45, v58, v57
	v_fma_f32 v57, -v46, v59, v57
	v_fma_f32 v57, -v47, v60, v57
	v_fma_f32 v57, -v48, v61, v57
	ds_read_b128 v[58:61], v3 offset:14336
	s_waitcnt lgkmcnt(1)
	v_fma_f32 v3, -v49, v62, v57
	v_fma_f32 v3, -v50, v63, v3
	v_fma_f32 v3, -v51, v64, v3
	v_fma_f32 v3, -v52, v65, v3
	s_waitcnt lgkmcnt(0)
	v_fma_f32 v3, -v53, v58, v3
	v_fma_f32 v3, -v54, v59, v3
	v_fma_f32 v3, -v55, v60, v3
	v_fma_f32 v57, -v56, v61, v3
	ds_read_u16 v59, v2 offset:14416
	v_lshlrev_b32_e32 v3, 2, v0
	v_add_u32_e32 v58, s0, v3
	ds_read2_b32 v[62:63], v58 offset0:53 offset1:117
	v_add_u32_e32 v3, 32, v3
	v_add_u32_e32 v3, 0xcc00, v3
	s_waitcnt lgkmcnt(0)
	v_mul_f32_e32 v58, 0x3fb8aa3b, v63
	v_exp_f32_e32 v58, v58
	v_lshlrev_b32_e32 v63, 16, v59
	v_mul_f32_e32 v75, v62, v63
	v_cndmask_b32_e64 v74, v58, 1.0, vcc
	ds_read_b128 v[58:61], v3 offset:14416
	ds_read_b128 v[62:65], v3 offset:14432
	ds_read_b128 v[66:69], v3 offset:14448
	ds_read_b128 v[70:73], v3 offset:14464
	s_waitcnt lgkmcnt(3)
	v_mul_f32_e32 v58, v4, v58
	v_fma_f32 v58, v74, v75, -v58
	v_fma_f32 v58, -v5, v59, v58
	v_fma_f32 v58, -v6, v60, v58
	v_fma_f32 v58, -v7, v61, v58
	s_waitcnt lgkmcnt(2)
	v_fma_f32 v58, -v8, v62, v58
	v_fma_f32 v58, -v9, v63, v58
	v_fma_f32 v58, -v10, v64, v58
	v_fma_f32 v58, -v11, v65, v58
	s_waitcnt lgkmcnt(1)
	v_fma_f32 v58, -v12, v66, v58
	v_fma_f32 v58, -v13, v67, v58
	v_fma_f32 v58, -v14, v68, v58
	v_fma_f32 v58, -v15, v69, v58
	s_waitcnt lgkmcnt(0)
	v_fma_f32 v62, -v16, v70, v58
	ds_read_b128 v[58:61], v3 offset:14480
	v_fma_f32 v62, -v17, v71, v62
	v_fma_f32 v62, -v18, v72, v62
	v_fma_f32 v66, -v19, v73, v62
	ds_read_b128 v[62:65], v3 offset:14496
	s_waitcnt lgkmcnt(1)
	v_fma_f32 v58, -v20, v58, v66
	v_fma_f32 v58, -v21, v59, v58
	v_fma_f32 v58, -v22, v60, v58
	v_fma_f32 v58, -v23, v61, v58
	s_waitcnt lgkmcnt(0)
	v_fma_f32 v62, -v24, v62, v58
	ds_read_b128 v[58:61], v3 offset:14512
	v_fma_f32 v62, -v25, v63, v62
	v_fma_f32 v62, -v26, v64, v62
	v_fma_f32 v66, -v27, v65, v62
	ds_read_b128 v[62:65], v3 offset:14528
	s_waitcnt lgkmcnt(1)
	v_fma_f32 v58, -v28, v58, v66
	v_fma_f32 v58, -v29, v59, v58
	v_fma_f32 v58, -v30, v60, v58
	v_fma_f32 v58, -v31, v61, v58
	s_waitcnt lgkmcnt(0)
	v_fma_f32 v62, -v32, v62, v58
	ds_read_b128 v[58:61], v3 offset:14544
	v_fma_f32 v62, -v33, v63, v62
	v_fma_f32 v62, -v35, v64, v62
	v_fma_f32 v66, -v36, v65, v62
	ds_read_b128 v[62:65], v3 offset:14560
	s_waitcnt lgkmcnt(1)
	v_fma_f32 v58, -v37, v58, v66
	v_fma_f32 v58, -v38, v59, v58
	v_fma_f32 v58, -v39, v60, v58
	v_fma_f32 v58, -v40, v61, v58
	s_waitcnt lgkmcnt(0)
	v_fma_f32 v62, -v41, v62, v58
	ds_read_b128 v[58:61], v3 offset:14576
	v_fma_f32 v62, -v42, v63, v62
	v_fma_f32 v62, -v43, v64, v62
	v_fma_f32 v66, -v44, v65, v62
	ds_read_b128 v[62:65], v3 offset:14592
	s_waitcnt lgkmcnt(1)
	v_fma_f32 v58, -v45, v58, v66
	v_fma_f32 v58, -v46, v59, v58
	v_fma_f32 v58, -v47, v60, v58
	v_fma_f32 v58, -v48, v61, v58
	s_waitcnt lgkmcnt(0)
	v_fma_f32 v62, -v49, v62, v58
	ds_read_b128 v[58:61], v3 offset:14608
	v_fma_f32 v62, -v50, v63, v62
	v_fma_f32 v62, -v51, v64, v62
	v_fma_f32 v66, -v52, v65, v62
	ds_read_b128 v[62:65], v3 offset:14624
	s_waitcnt lgkmcnt(1)
	v_fma_f32 v3, -v53, v58, v66
	v_fma_f32 v3, -v54, v59, v3
	v_fma_f32 v3, -v55, v60, v3
	v_fma_f32 v3, -v56, v61, v3
	s_waitcnt lgkmcnt(0)
	v_fma_f32 v58, -v57, v62, v3
	v_fmac_f32_e32 v58, 0x80000000, v63
	v_fmac_f32_e32 v58, 0x80000000, v64
	v_fmac_f32_e32 v58, 0x80000000, v65
	ds_read_u16 v60, v2 offset:14688
	v_lshlrev_b32_e32 v3, 2, v0
	v_add_u32_e32 v59, s0, v3
	ds_read2_b32 v[64:65], v59 offset0:54 offset1:118
	v_add_u32_e32 v3, 32, v3
	v_add_u32_e32 v3, 0xcc00, v3
	s_waitcnt lgkmcnt(0)
	v_mul_f32_e32 v59, 0x3fb8aa3b, v65
	v_lshlrev_b32_e32 v65, 16, v60
	ds_read_b128 v[60:63], v3 offset:14688
	v_exp_f32_e32 v59, v59
	v_mul_f32_e32 v76, v64, v65
	ds_read_b128 v[64:67], v3 offset:14704
	ds_read_b128 v[68:71], v3 offset:14720
	ds_read_b128 v[72:75], v3 offset:14736
	v_cndmask_b32_e64 v59, v59, 1.0, vcc
	s_waitcnt lgkmcnt(3)
	v_mul_f32_e32 v60, v4, v60
	v_fma_f32 v59, v59, v76, -v60
	v_fma_f32 v59, -v5, v61, v59
	v_fma_f32 v59, -v6, v62, v59
	v_fma_f32 v59, -v7, v63, v59
	s_waitcnt lgkmcnt(2)
	v_fma_f32 v59, -v8, v64, v59
	v_fma_f32 v59, -v9, v65, v59
	v_fma_f32 v59, -v10, v66, v59
	v_fma_f32 v59, -v11, v67, v59
	s_waitcnt lgkmcnt(1)
	v_fma_f32 v59, -v12, v68, v59
	v_fma_f32 v59, -v13, v69, v59
	v_fma_f32 v59, -v14, v70, v59
	v_fma_f32 v59, -v15, v71, v59
	ds_read_b128 v[60:63], v3 offset:14752
	s_waitcnt lgkmcnt(1)
	v_fma_f32 v59, -v16, v72, v59
	v_fma_f32 v59, -v17, v73, v59
	v_fma_f32 v59, -v18, v74, v59
	v_fma_f32 v59, -v19, v75, v59
	ds_read_b128 v[64:67], v3 offset:14768
	s_waitcnt lgkmcnt(1)
	v_fma_f32 v59, -v20, v60, v59
	v_fma_f32 v59, -v21, v61, v59
	v_fma_f32 v59, -v22, v62, v59
	v_fma_f32 v59, -v23, v63, v59
	ds_read_b128 v[60:63], v3 offset:14784
	s_waitcnt lgkmcnt(1)
	v_fma_f32 v59, -v24, v64, v59
	v_fma_f32 v59, -v25, v65, v59
	v_fma_f32 v59, -v26, v66, v59
	v_fma_f32 v59, -v27, v67, v59
	ds_read_b128 v[64:67], v3 offset:14800
	s_waitcnt lgkmcnt(1)
	v_fma_f32 v59, -v28, v60, v59
	v_fma_f32 v59, -v29, v61, v59
	v_fma_f32 v59, -v30, v62, v59
	v_fma_f32 v59, -v31, v63, v59
	ds_read_b128 v[60:63], v3 offset:14816
	s_waitcnt lgkmcnt(1)
	v_fma_f32 v59, -v32, v64, v59
	v_fma_f32 v59, -v33, v65, v59
	v_fma_f32 v59, -v35, v66, v59
	v_fma_f32 v59, -v36, v67, v59
	ds_read_b128 v[64:67], v3 offset:14832
	s_waitcnt lgkmcnt(1)
; DEVI float bf2f(bf16_t b) { return __uint_as_float(((unsigned)b) << 16); }
; DEVI void prep_item(const Params& p, int j, int n, int h, char* smem) {
;     ...
; #pragma unroll
;     for (int i = 0; i < 64; ++i) {
;       const float* amz = am + zero;
;       const float* sbz = sbeta + zero;
;       const float eg = __expf(sbz[64 + i]);
;       float acc = bf2f(*(const unsigned short*)(src + i * 272)) * sbz[i] * (isu ? 1.0f : eg);
; #pragma unroll
;       for (int j4 = 0; j4 < (i + 3) / 4; ++j4) {
;         const f32x4 a = *(const f32x4*)(amz + i * 68 + j4 * 4);
;         acc -= a[0] * x[j4 * 4 + 0];
;         acc -= a[1] * x[j4 * 4 + 1];
;         acc -= a[2] * x[j4 * 4 + 2];
;         acc -= a[3] * x[j4 * 4 + 3];
;       }
;       asm volatile("" : "+v"(zero), "+v"(acc));
;       x[i] = acc;
;     }
	v_fma_f32 v59, -v37, v60, v59
	v_fma_f32 v59, -v38, v61, v59
	v_fma_f32 v59, -v39, v62, v59
	v_fma_f32 v59, -v40, v63, v59
	ds_read_b128 v[60:63], v3 offset:14848
	s_waitcnt lgkmcnt(1)
	v_fma_f32 v59, -v41, v64, v59
	v_fma_f32 v59, -v42, v65, v59
	v_fma_f32 v59, -v43, v66, v59
	v_fma_f32 v59, -v44, v67, v59
	ds_read_b128 v[64:67], v3 offset:14864
	s_waitcnt lgkmcnt(1)
	v_fma_f32 v59, -v45, v60, v59
	v_fma_f32 v59, -v46, v61, v59
	v_fma_f32 v59, -v47, v62, v59
	v_fma_f32 v59, -v48, v63, v59
	ds_read_b128 v[60:63], v3 offset:14880
	s_waitcnt lgkmcnt(1)
	v_fma_f32 v59, -v49, v64, v59
	v_fma_f32 v59, -v50, v65, v59
	v_fma_f32 v59, -v51, v66, v59
	v_fma_f32 v59, -v52, v67, v59
	ds_read_b128 v[64:67], v3 offset:14896
	s_waitcnt lgkmcnt(1)
	v_fma_f32 v3, -v53, v60, v59
	v_fma_f32 v3, -v54, v61, v3
	v_fma_f32 v3, -v55, v62, v3
	v_fma_f32 v3, -v56, v63, v3
	s_waitcnt lgkmcnt(0)
	v_fma_f32 v3, -v57, v64, v3
	v_fma_f32 v59, -v58, v65, v3
	v_fmac_f32_e32 v59, 0x80000000, v66
	v_fmac_f32_e32 v59, 0x80000000, v67
	ds_read_u16 v61, v2 offset:14960
	v_lshlrev_b32_e32 v3, 2, v0
	v_add_u32_e32 v60, s0, v3
	ds_read2_b32 v[64:65], v60 offset0:55 offset1:119
	v_add_u32_e32 v3, 32, v3
	v_add_u32_e32 v3, 0xcc00, v3
	s_waitcnt lgkmcnt(0)
	v_mul_f32_e32 v60, 0x3fb8aa3b, v65
	v_exp_f32_e32 v60, v60
	v_lshlrev_b32_e32 v65, 16, v61
	v_mul_f32_e32 v77, v64, v65
	v_cndmask_b32_e64 v76, v60, 1.0, vcc
	ds_read_b128 v[60:63], v3 offset:14960
	ds_read_b128 v[64:67], v3 offset:14976
	ds_read_b128 v[68:71], v3 offset:14992
	ds_read_b128 v[72:75], v3 offset:15008
	s_waitcnt lgkmcnt(3)
	v_mul_f32_e32 v60, v4, v60
	v_fma_f32 v60, v76, v77, -v60
	v_fma_f32 v60, -v5, v61, v60
	v_fma_f32 v60, -v6, v62, v60
	v_fma_f32 v60, -v7, v63, v60
	s_waitcnt lgkmcnt(2)
	v_fma_f32 v60, -v8, v64, v60
	v_fma_f32 v60, -v9, v65, v60
	v_fma_f32 v60, -v10, v66, v60
	v_fma_f32 v60, -v11, v67, v60
	s_waitcnt lgkmcnt(1)
	v_fma_f32 v60, -v12, v68, v60
	v_fma_f32 v60, -v13, v69, v60
	v_fma_f32 v60, -v14, v70, v60
	v_fma_f32 v60, -v15, v71, v60
	s_waitcnt lgkmcnt(0)
	v_fma_f32 v64, -v16, v72, v60
	ds_read_b128 v[60:63], v3 offset:15024
	v_fma_f32 v64, -v17, v73, v64
	v_fma_f32 v64, -v18, v74, v64
	v_fma_f32 v68, -v19, v75, v64
	ds_read_b128 v[64:67], v3 offset:15040
	s_waitcnt lgkmcnt(1)
	v_fma_f32 v60, -v20, v60, v68
	v_fma_f32 v60, -v21, v61, v60
	v_fma_f32 v60, -v22, v62, v60
	v_fma_f32 v60, -v23, v63, v60
	s_waitcnt lgkmcnt(0)
	v_fma_f32 v64, -v24, v64, v60
	ds_read_b128 v[60:63], v3 offset:15056
	v_fma_f32 v64, -v25, v65, v64
	v_fma_f32 v64, -v26, v66, v64
	v_fma_f32 v68, -v27, v67, v64
	ds_read_b128 v[64:67], v3 offset:15072
	s_waitcnt lgkmcnt(1)
	v_fma_f32 v60, -v28, v60, v68
	v_fma_f32 v60, -v29, v61, v60
	v_fma_f32 v60, -v30, v62, v60
	v_fma_f32 v60, -v31, v63, v60
	s_waitcnt lgkmcnt(0)
	v_fma_f32 v64, -v32, v64, v60
	ds_read_b128 v[60:63], v3 offset:15088
	v_fma_f32 v64, -v33, v65, v64
	v_fma_f32 v64, -v35, v66, v64
	v_fma_f32 v68, -v36, v67, v64
	ds_read_b128 v[64:67], v3 offset:15104
	s_waitcnt lgkmcnt(1)
	v_fma_f32 v60, -v37, v60, v68
	v_fma_f32 v60, -v38, v61, v60
	v_fma_f32 v60, -v39, v62, v60
	v_fma_f32 v60, -v40, v63, v60
	s_waitcnt lgkmcnt(0)
	v_fma_f32 v64, -v41, v64, v60
	ds_read_b128 v[60:63], v3 offset:15120
	v_fma_f32 v64, -v42, v65, v64
	v_fma_f32 v64, -v43, v66, v64
	v_fma_f32 v68, -v44, v67, v64
	ds_read_b128 v[64:67], v3 offset:15136
	s_waitcnt lgkmcnt(1)
	v_fma_f32 v60, -v45, v60, v68
	v_fma_f32 v60, -v46, v61, v60
	v_fma_f32 v60, -v47, v62, v60
	v_fma_f32 v60, -v48, v63, v60
	s_waitcnt lgkmcnt(0)
	v_fma_f32 v64, -v49, v64, v60
	ds_read_b128 v[60:63], v3 offset:15152
	v_fma_f32 v64, -v50, v65, v64
	v_fma_f32 v64, -v51, v66, v64
	v_fma_f32 v68, -v52, v67, v64
	ds_read_b128 v[64:67], v3 offset:15168
	s_waitcnt lgkmcnt(1)
	v_fma_f32 v3, -v53, v60, v68
	v_fma_f32 v3, -v54, v61, v3
	v_fma_f32 v3, -v55, v62, v3
	v_fma_f32 v3, -v56, v63, v3
	s_waitcnt lgkmcnt(0)
	v_fma_f32 v3, -v57, v64, v3
	v_fma_f32 v3, -v58, v65, v3
	v_fma_f32 v60, -v59, v66, v3
	v_fmac_f32_e32 v60, 0x80000000, v67
	ds_read_u16 v62, v2 offset:15232
	v_lshlrev_b32_e32 v3, 2, v0
	v_add_u32_e32 v61, s0, v3
	ds_read2_b32 v[66:67], v61 offset0:56 offset1:120
	v_add_u32_e32 v3, 32, v3
	v_add_u32_e32 v3, 0xcc00, v3
	s_waitcnt lgkmcnt(0)
	v_mul_f32_e32 v61, 0x3fb8aa3b, v67
	v_lshlrev_b32_e32 v67, 16, v62
	ds_read_b128 v[62:65], v3 offset:15232
	v_exp_f32_e32 v61, v61
	v_mul_f32_e32 v78, v66, v67
	ds_read_b128 v[66:69], v3 offset:15248
	ds_read_b128 v[70:73], v3 offset:15264
	ds_read_b128 v[74:77], v3 offset:15280
	v_cndmask_b32_e64 v61, v61, 1.0, vcc
	s_waitcnt lgkmcnt(3)
	v_mul_f32_e32 v62, v4, v62
	v_fma_f32 v61, v61, v78, -v62
	v_fma_f32 v61, -v5, v63, v61
	v_fma_f32 v61, -v6, v64, v61
	v_fma_f32 v61, -v7, v65, v61
	s_waitcnt lgkmcnt(2)
	v_fma_f32 v61, -v8, v66, v61
	v_fma_f32 v61, -v9, v67, v61
	v_fma_f32 v61, -v10, v68, v61
	v_fma_f32 v61, -v11, v69, v61
	s_waitcnt lgkmcnt(1)
	v_fma_f32 v61, -v12, v70, v61
	v_fma_f32 v61, -v13, v71, v61
	v_fma_f32 v61, -v14, v72, v61
	v_fma_f32 v61, -v15, v73, v61
	ds_read_b128 v[62:65], v3 offset:15296
	s_waitcnt lgkmcnt(1)
	v_fma_f32 v61, -v16, v74, v61
	v_fma_f32 v61, -v17, v75, v61
	v_fma_f32 v61, -v18, v76, v61
	v_fma_f32 v61, -v19, v77, v61
	ds_read_b128 v[66:69], v3 offset:15312
	s_waitcnt lgkmcnt(1)
	v_fma_f32 v61, -v20, v62, v61
	v_fma_f32 v61, -v21, v63, v61
	v_fma_f32 v61, -v22, v64, v61
	v_fma_f32 v61, -v23, v65, v61
	ds_read_b128 v[62:65], v3 offset:15328
	s_waitcnt lgkmcnt(1)
	v_fma_f32 v61, -v24, v66, v61
	v_fma_f32 v61, -v25, v67, v61
	v_fma_f32 v61, -v26, v68, v61
	v_fma_f32 v61, -v27, v69, v61
	ds_read_b128 v[66:69], v3 offset:15344
	s_waitcnt lgkmcnt(1)
; DEVI float bf2f(bf16_t b) { return __uint_as_float(((unsigned)b) << 16); }
; DEVI void prep_item(const Params& p, int j, int n, int h, char* smem) {
;     ...
; #pragma unroll
;     for (int i = 0; i < 64; ++i) {
;       const float* amz = am + zero;
;       const float* sbz = sbeta + zero;
;       const float eg = __expf(sbz[64 + i]);
;       float acc = bf2f(*(const unsigned short*)(src + i * 272)) * sbz[i] * (isu ? 1.0f : eg);
; #pragma unroll
;       for (int j4 = 0; j4 < (i + 3) / 4; ++j4) {
;         const f32x4 a = *(const f32x4*)(amz + i * 68 + j4 * 4);
;         acc -= a[0] * x[j4 * 4 + 0];
;         acc -= a[1] * x[j4 * 4 + 1];
;         acc -= a[2] * x[j4 * 4 + 2];
;         acc -= a[3] * x[j4 * 4 + 3];
;       }
;       asm volatile("" : "+v"(zero), "+v"(acc));
;       x[i] = acc;
;     }
	v_fma_f32 v61, -v28, v62, v61
	v_fma_f32 v61, -v29, v63, v61
	v_fma_f32 v61, -v30, v64, v61
	v_fma_f32 v61, -v31, v65, v61
	ds_read_b128 v[62:65], v3 offset:15360
	s_waitcnt lgkmcnt(1)
	v_fma_f32 v61, -v32, v66, v61
	v_fma_f32 v61, -v33, v67, v61
	v_fma_f32 v61, -v35, v68, v61
	v_fma_f32 v61, -v36, v69, v61
	ds_read_b128 v[66:69], v3 offset:15376
	s_waitcnt lgkmcnt(1)
	v_fma_f32 v61, -v37, v62, v61
	v_fma_f32 v61, -v38, v63, v61
	v_fma_f32 v61, -v39, v64, v61
	v_fma_f32 v61, -v40, v65, v61
	ds_read_b128 v[62:65], v3 offset:15392
	s_waitcnt lgkmcnt(1)
	v_fma_f32 v61, -v41, v66, v61
	v_fma_f32 v61, -v42, v67, v61
	v_fma_f32 v61, -v43, v68, v61
	v_fma_f32 v61, -v44, v69, v61
	ds_read_b128 v[66:69], v3 offset:15408
	s_waitcnt lgkmcnt(1)
	v_fma_f32 v61, -v45, v62, v61
	v_fma_f32 v61, -v46, v63, v61
	v_fma_f32 v61, -v47, v64, v61
	v_fma_f32 v61, -v48, v65, v61
	ds_read_b128 v[62:65], v3 offset:15424
	s_waitcnt lgkmcnt(1)
	v_fma_f32 v61, -v49, v66, v61
	v_fma_f32 v61, -v50, v67, v61
	v_fma_f32 v61, -v51, v68, v61
	v_fma_f32 v61, -v52, v69, v61
	ds_read_b128 v[66:69], v3 offset:15440
	s_waitcnt lgkmcnt(1)
	v_fma_f32 v3, -v53, v62, v61
	v_fma_f32 v3, -v54, v63, v3
	v_fma_f32 v3, -v55, v64, v3
	v_fma_f32 v3, -v56, v65, v3
	s_waitcnt lgkmcnt(0)
	v_fma_f32 v3, -v57, v66, v3
	v_fma_f32 v3, -v58, v67, v3
	v_fma_f32 v3, -v59, v68, v3
	v_fma_f32 v61, -v60, v69, v3
	ds_read_u16 v63, v2 offset:15504
	v_lshlrev_b32_e32 v3, 2, v0
	v_add_u32_e32 v62, s0, v3
	ds_read2_b32 v[66:67], v62 offset0:57 offset1:121
	v_add_u32_e32 v3, 32, v3
	v_add_u32_e32 v3, 0xcc00, v3
	s_waitcnt lgkmcnt(0)
	v_mul_f32_e32 v62, 0x3fb8aa3b, v67
	v_exp_f32_e32 v62, v62
	v_lshlrev_b32_e32 v67, 16, v63
	v_mul_f32_e32 v79, v66, v67
	v_cndmask_b32_e64 v78, v62, 1.0, vcc
	ds_read_b128 v[62:65], v3 offset:15504
	ds_read_b128 v[66:69], v3 offset:15520
	ds_read_b128 v[70:73], v3 offset:15536
	ds_read_b128 v[74:77], v3 offset:15552
	s_waitcnt lgkmcnt(3)
	v_mul_f32_e32 v62, v4, v62
	v_fma_f32 v62, v78, v79, -v62
	v_fma_f32 v62, -v5, v63, v62
	v_fma_f32 v62, -v6, v64, v62
	v_fma_f32 v62, -v7, v65, v62
	s_waitcnt lgkmcnt(2)
	v_fma_f32 v62, -v8, v66, v62
	v_fma_f32 v62, -v9, v67, v62
	v_fma_f32 v62, -v10, v68, v62
	v_fma_f32 v62, -v11, v69, v62
	s_waitcnt lgkmcnt(1)
	v_fma_f32 v62, -v12, v70, v62
	v_fma_f32 v62, -v13, v71, v62
	v_fma_f32 v62, -v14, v72, v62
	v_fma_f32 v62, -v15, v73, v62
	s_waitcnt lgkmcnt(0)
	v_fma_f32 v66, -v16, v74, v62
	ds_read_b128 v[62:65], v3 offset:15568
	v_fma_f32 v66, -v17, v75, v66
	v_fma_f32 v66, -v18, v76, v66
	v_fma_f32 v70, -v19, v77, v66
	ds_read_b128 v[66:69], v3 offset:15584
	s_waitcnt lgkmcnt(1)
	v_fma_f32 v62, -v20, v62, v70
	v_fma_f32 v62, -v21, v63, v62
	v_fma_f32 v62, -v22, v64, v62
	v_fma_f32 v62, -v23, v65, v62
	s_waitcnt lgkmcnt(0)
	v_fma_f32 v66, -v24, v66, v62
	ds_read_b128 v[62:65], v3 offset:15600
	v_fma_f32 v66, -v25, v67, v66
	v_fma_f32 v66, -v26, v68, v66
	v_fma_f32 v70, -v27, v69, v66
	ds_read_b128 v[66:69], v3 offset:15616
	s_waitcnt lgkmcnt(1)
	v_fma_f32 v62, -v28, v62, v70
	v_fma_f32 v62, -v29, v63, v62
	v_fma_f32 v62, -v30, v64, v62
	v_fma_f32 v62, -v31, v65, v62
	s_waitcnt lgkmcnt(0)
	v_fma_f32 v66, -v32, v66, v62
	ds_read_b128 v[62:65], v3 offset:15632
	v_fma_f32 v66, -v33, v67, v66
	v_fma_f32 v66, -v35, v68, v66
	v_fma_f32 v70, -v36, v69, v66
	ds_read_b128 v[66:69], v3 offset:15648
	s_waitcnt lgkmcnt(1)
	v_fma_f32 v62, -v37, v62, v70
	v_fma_f32 v62, -v38, v63, v62
	v_fma_f32 v62, -v39, v64, v62
	v_fma_f32 v62, -v40, v65, v62
	s_waitcnt lgkmcnt(0)
	v_fma_f32 v66, -v41, v66, v62
	ds_read_b128 v[62:65], v3 offset:15664
	v_fma_f32 v66, -v42, v67, v66
	v_fma_f32 v66, -v43, v68, v66
	v_fma_f32 v70, -v44, v69, v66
	ds_read_b128 v[66:69], v3 offset:15680
	s_waitcnt lgkmcnt(1)
	v_fma_f32 v62, -v45, v62, v70
	v_fma_f32 v62, -v46, v63, v62
	v_fma_f32 v62, -v47, v64, v62
	v_fma_f32 v62, -v48, v65, v62
	s_waitcnt lgkmcnt(0)
	v_fma_f32 v66, -v49, v66, v62
	ds_read_b128 v[62:65], v3 offset:15696
	v_fma_f32 v66, -v50, v67, v66
	v_fma_f32 v66, -v51, v68, v66
	v_fma_f32 v70, -v52, v69, v66
	ds_read_b128 v[66:69], v3 offset:15712
	s_waitcnt lgkmcnt(1)
	v_fma_f32 v62, -v53, v62, v70
	v_fma_f32 v62, -v54, v63, v62
	v_fma_f32 v62, -v55, v64, v62
	v_fma_f32 v70, -v56, v65, v62
	ds_read_b128 v[62:65], v3 offset:15728
	s_waitcnt lgkmcnt(1)
	v_fma_f32 v3, -v57, v66, v70
	v_fma_f32 v3, -v58, v67, v3
	v_fma_f32 v3, -v59, v68, v3
	v_fma_f32 v3, -v60, v69, v3
	s_waitcnt lgkmcnt(0)
	v_fma_f32 v62, -v61, v62, v3
	v_fmac_f32_e32 v62, 0x80000000, v63
	v_fmac_f32_e32 v62, 0x80000000, v64
	v_fmac_f32_e32 v62, 0x80000000, v65
	ds_read_u16 v64, v2 offset:15776
	v_lshlrev_b32_e32 v3, 2, v0
	v_add_u32_e32 v63, s0, v3
	ds_read2_b32 v[68:69], v63 offset0:58 offset1:122
	v_add_u32_e32 v3, 32, v3
	v_add_u32_e32 v3, 0xcc00, v3
	s_waitcnt lgkmcnt(0)
	v_mul_f32_e32 v63, 0x3fb8aa3b, v69
	v_lshlrev_b32_e32 v69, 16, v64
	ds_read_b128 v[64:67], v3 offset:15776
	v_exp_f32_e32 v63, v63
	v_mul_f32_e32 v80, v68, v69
	ds_read_b128 v[68:71], v3 offset:15792
	ds_read_b128 v[72:75], v3 offset:15808
	ds_read_b128 v[76:79], v3 offset:15824
	v_cndmask_b32_e64 v63, v63, 1.0, vcc
	s_waitcnt lgkmcnt(3)
	v_mul_f32_e32 v64, v4, v64
	v_fma_f32 v63, v63, v80, -v64
	v_fma_f32 v63, -v5, v65, v63
	v_fma_f32 v63, -v6, v66, v63
	v_fma_f32 v63, -v7, v67, v63
	s_waitcnt lgkmcnt(2)
	v_fma_f32 v63, -v8, v68, v63
	v_fma_f32 v63, -v9, v69, v63
	v_fma_f32 v63, -v10, v70, v63
	v_fma_f32 v63, -v11, v71, v63
	s_waitcnt lgkmcnt(1)
	v_fma_f32 v63, -v12, v72, v63
	v_fma_f32 v63, -v13, v73, v63
	v_fma_f32 v63, -v14, v74, v63
	v_fma_f32 v63, -v15, v75, v63
	ds_read_b128 v[64:67], v3 offset:15840
	s_waitcnt lgkmcnt(1)
; DEVI float bf2f(bf16_t b) { return __uint_as_float(((unsigned)b) << 16); }
; DEVI void prep_item(const Params& p, int j, int n, int h, char* smem) {
;     ...
; #pragma unroll
;     for (int i = 0; i < 64; ++i) {
;       const float* amz = am + zero;
;       const float* sbz = sbeta + zero;
;       const float eg = __expf(sbz[64 + i]);
;       float acc = bf2f(*(const unsigned short*)(src + i * 272)) * sbz[i] * (isu ? 1.0f : eg);
; #pragma unroll
;       for (int j4 = 0; j4 < (i + 3) / 4; ++j4) {
;         const f32x4 a = *(const f32x4*)(amz + i * 68 + j4 * 4);
;         acc -= a[0] * x[j4 * 4 + 0];
;         acc -= a[1] * x[j4 * 4 + 1];
;         acc -= a[2] * x[j4 * 4 + 2];
;         acc -= a[3] * x[j4 * 4 + 3];
;       }
;       asm volatile("" : "+v"(zero), "+v"(acc));
;       x[i] = acc;
;     }
	v_fma_f32 v63, -v16, v76, v63
	v_fma_f32 v63, -v17, v77, v63
	v_fma_f32 v63, -v18, v78, v63
	v_fma_f32 v63, -v19, v79, v63
	ds_read_b128 v[68:71], v3 offset:15856
	s_waitcnt lgkmcnt(1)
	v_fma_f32 v63, -v20, v64, v63
	v_fma_f32 v63, -v21, v65, v63
	v_fma_f32 v63, -v22, v66, v63
	v_fma_f32 v63, -v23, v67, v63
	ds_read_b128 v[64:67], v3 offset:15872
	s_waitcnt lgkmcnt(1)
	v_fma_f32 v63, -v24, v68, v63
	v_fma_f32 v63, -v25, v69, v63
	v_fma_f32 v63, -v26, v70, v63
	v_fma_f32 v63, -v27, v71, v63
	ds_read_b128 v[68:71], v3 offset:15888
	s_waitcnt lgkmcnt(1)
	v_fma_f32 v63, -v28, v64, v63
	v_fma_f32 v63, -v29, v65, v63
	v_fma_f32 v63, -v30, v66, v63
	v_fma_f32 v63, -v31, v67, v63
	ds_read_b128 v[64:67], v3 offset:15904
	s_waitcnt lgkmcnt(1)
	v_fma_f32 v63, -v32, v68, v63
	v_fma_f32 v63, -v33, v69, v63
	v_fma_f32 v63, -v35, v70, v63
	v_fma_f32 v63, -v36, v71, v63
	ds_read_b128 v[68:71], v3 offset:15920
	s_waitcnt lgkmcnt(1)
	v_fma_f32 v63, -v37, v64, v63
	v_fma_f32 v63, -v38, v65, v63
	v_fma_f32 v63, -v39, v66, v63
	v_fma_f32 v63, -v40, v67, v63
	ds_read_b128 v[64:67], v3 offset:15936
	s_waitcnt lgkmcnt(1)
	v_fma_f32 v63, -v41, v68, v63
	v_fma_f32 v63, -v42, v69, v63
	v_fma_f32 v63, -v43, v70, v63
	v_fma_f32 v63, -v44, v71, v63
	ds_read_b128 v[68:71], v3 offset:15952
	s_waitcnt lgkmcnt(1)
	v_fma_f32 v63, -v45, v64, v63
	v_fma_f32 v63, -v46, v65, v63
	v_fma_f32 v63, -v47, v66, v63
	v_fma_f32 v63, -v48, v67, v63
	ds_read_b128 v[64:67], v3 offset:15968
	s_waitcnt lgkmcnt(1)
	v_fma_f32 v63, -v49, v68, v63
	v_fma_f32 v63, -v50, v69, v63
	v_fma_f32 v63, -v51, v70, v63
	v_fma_f32 v63, -v52, v71, v63
	ds_read_b128 v[68:71], v3 offset:15984
	s_waitcnt lgkmcnt(1)
	v_fma_f32 v63, -v53, v64, v63
	v_fma_f32 v63, -v54, v65, v63
	v_fma_f32 v63, -v55, v66, v63
	v_fma_f32 v63, -v56, v67, v63
	ds_read_b128 v[64:67], v3 offset:16000
	s_waitcnt lgkmcnt(1)
	v_fma_f32 v3, -v57, v68, v63
	v_fma_f32 v3, -v58, v69, v3
	v_fma_f32 v3, -v59, v70, v3
	v_fma_f32 v3, -v60, v71, v3
	s_waitcnt lgkmcnt(0)
	v_fma_f32 v3, -v61, v64, v3
	v_fma_f32 v63, -v62, v65, v3
	v_fmac_f32_e32 v63, 0x80000000, v66
	v_fmac_f32_e32 v63, 0x80000000, v67
	ds_read_u16 v65, v2 offset:16048
	v_lshlrev_b32_e32 v3, 2, v0
	v_add_u32_e32 v64, s0, v3
	ds_read2_b32 v[68:69], v64 offset0:59 offset1:123
	v_add_u32_e32 v3, 32, v3
	v_add_u32_e32 v3, 0xcc00, v3
	s_waitcnt lgkmcnt(0)
	v_mul_f32_e32 v64, 0x3fb8aa3b, v69
	v_exp_f32_e32 v64, v64
	v_lshlrev_b32_e32 v69, 16, v65
	v_mul_f32_e32 v81, v68, v69
	v_cndmask_b32_e64 v80, v64, 1.0, vcc
	ds_read_b128 v[64:67], v3 offset:16048
	ds_read_b128 v[68:71], v3 offset:16064
	ds_read_b128 v[72:75], v3 offset:16080
	ds_read_b128 v[76:79], v3 offset:16096
	s_waitcnt lgkmcnt(3)
	v_mul_f32_e32 v64, v4, v64
	v_fma_f32 v64, v80, v81, -v64
	v_fma_f32 v64, -v5, v65, v64
	v_fma_f32 v64, -v6, v66, v64
	v_fma_f32 v64, -v7, v67, v64
	s_waitcnt lgkmcnt(2)
	v_fma_f32 v64, -v8, v68, v64
	v_fma_f32 v64, -v9, v69, v64
	v_fma_f32 v64, -v10, v70, v64
	v_fma_f32 v64, -v11, v71, v64
	s_waitcnt lgkmcnt(1)
	v_fma_f32 v64, -v12, v72, v64
	v_fma_f32 v64, -v13, v73, v64
	v_fma_f32 v64, -v14, v74, v64
	v_fma_f32 v64, -v15, v75, v64
	s_waitcnt lgkmcnt(0)
	v_fma_f32 v68, -v16, v76, v64
	ds_read_b128 v[64:67], v3 offset:16112
	v_fma_f32 v68, -v17, v77, v68
	v_fma_f32 v68, -v18, v78, v68
	v_fma_f32 v72, -v19, v79, v68
	ds_read_b128 v[68:71], v3 offset:16128
	s_waitcnt lgkmcnt(1)
	v_fma_f32 v64, -v20, v64, v72
	v_fma_f32 v64, -v21, v65, v64
	v_fma_f32 v64, -v22, v66, v64
	v_fma_f32 v64, -v23, v67, v64
	s_waitcnt lgkmcnt(0)
	v_fma_f32 v68, -v24, v68, v64
	ds_read_b128 v[64:67], v3 offset:16144
	v_fma_f32 v68, -v25, v69, v68
	v_fma_f32 v68, -v26, v70, v68
	v_fma_f32 v72, -v27, v71, v68
	ds_read_b128 v[68:71], v3 offset:16160
	s_waitcnt lgkmcnt(1)
	v_fma_f32 v64, -v28, v64, v72
	v_fma_f32 v64, -v29, v65, v64
	v_fma_f32 v64, -v30, v66, v64
	v_fma_f32 v64, -v31, v67, v64
	s_waitcnt lgkmcnt(0)
	v_fma_f32 v68, -v32, v68, v64
	ds_read_b128 v[64:67], v3 offset:16176
	v_fma_f32 v68, -v33, v69, v68
	v_fma_f32 v68, -v35, v70, v68
	v_fma_f32 v72, -v36, v71, v68
	ds_read_b128 v[68:71], v3 offset:16192
	s_waitcnt lgkmcnt(1)
	v_fma_f32 v64, -v37, v64, v72
	v_fma_f32 v64, -v38, v65, v64
	v_fma_f32 v64, -v39, v66, v64
	v_fma_f32 v64, -v40, v67, v64
	s_waitcnt lgkmcnt(0)
	v_fma_f32 v68, -v41, v68, v64
	ds_read_b128 v[64:67], v3 offset:16208
	v_fma_f32 v68, -v42, v69, v68
	v_fma_f32 v68, -v43, v70, v68
	v_fma_f32 v72, -v44, v71, v68
	ds_read_b128 v[68:71], v3 offset:16224
	s_waitcnt lgkmcnt(1)
	v_fma_f32 v64, -v45, v64, v72
	v_fma_f32 v64, -v46, v65, v64
	v_fma_f32 v64, -v47, v66, v64
	v_fma_f32 v64, -v48, v67, v64
	s_waitcnt lgkmcnt(0)
	v_fma_f32 v68, -v49, v68, v64
	ds_read_b128 v[64:67], v3 offset:16240
	v_fma_f32 v68, -v50, v69, v68
	v_fma_f32 v68, -v51, v70, v68
	v_fma_f32 v72, -v52, v71, v68
	ds_read_b128 v[68:71], v3 offset:16256
	s_waitcnt lgkmcnt(1)
	v_fma_f32 v64, -v53, v64, v72
	v_fma_f32 v64, -v54, v65, v64
	v_fma_f32 v64, -v55, v66, v64
	v_fma_f32 v72, -v56, v67, v64
	ds_read_b128 v[64:67], v3 offset:16272
	s_waitcnt lgkmcnt(1)
	v_fma_f32 v3, -v57, v68, v72
	v_fma_f32 v3, -v58, v69, v3
	v_fma_f32 v3, -v59, v70, v3
	v_fma_f32 v3, -v60, v71, v3
	s_waitcnt lgkmcnt(0)
	v_fma_f32 v3, -v61, v64, v3
	v_fma_f32 v3, -v62, v65, v3
	v_fma_f32 v64, -v63, v66, v3
	v_fmac_f32_e32 v64, 0x80000000, v67
	ds_read_u16 v66, v2 offset:16320
	v_lshlrev_b32_e32 v3, 2, v0
	v_add_u32_e32 v65, s0, v3
	ds_read2_b32 v[70:71], v65 offset0:60 offset1:124
	v_add_u32_e32 v3, 32, v3
	v_add_u32_e32 v3, 0xcc00, v3
	s_waitcnt lgkmcnt(0)
; DEVI float bf2f(bf16_t b) { return __uint_as_float(((unsigned)b) << 16); }
; DEVI void prep_item(const Params& p, int j, int n, int h, char* smem) {
;     ...
; #pragma unroll
;     for (int i = 0; i < 64; ++i) {
;       const float* amz = am + zero;
;       const float* sbz = sbeta + zero;
;       const float eg = __expf(sbz[64 + i]);
;       float acc = bf2f(*(const unsigned short*)(src + i * 272)) * sbz[i] * (isu ? 1.0f : eg);
; #pragma unroll
;       for (int j4 = 0; j4 < (i + 3) / 4; ++j4) {
;         const f32x4 a = *(const f32x4*)(amz + i * 68 + j4 * 4);
;         acc -= a[0] * x[j4 * 4 + 0];
;         acc -= a[1] * x[j4 * 4 + 1];
;         acc -= a[2] * x[j4 * 4 + 2];
;         acc -= a[3] * x[j4 * 4 + 3];
;       }
;       asm volatile("" : "+v"(zero), "+v"(acc));
;       x[i] = acc;
;     }
	v_mul_f32_e32 v65, 0x3fb8aa3b, v71
	v_lshlrev_b32_e32 v71, 16, v66
	ds_read_b128 v[66:69], v3 offset:16320
	v_exp_f32_e32 v65, v65
	v_mul_f32_e32 v82, v70, v71
	ds_read_b128 v[70:73], v3 offset:16336
	ds_read_b128 v[74:77], v3 offset:16352
	ds_read_b128 v[78:81], v3 offset:16368
	v_cndmask_b32_e64 v65, v65, 1.0, vcc
	s_waitcnt lgkmcnt(3)
	v_mul_f32_e32 v66, v4, v66
	v_fma_f32 v65, v65, v82, -v66
	v_fma_f32 v65, -v5, v67, v65
	v_fma_f32 v65, -v6, v68, v65
	v_fma_f32 v65, -v7, v69, v65
	s_waitcnt lgkmcnt(2)
	v_fma_f32 v65, -v8, v70, v65
	v_fma_f32 v65, -v9, v71, v65
	v_fma_f32 v65, -v10, v72, v65
	v_fma_f32 v65, -v11, v73, v65
	s_waitcnt lgkmcnt(1)
	v_fma_f32 v65, -v12, v74, v65
	v_fma_f32 v65, -v13, v75, v65
	v_fma_f32 v65, -v14, v76, v65
	v_fma_f32 v65, -v15, v77, v65
	ds_read_b128 v[66:69], v3 offset:16384
	s_waitcnt lgkmcnt(1)
	v_fma_f32 v65, -v16, v78, v65
	v_fma_f32 v65, -v17, v79, v65
	v_fma_f32 v65, -v18, v80, v65
	v_fma_f32 v65, -v19, v81, v65
	ds_read_b128 v[70:73], v3 offset:16400
	s_waitcnt lgkmcnt(1)
	v_fma_f32 v65, -v20, v66, v65
	v_fma_f32 v65, -v21, v67, v65
	v_fma_f32 v65, -v22, v68, v65
	v_fma_f32 v65, -v23, v69, v65
	ds_read_b128 v[66:69], v3 offset:16416
	s_waitcnt lgkmcnt(1)
	v_fma_f32 v65, -v24, v70, v65
	v_fma_f32 v65, -v25, v71, v65
	v_fma_f32 v65, -v26, v72, v65
	v_fma_f32 v65, -v27, v73, v65
	ds_read_b128 v[70:73], v3 offset:16432
	s_waitcnt lgkmcnt(1)
	v_fma_f32 v65, -v28, v66, v65
	v_fma_f32 v65, -v29, v67, v65
	v_fma_f32 v65, -v30, v68, v65
	v_fma_f32 v65, -v31, v69, v65
	ds_read_b128 v[66:69], v3 offset:16448
	s_waitcnt lgkmcnt(1)
	v_fma_f32 v65, -v32, v70, v65
	v_fma_f32 v65, -v33, v71, v65
	v_fma_f32 v65, -v35, v72, v65
	v_fma_f32 v65, -v36, v73, v65
	ds_read_b128 v[70:73], v3 offset:16464
	s_waitcnt lgkmcnt(1)
	v_fma_f32 v65, -v37, v66, v65
	v_fma_f32 v65, -v38, v67, v65
	v_fma_f32 v65, -v39, v68, v65
	v_fma_f32 v65, -v40, v69, v65
	ds_read_b128 v[66:69], v3 offset:16480
	s_waitcnt lgkmcnt(1)
	v_fma_f32 v65, -v41, v70, v65
	v_fma_f32 v65, -v42, v71, v65
	v_fma_f32 v65, -v43, v72, v65
	v_fma_f32 v65, -v44, v73, v65
	ds_read_b128 v[70:73], v3 offset:16496
	s_waitcnt lgkmcnt(1)
	v_fma_f32 v65, -v45, v66, v65
	v_fma_f32 v65, -v46, v67, v65
	v_fma_f32 v65, -v47, v68, v65
	v_fma_f32 v65, -v48, v69, v65
	ds_read_b128 v[66:69], v3 offset:16512
	s_waitcnt lgkmcnt(1)
	v_fma_f32 v65, -v49, v70, v65
	v_fma_f32 v65, -v50, v71, v65
	v_fma_f32 v65, -v51, v72, v65
	v_fma_f32 v65, -v52, v73, v65
	ds_read_b128 v[70:73], v3 offset:16528
	s_waitcnt lgkmcnt(1)
	v_fma_f32 v65, -v53, v66, v65
	v_fma_f32 v65, -v54, v67, v65
	v_fma_f32 v65, -v55, v68, v65
	v_fma_f32 v65, -v56, v69, v65
	ds_read_b128 v[66:69], v3 offset:16544
	s_waitcnt lgkmcnt(1)
	v_fma_f32 v3, -v57, v70, v65
	v_fma_f32 v3, -v58, v71, v3
	v_fma_f32 v3, -v59, v72, v3
	v_fma_f32 v3, -v60, v73, v3
	s_waitcnt lgkmcnt(0)
	v_fma_f32 v3, -v61, v66, v3
	v_fma_f32 v3, -v62, v67, v3
	v_fma_f32 v3, -v63, v68, v3
	v_fma_f32 v65, -v64, v69, v3
	ds_read_u16 v67, v2 offset:16592
	v_lshlrev_b32_e32 v3, 2, v0
	v_add_u32_e32 v66, s0, v3
	ds_read2_b32 v[70:71], v66 offset0:61 offset1:125
	v_add_u32_e32 v3, 32, v3
	v_add_u32_e32 v3, 0xcc00, v3
	s_waitcnt lgkmcnt(0)
	v_mul_f32_e32 v66, 0x3fb8aa3b, v71
	v_exp_f32_e32 v66, v66
	v_lshlrev_b32_e32 v71, 16, v67
	v_mul_f32_e32 v83, v70, v71
	v_cndmask_b32_e64 v82, v66, 1.0, vcc
	ds_read_b128 v[66:69], v3 offset:16592
	ds_read_b128 v[70:73], v3 offset:16608
	ds_read_b128 v[74:77], v3 offset:16624
	ds_read_b128 v[78:81], v3 offset:16640
	s_waitcnt lgkmcnt(3)
	v_mul_f32_e32 v66, v4, v66
	v_fma_f32 v66, v82, v83, -v66
	v_fma_f32 v66, -v5, v67, v66
	v_fma_f32 v66, -v6, v68, v66
	v_fma_f32 v66, -v7, v69, v66
	s_waitcnt lgkmcnt(2)
	v_fma_f32 v66, -v8, v70, v66
	v_fma_f32 v66, -v9, v71, v66
	v_fma_f32 v66, -v10, v72, v66
	v_fma_f32 v66, -v11, v73, v66
	s_waitcnt lgkmcnt(1)
	v_fma_f32 v66, -v12, v74, v66
	v_fma_f32 v66, -v13, v75, v66
	v_fma_f32 v66, -v14, v76, v66
	v_fma_f32 v66, -v15, v77, v66
	s_waitcnt lgkmcnt(0)
	v_fma_f32 v70, -v16, v78, v66
	ds_read_b128 v[66:69], v3 offset:16656
	v_fma_f32 v70, -v17, v79, v70
	v_fma_f32 v70, -v18, v80, v70
	v_fma_f32 v74, -v19, v81, v70
	ds_read_b128 v[70:73], v3 offset:16672
	s_waitcnt lgkmcnt(1)
	v_fma_f32 v66, -v20, v66, v74
	v_fma_f32 v66, -v21, v67, v66
	v_fma_f32 v66, -v22, v68, v66
	v_fma_f32 v66, -v23, v69, v66
	s_waitcnt lgkmcnt(0)
	v_fma_f32 v70, -v24, v70, v66
	ds_read_b128 v[66:69], v3 offset:16688
	v_fma_f32 v70, -v25, v71, v70
	v_fma_f32 v70, -v26, v72, v70
	v_fma_f32 v74, -v27, v73, v70
	ds_read_b128 v[70:73], v3 offset:16704
	s_waitcnt lgkmcnt(1)
	v_fma_f32 v66, -v28, v66, v74
	v_fma_f32 v66, -v29, v67, v66
	v_fma_f32 v66, -v30, v68, v66
	v_fma_f32 v66, -v31, v69, v66
	s_waitcnt lgkmcnt(0)
	v_fma_f32 v70, -v32, v70, v66
	ds_read_b128 v[66:69], v3 offset:16720
	v_fma_f32 v70, -v33, v71, v70
	v_fma_f32 v70, -v35, v72, v70
	v_fma_f32 v74, -v36, v73, v70
	ds_read_b128 v[70:73], v3 offset:16736
	s_waitcnt lgkmcnt(1)
	v_fma_f32 v66, -v37, v66, v74
	v_fma_f32 v66, -v38, v67, v66
	v_fma_f32 v66, -v39, v68, v66
	v_fma_f32 v66, -v40, v69, v66
	s_waitcnt lgkmcnt(0)
	v_fma_f32 v70, -v41, v70, v66
	ds_read_b128 v[66:69], v3 offset:16752
	v_fma_f32 v70, -v42, v71, v70
	v_fma_f32 v70, -v43, v72, v70
	v_fma_f32 v74, -v44, v73, v70
	ds_read_b128 v[70:73], v3 offset:16768
	s_waitcnt lgkmcnt(1)
	v_fma_f32 v66, -v45, v66, v74
	v_fma_f32 v66, -v46, v67, v66
	v_fma_f32 v66, -v47, v68, v66
	v_fma_f32 v66, -v48, v69, v66
	s_waitcnt lgkmcnt(0)
	v_fma_f32 v70, -v49, v70, v66
	ds_read_b128 v[66:69], v3 offset:16784
	v_fma_f32 v70, -v50, v71, v70
	v_fma_f32 v70, -v51, v72, v70
	v_fma_f32 v74, -v52, v73, v70
	ds_read_b128 v[70:73], v3 offset:16800
	s_waitcnt lgkmcnt(1)
; DEVI float bf2f(bf16_t b) { return __uint_as_float(((unsigned)b) << 16); }
; DEVI void prep_item(const Params& p, int j, int n, int h, char* smem) {
;     ...
; #pragma unroll
;     for (int i = 0; i < 64; ++i) {
;       const float* amz = am + zero;
;       const float* sbz = sbeta + zero;
;       const float eg = __expf(sbz[64 + i]);
;       float acc = bf2f(*(const unsigned short*)(src + i * 272)) * sbz[i] * (isu ? 1.0f : eg);
; #pragma unroll
;       for (int j4 = 0; j4 < (i + 3) / 4; ++j4) {
;         const f32x4 a = *(const f32x4*)(amz + i * 68 + j4 * 4);
;         acc -= a[0] * x[j4 * 4 + 0];
;         acc -= a[1] * x[j4 * 4 + 1];
;         acc -= a[2] * x[j4 * 4 + 2];
;         acc -= a[3] * x[j4 * 4 + 3];
;       }
;       asm volatile("" : "+v"(zero), "+v"(acc));
;       x[i] = acc;
;     }
	v_fma_f32 v66, -v53, v66, v74
	v_fma_f32 v66, -v54, v67, v66
	v_fma_f32 v66, -v55, v68, v66
	v_fma_f32 v66, -v56, v69, v66
	s_waitcnt lgkmcnt(0)
	v_fma_f32 v70, -v57, v70, v66
	ds_read_b128 v[66:69], v3 offset:16816
	v_fma_f32 v70, -v58, v71, v70
	v_fma_f32 v70, -v59, v72, v70
	v_fma_f32 v74, -v60, v73, v70
	ds_read_b128 v[70:73], v3 offset:16832
	s_waitcnt lgkmcnt(1)
	v_fma_f32 v3, -v61, v66, v74
	v_fma_f32 v3, -v62, v67, v3
	v_fma_f32 v3, -v63, v68, v3
	v_fma_f32 v3, -v64, v69, v3
	s_waitcnt lgkmcnt(0)
	v_fma_f32 v66, -v65, v70, v3
	v_fmac_f32_e32 v66, 0x80000000, v71
	v_fmac_f32_e32 v66, 0x80000000, v72
	v_fmac_f32_e32 v66, 0x80000000, v73
	ds_read_u16 v68, v2 offset:16864
	v_lshlrev_b32_e32 v3, 2, v0
	v_add_u32_e32 v67, s0, v3
	ds_read2_b32 v[72:73], v67 offset0:62 offset1:126
	v_add_u32_e32 v3, 32, v3
	v_add_u32_e32 v3, 0xcc00, v3
	s_waitcnt lgkmcnt(0)
	v_mul_f32_e32 v67, 0x3fb8aa3b, v73
	v_lshlrev_b32_e32 v73, 16, v68
	ds_read_b128 v[68:71], v3 offset:16864
	v_exp_f32_e32 v67, v67
	v_mul_f32_e32 v84, v72, v73
	ds_read_b128 v[72:75], v3 offset:16880
	ds_read_b128 v[76:79], v3 offset:16896
	ds_read_b128 v[80:83], v3 offset:16912
	v_cndmask_b32_e64 v67, v67, 1.0, vcc
	s_waitcnt lgkmcnt(3)
	v_mul_f32_e32 v68, v4, v68
	v_fma_f32 v67, v67, v84, -v68
	v_fma_f32 v67, -v5, v69, v67
	v_fma_f32 v67, -v6, v70, v67
	v_fma_f32 v67, -v7, v71, v67
	s_waitcnt lgkmcnt(2)
	v_fma_f32 v67, -v8, v72, v67
	v_fma_f32 v67, -v9, v73, v67
	v_fma_f32 v67, -v10, v74, v67
	v_fma_f32 v67, -v11, v75, v67
	s_waitcnt lgkmcnt(1)
	v_fma_f32 v67, -v12, v76, v67
	v_fma_f32 v67, -v13, v77, v67
	v_fma_f32 v67, -v14, v78, v67
	v_fma_f32 v67, -v15, v79, v67
	ds_read_b128 v[68:71], v3 offset:16928
	s_waitcnt lgkmcnt(1)
	v_fma_f32 v67, -v16, v80, v67
	v_fma_f32 v67, -v17, v81, v67
	v_fma_f32 v67, -v18, v82, v67
	v_fma_f32 v67, -v19, v83, v67
	ds_read_b128 v[72:75], v3 offset:16944
	s_waitcnt lgkmcnt(1)
	v_fma_f32 v67, -v20, v68, v67
	v_fma_f32 v67, -v21, v69, v67
	v_fma_f32 v67, -v22, v70, v67
	v_fma_f32 v67, -v23, v71, v67
	ds_read_b128 v[68:71], v3 offset:16960
	s_waitcnt lgkmcnt(1)
	v_fma_f32 v67, -v24, v72, v67
	v_fma_f32 v67, -v25, v73, v67
	v_fma_f32 v67, -v26, v74, v67
	v_fma_f32 v67, -v27, v75, v67
	ds_read_b128 v[72:75], v3 offset:16976
	s_waitcnt lgkmcnt(1)
	v_fma_f32 v67, -v28, v68, v67
	v_fma_f32 v67, -v29, v69, v67
	v_fma_f32 v67, -v30, v70, v67
	v_fma_f32 v67, -v31, v71, v67
	ds_read_b128 v[68:71], v3 offset:16992
	s_waitcnt lgkmcnt(1)
	v_fma_f32 v67, -v32, v72, v67
	v_fma_f32 v67, -v33, v73, v67
	v_fma_f32 v67, -v35, v74, v67
	v_fma_f32 v67, -v36, v75, v67
	ds_read_b128 v[72:75], v3 offset:17008
	s_waitcnt lgkmcnt(1)
	v_fma_f32 v67, -v37, v68, v67
	v_fma_f32 v67, -v38, v69, v67
	v_fma_f32 v67, -v39, v70, v67
	v_fma_f32 v67, -v40, v71, v67
	ds_read_b128 v[68:71], v3 offset:17024
	s_waitcnt lgkmcnt(1)
	v_fma_f32 v67, -v41, v72, v67
	v_fma_f32 v67, -v42, v73, v67
	v_fma_f32 v67, -v43, v74, v67
	v_fma_f32 v67, -v44, v75, v67
	ds_read_b128 v[72:75], v3 offset:17040
	s_waitcnt lgkmcnt(1)
	v_fma_f32 v67, -v45, v68, v67
	v_fma_f32 v67, -v46, v69, v67
	v_fma_f32 v67, -v47, v70, v67
	v_fma_f32 v67, -v48, v71, v67
	ds_read_b128 v[68:71], v3 offset:17056
	s_waitcnt lgkmcnt(1)
	v_fma_f32 v67, -v49, v72, v67
	v_fma_f32 v67, -v50, v73, v67
	v_fma_f32 v67, -v51, v74, v67
	v_fma_f32 v67, -v52, v75, v67
	ds_read_b128 v[72:75], v3 offset:17072
	s_waitcnt lgkmcnt(1)
	v_fma_f32 v67, -v53, v68, v67
	v_fma_f32 v67, -v54, v69, v67
	v_fma_f32 v67, -v55, v70, v67
	v_fma_f32 v67, -v56, v71, v67
	ds_read_b128 v[68:71], v3 offset:17088
	s_waitcnt lgkmcnt(1)
	v_fma_f32 v67, -v57, v72, v67
	v_fma_f32 v67, -v58, v73, v67
	v_fma_f32 v67, -v59, v74, v67
	v_fma_f32 v67, -v60, v75, v67
	ds_read_b128 v[72:75], v3 offset:17104
	s_waitcnt lgkmcnt(1)
	v_fma_f32 v3, -v61, v68, v67
	v_fma_f32 v3, -v62, v69, v3
	v_fma_f32 v3, -v63, v70, v3
	v_fma_f32 v3, -v64, v71, v3
	s_waitcnt lgkmcnt(0)
	v_fma_f32 v3, -v65, v72, v3
	v_fma_f32 v67, -v66, v73, v3
	v_fmac_f32_e32 v67, 0x80000000, v74
	v_fmac_f32_e32 v67, 0x80000000, v75
	ds_read_u16 v2, v2 offset:17136
	v_lshlrev_b32_e32 v3, 2, v0
	v_add_u32_e32 v68, s0, v3
	ds_read2_b32 v[72:73], v68 offset0:63 offset1:127
	v_add_u32_e32 v3, 32, v3
	v_add_u32_e32 v3, 0xcc00, v3
	s_waitcnt lgkmcnt(1)
	v_lshlrev_b32_e32 v2, 16, v2
	v_readlane_b32 s0, v247, 26
	s_waitcnt lgkmcnt(0)
	v_mul_f32_e32 v68, 0x3fb8aa3b, v73
	v_exp_f32_e32 v68, v68
	v_mul_f32_e32 v2, v72, v2
	v_readlane_b32 s1, v247, 27
	v_cndmask_b32_e64 v84, v68, 1.0, vcc
	ds_read_b128 v[68:71], v3 offset:17136
	ds_read_b128 v[72:75], v3 offset:17152
	ds_read_b128 v[76:79], v3 offset:17168
	ds_read_b128 v[80:83], v3 offset:17184
	s_waitcnt lgkmcnt(3)
	v_mul_f32_e32 v68, v4, v68
	v_fma_f32 v2, v84, v2, -v68
	v_fma_f32 v2, -v5, v69, v2
	v_fma_f32 v2, -v6, v70, v2
	v_fma_f32 v2, -v7, v71, v2
	s_waitcnt lgkmcnt(2)
	v_fma_f32 v2, -v8, v72, v2
	v_fma_f32 v2, -v9, v73, v2
	v_fma_f32 v2, -v10, v74, v2
	v_fma_f32 v2, -v11, v75, v2
	s_waitcnt lgkmcnt(1)
	v_fma_f32 v2, -v12, v76, v2
	v_fma_f32 v2, -v13, v77, v2
	v_fma_f32 v2, -v14, v78, v2
	v_fma_f32 v2, -v15, v79, v2
	ds_read_b128 v[68:71], v3 offset:17200
	s_waitcnt lgkmcnt(1)
	v_fma_f32 v2, -v16, v80, v2
	v_fma_f32 v2, -v17, v81, v2
	v_fma_f32 v2, -v18, v82, v2
	v_fma_f32 v2, -v19, v83, v2
	ds_read_b128 v[72:75], v3 offset:17216
	s_waitcnt lgkmcnt(1)
	v_fma_f32 v2, -v20, v68, v2
	v_fma_f32 v2, -v21, v69, v2
	v_fma_f32 v2, -v22, v70, v2
	v_fma_f32 v2, -v23, v71, v2
	ds_read_b128 v[68:71], v3 offset:17232
	s_waitcnt lgkmcnt(1)
	v_fma_f32 v2, -v24, v72, v2
	v_fma_f32 v2, -v25, v73, v2
	v_fma_f32 v2, -v26, v74, v2
	v_fma_f32 v2, -v27, v75, v2
	ds_read_b128 v[72:75], v3 offset:17248
	s_waitcnt lgkmcnt(1)
; DEVI bf16_t f2bf(float a) { return (bf16_t)(pack2(a, 0.f) & 0xffff); }
; DEVI void prep_item(const Params& p, int j, int n, int h, char* smem) {
;     ...
; #pragma unroll
;       for (int j4 = 0; j4 < (i + 3) / 4; ++j4) {
;         const f32x4 a = *(const f32x4*)(amz + i * 68 + j4 * 4);
;         acc -= a[0] * x[j4 * 4 + 0];
;         acc -= a[1] * x[j4 * 4 + 1];
;         acc -= a[2] * x[j4 * 4 + 2];
;         acc -= a[3] * x[j4 * 4 + 3];
;       }
;       asm volatile("" : "+v"(zero), "+v"(acc));
;       x[i] = acc;
;     }
;     bf16_t* dst = r1 + (isu ? 2048 : 1024) + h * 128 + (c & 127);
; #pragma unroll
;     for (int i = 0; i < 64; ++i) {
;       const int t = t0 + i;
;       if (t >= 0) dst[(size_t)t * 3072] = f2bf(x[i]);
;     }
	v_fma_f32 v2, -v28, v68, v2
	v_fma_f32 v2, -v29, v69, v2
	v_fma_f32 v2, -v30, v70, v2
	v_fma_f32 v2, -v31, v71, v2
	ds_read_b128 v[68:71], v3 offset:17264
	s_waitcnt lgkmcnt(1)
	v_fma_f32 v2, -v32, v72, v2
	v_fma_f32 v2, -v33, v73, v2
	v_fma_f32 v2, -v35, v74, v2
	v_fma_f32 v2, -v36, v75, v2
	ds_read_b128 v[72:75], v3 offset:17280
	s_waitcnt lgkmcnt(1)
	v_fma_f32 v2, -v37, v68, v2
	v_fma_f32 v2, -v38, v69, v2
	v_fma_f32 v2, -v39, v70, v2
	v_fma_f32 v2, -v40, v71, v2
	ds_read_b128 v[68:71], v3 offset:17296
	s_waitcnt lgkmcnt(1)
	v_fma_f32 v2, -v41, v72, v2
	v_fma_f32 v2, -v42, v73, v2
	v_fma_f32 v2, -v43, v74, v2
	v_fma_f32 v2, -v44, v75, v2
	ds_read_b128 v[72:75], v3 offset:17312
	s_waitcnt lgkmcnt(1)
	v_fma_f32 v2, -v45, v68, v2
	v_fma_f32 v2, -v46, v69, v2
	v_fma_f32 v2, -v47, v70, v2
	v_fma_f32 v2, -v48, v71, v2
	ds_read_b128 v[68:71], v3 offset:17328
	s_waitcnt lgkmcnt(1)
	v_fma_f32 v2, -v49, v72, v2
	v_fma_f32 v2, -v50, v73, v2
	v_fma_f32 v2, -v51, v74, v2
	v_fma_f32 v2, -v52, v75, v2
	ds_read_b128 v[72:75], v3 offset:17344
	s_waitcnt lgkmcnt(1)
	v_fma_f32 v2, -v53, v68, v2
	v_fma_f32 v2, -v54, v69, v2
	v_fma_f32 v2, -v55, v70, v2
	v_fma_f32 v2, -v56, v71, v2
	ds_read_b128 v[68:71], v3 offset:17360
	s_waitcnt lgkmcnt(1)
	v_fma_f32 v2, -v57, v72, v2
	v_fma_f32 v2, -v58, v73, v2
	v_fma_f32 v2, -v59, v74, v2
	v_fma_f32 v2, -v60, v75, v2
	ds_read_b128 v[72:75], v3 offset:17376
	s_waitcnt lgkmcnt(1)
	v_fma_f32 v2, -v61, v68, v2
	v_fma_f32 v2, -v62, v69, v2
	v_fma_f32 v2, -v63, v70, v2
	v_fma_f32 v2, -v64, v71, v2
	s_waitcnt lgkmcnt(0)
	v_fma_f32 v2, -v65, v72, v2
	v_fma_f32 v2, -v66, v73, v2
	v_fma_f32 v68, -v67, v74, v2
	v_fmac_f32_e32 v68, 0x80000000, v75
	s_nop 0
	v_and_b32_e32 v0, 0x7f, v34
	v_and_b32_e32 v85, 0x63, v0
	v_and_b32_e32 v86, 12, v0
	v_lshl_or_b32 v85, v86, 1, v85
	v_and_b32_e32 v86, 16, v0
	v_lshrrev_b32_e32 v86, 2, v86
	v_or_b32_e32 v85, v85, v86
	v_and_b32_e32 v86, 7, v85
	v_lshlrev_b32_e32 v86, 1, v86
	v_lshrrev_b32_e32 v85, 3, v85
	v_mul_u32_u24_e32 v85, 0x1800, v85
	v_add_u32_e32 v85, v85, v86
	v_lshlrev_b32_e32 v0, 1, v0
	v_cndmask_b32_e32 v0, v85, v0, vcc
	v_cndmask_b32_e32 v85, v220, v221, vcc
	v_add_u32_e32 v0, v0, v85
	v_mov_b32_e32 v86, 16
	v_mov_b32_e32 v87, 0x1800
	v_cndmask_b32_e32 v86, v86, v87, vcc
	v_lshl_add_u64 v[2:3], s[0:1], 0, v[0:1]
	v_lshl_add_u64 v[2:3], v[2:3], 0, s[62:63]
	v_mad_u64_u32 v[72:73], s[0:1], s43, v222, v[2:3]
	s_mov_b32 s16, 0xfffb8000
	s_mov_b32 s17, -1
	v_lshl_add_u64 v[2:3], v[72:73], 0, s[16:17]
	s_mov_b32 s16, 0x18000
	s_mov_b32 s17, 0
	s_cmp_lt_i32 s44, 1
	s_cbranch_scc1 .LBB0_1295
	v_cvt_pk_bf16_f32 v0, v4, s0
	global_store_short v[2:3], v0, off
	v_cvt_pk_bf16_f32 v0, v5, s0
	v_mad_u64_u32 v[70:71], s[0:1], v86, 1, v[2:3]
	global_store_short v[70:71], v0, off
	v_cvt_pk_bf16_f32 v0, v6, s0
	v_mad_u64_u32 v[70:71], s[0:1], v86, 2, v[2:3]
	global_store_short v[70:71], v0, off
	v_cvt_pk_bf16_f32 v0, v7, s0
	v_mad_u64_u32 v[70:71], s[0:1], v86, 3, v[2:3]
	global_store_short v[70:71], v0, off
	v_cvt_pk_bf16_f32 v0, v8, s0
	v_mad_u64_u32 v[70:71], s[0:1], v86, 4, v[2:3]
	global_store_short v[70:71], v0, off
	v_cvt_pk_bf16_f32 v0, v9, s0
	v_mad_u64_u32 v[70:71], s[0:1], v86, 5, v[2:3]
	global_store_short v[70:71], v0, off
	v_cvt_pk_bf16_f32 v0, v10, s0
	v_mad_u64_u32 v[70:71], s[0:1], v86, 6, v[2:3]
	global_store_short v[70:71], v0, off
	v_cvt_pk_bf16_f32 v0, v11, s0
	v_mad_u64_u32 v[70:71], s[0:1], v86, 7, v[2:3]
	global_store_short v[70:71], v0, off
	v_cvt_pk_bf16_f32 v0, v12, s0
	v_mad_u64_u32 v[70:71], s[0:1], v86, 8, v[2:3]
	global_store_short v[70:71], v0, off
	v_cvt_pk_bf16_f32 v0, v13, s0
	v_mad_u64_u32 v[70:71], s[0:1], v86, 9, v[2:3]
	global_store_short v[70:71], v0, off
	v_cvt_pk_bf16_f32 v0, v14, s0
	v_mad_u64_u32 v[70:71], s[0:1], v86, 10, v[2:3]
	global_store_short v[70:71], v0, off
	v_cvt_pk_bf16_f32 v0, v15, s0
	v_mad_u64_u32 v[70:71], s[0:1], v86, 11, v[2:3]
	global_store_short v[70:71], v0, off
	v_cvt_pk_bf16_f32 v0, v16, s0
	v_mad_u64_u32 v[70:71], s[0:1], v86, 12, v[2:3]
	global_store_short v[70:71], v0, off
	v_cvt_pk_bf16_f32 v0, v17, s0
	v_mad_u64_u32 v[70:71], s[0:1], v86, 13, v[2:3]
	global_store_short v[70:71], v0, off
	v_cvt_pk_bf16_f32 v0, v18, s0
	v_mad_u64_u32 v[70:71], s[0:1], v86, 14, v[2:3]
	global_store_short v[70:71], v0, off
	v_cvt_pk_bf16_f32 v0, v19, s0
	v_mad_u64_u32 v[70:71], s[0:1], v86, 15, v[2:3]
	global_store_short v[70:71], v0, off
	v_lshl_add_u64 v[2:3], v[2:3], 0, s[16:17]
	v_cvt_pk_bf16_f32 v0, v20, s0
	global_store_short v[2:3], v0, off
	v_cvt_pk_bf16_f32 v0, v21, s0
	v_mad_u64_u32 v[70:71], s[0:1], v86, 1, v[2:3]
	global_store_short v[70:71], v0, off
	v_cvt_pk_bf16_f32 v0, v22, s0
	v_mad_u64_u32 v[70:71], s[0:1], v86, 2, v[2:3]
	global_store_short v[70:71], v0, off
	v_cvt_pk_bf16_f32 v0, v23, s0
	v_mad_u64_u32 v[70:71], s[0:1], v86, 3, v[2:3]
	global_store_short v[70:71], v0, off
	v_cvt_pk_bf16_f32 v0, v24, s0
	v_mad_u64_u32 v[70:71], s[0:1], v86, 4, v[2:3]
	global_store_short v[70:71], v0, off
	v_cvt_pk_bf16_f32 v0, v25, s0
; DEVI bf16_t f2bf(float a) { return (bf16_t)(pack2(a, 0.f) & 0xffff); }
; DEVI void prep_item(const Params& p, int j, int n, int h, char* smem) {
;     ...
;     bf16_t* dst = r1 + (isu ? 2048 : 1024) + h * 128 + (c & 127);
; #pragma unroll
;     for (int i = 0; i < 64; ++i) {
;       const int t = t0 + i;
;       if (t >= 0) dst[(size_t)t * 3072] = f2bf(x[i]);
;     }
	v_mad_u64_u32 v[70:71], s[0:1], v86, 5, v[2:3]
	global_store_short v[70:71], v0, off
	v_cvt_pk_bf16_f32 v0, v26, s0
	v_mad_u64_u32 v[70:71], s[0:1], v86, 6, v[2:3]
	global_store_short v[70:71], v0, off
	v_cvt_pk_bf16_f32 v0, v27, s0
	v_mad_u64_u32 v[70:71], s[0:1], v86, 7, v[2:3]
	global_store_short v[70:71], v0, off
	v_cvt_pk_bf16_f32 v0, v28, s0
	v_mad_u64_u32 v[70:71], s[0:1], v86, 8, v[2:3]
	global_store_short v[70:71], v0, off
	v_cvt_pk_bf16_f32 v0, v29, s0
	v_mad_u64_u32 v[70:71], s[0:1], v86, 9, v[2:3]
	global_store_short v[70:71], v0, off
	v_cvt_pk_bf16_f32 v0, v30, s0
	v_mad_u64_u32 v[70:71], s[0:1], v86, 10, v[2:3]
	global_store_short v[70:71], v0, off
	v_cvt_pk_bf16_f32 v0, v31, s0
	v_mad_u64_u32 v[70:71], s[0:1], v86, 11, v[2:3]
	global_store_short v[70:71], v0, off
	v_cvt_pk_bf16_f32 v0, v32, s0
	v_mad_u64_u32 v[70:71], s[0:1], v86, 12, v[2:3]
	global_store_short v[70:71], v0, off
	v_cvt_pk_bf16_f32 v0, v33, s0
	v_mad_u64_u32 v[70:71], s[0:1], v86, 13, v[2:3]
	global_store_short v[70:71], v0, off
	v_cvt_pk_bf16_f32 v0, v35, s0
	v_mad_u64_u32 v[70:71], s[0:1], v86, 14, v[2:3]
	global_store_short v[70:71], v0, off
	v_cvt_pk_bf16_f32 v0, v36, s0
	v_mad_u64_u32 v[70:71], s[0:1], v86, 15, v[2:3]
	global_store_short v[70:71], v0, off
	v_lshl_add_u64 v[2:3], v[2:3], 0, s[16:17]
	v_cvt_pk_bf16_f32 v0, v37, s0
	global_store_short v[2:3], v0, off
	v_cvt_pk_bf16_f32 v0, v38, s0
	v_mad_u64_u32 v[70:71], s[0:1], v86, 1, v[2:3]
	global_store_short v[70:71], v0, off
	v_cvt_pk_bf16_f32 v0, v39, s0
	v_mad_u64_u32 v[70:71], s[0:1], v86, 2, v[2:3]
	global_store_short v[70:71], v0, off
	v_cvt_pk_bf16_f32 v0, v40, s0
	v_mad_u64_u32 v[70:71], s[0:1], v86, 3, v[2:3]
	global_store_short v[70:71], v0, off
	v_cvt_pk_bf16_f32 v0, v41, s0
	v_mad_u64_u32 v[70:71], s[0:1], v86, 4, v[2:3]
	global_store_short v[70:71], v0, off
	v_cvt_pk_bf16_f32 v0, v42, s0
	v_mad_u64_u32 v[70:71], s[0:1], v86, 5, v[2:3]
	global_store_short v[70:71], v0, off
	v_cvt_pk_bf16_f32 v0, v43, s0
	v_mad_u64_u32 v[70:71], s[0:1], v86, 6, v[2:3]
	global_store_short v[70:71], v0, off
	v_cvt_pk_bf16_f32 v0, v44, s0
	v_mad_u64_u32 v[70:71], s[0:1], v86, 7, v[2:3]
	global_store_short v[70:71], v0, off
	v_cvt_pk_bf16_f32 v0, v45, s0
	v_mad_u64_u32 v[70:71], s[0:1], v86, 8, v[2:3]
	global_store_short v[70:71], v0, off
	v_cvt_pk_bf16_f32 v0, v46, s0
	v_mad_u64_u32 v[70:71], s[0:1], v86, 9, v[2:3]
	global_store_short v[70:71], v0, off
	v_cvt_pk_bf16_f32 v0, v47, s0
	v_mad_u64_u32 v[70:71], s[0:1], v86, 10, v[2:3]
	global_store_short v[70:71], v0, off
	v_cvt_pk_bf16_f32 v0, v48, s0
	v_mad_u64_u32 v[70:71], s[0:1], v86, 11, v[2:3]
	global_store_short v[70:71], v0, off
	v_cvt_pk_bf16_f32 v0, v49, s0
	v_mad_u64_u32 v[70:71], s[0:1], v86, 12, v[2:3]
	global_store_short v[70:71], v0, off
	v_cvt_pk_bf16_f32 v0, v50, s0
	v_mad_u64_u32 v[70:71], s[0:1], v86, 13, v[2:3]
	global_store_short v[70:71], v0, off
	v_cvt_pk_bf16_f32 v0, v51, s0
	v_mad_u64_u32 v[70:71], s[0:1], v86, 14, v[2:3]
	global_store_short v[70:71], v0, off
	v_cvt_pk_bf16_f32 v0, v52, s0
	v_mad_u64_u32 v[70:71], s[0:1], v86, 15, v[2:3]
	global_store_short v[70:71], v0, off
.LBB0_1295:
	v_mov_b64_e32 v[2:3], v[72:73]
	v_cvt_pk_bf16_f32 v0, v53, s0
	global_store_short v[2:3], v0, off
	v_cvt_pk_bf16_f32 v0, v54, s0
	v_mad_u64_u32 v[70:71], s[0:1], v86, 1, v[2:3]
	global_store_short v[70:71], v0, off
	v_cvt_pk_bf16_f32 v0, v55, s0
	v_mad_u64_u32 v[70:71], s[0:1], v86, 2, v[2:3]
	global_store_short v[70:71], v0, off
	v_cvt_pk_bf16_f32 v0, v56, s0
	v_mad_u64_u32 v[70:71], s[0:1], v86, 3, v[2:3]
	global_store_short v[70:71], v0, off
	v_cvt_pk_bf16_f32 v0, v57, s0
	v_mad_u64_u32 v[70:71], s[0:1], v86, 4, v[2:3]
	global_store_short v[70:71], v0, off
	v_cvt_pk_bf16_f32 v0, v58, s0
	v_mad_u64_u32 v[70:71], s[0:1], v86, 5, v[2:3]
	global_store_short v[70:71], v0, off
	v_cvt_pk_bf16_f32 v0, v59, s0
	v_mad_u64_u32 v[70:71], s[0:1], v86, 6, v[2:3]
	global_store_short v[70:71], v0, off
	v_cvt_pk_bf16_f32 v0, v60, s0
	v_mad_u64_u32 v[70:71], s[0:1], v86, 7, v[2:3]
	global_store_short v[70:71], v0, off
	v_cvt_pk_bf16_f32 v0, v61, s0
	v_mad_u64_u32 v[70:71], s[0:1], v86, 8, v[2:3]
	global_store_short v[70:71], v0, off
	v_cvt_pk_bf16_f32 v0, v62, s0
	v_mad_u64_u32 v[70:71], s[0:1], v86, 9, v[2:3]
	global_store_short v[70:71], v0, off
	v_cvt_pk_bf16_f32 v0, v63, s0
	v_mad_u64_u32 v[70:71], s[0:1], v86, 10, v[2:3]
	global_store_short v[70:71], v0, off
	v_cvt_pk_bf16_f32 v0, v64, s0
	v_mad_u64_u32 v[70:71], s[0:1], v86, 11, v[2:3]
	global_store_short v[70:71], v0, off
	v_cvt_pk_bf16_f32 v0, v65, s0
	v_mad_u64_u32 v[70:71], s[0:1], v86, 12, v[2:3]
	global_store_short v[70:71], v0, off
	v_cvt_pk_bf16_f32 v0, v66, s0
	v_mad_u64_u32 v[70:71], s[0:1], v86, 13, v[2:3]
	global_store_short v[70:71], v0, off
	v_cvt_pk_bf16_f32 v0, v67, s0
	v_mad_u64_u32 v[70:71], s[0:1], v86, 14, v[2:3]
	global_store_short v[70:71], v0, off
	v_cvt_pk_bf16_f32 v0, v68, s0
	v_mad_u64_u32 v[70:71], s[0:1], v86, 15, v[2:3]
	global_store_short v[70:71], v0, off
	s_branch .LBB0_1242
